# non-temporal hint on the main-GEMM epilogue stores
# speedup vs baseline: 1.0061x; 1.0061x over previous
.LBB0_139:
	v_or_b32_e32 v140, 0x10000, v146
	v_add_u32_e32 v150, 0x10400, v146
	v_add_u32_e32 v154, 0x10800, v146
	v_add_u32_e32 v158, 0x10c00, v146
	ds_read_b128 v[140:143], v140
	ds_read_b128 v[150:153], v150
	ds_read_b128 v[154:157], v154
	ds_read_b128 v[158:161], v158
	s_add_u32 s10, s6, 0xfff80080
	s_addc_u32 s11, s7, -1
	s_cmp_eq_u32 s41, 28
	s_cselect_b32 s11, s63, s11
	s_cselect_b32 s10, s62, s10
	s_cselect_b32 s53, s61, s29
	s_cselect_b32 s52, s60, s28
	s_mov_b32 m0, s12
	v_lshl_add_u64 v[206:207], s[6:7], 0, v[136:137]
	ds_read_b128 v[162:165], v145
	ds_read_b128 v[166:169], v145 offset:1024
	ds_read_b128 v[170:173], v145 offset:2048
	ds_read_b128 v[174:177], v145 offset:3072
	ds_read_b128 v[178:181], v145 offset:4096
	ds_read_b128 v[182:185], v145 offset:5120
	ds_read_b128 v[186:189], v145 offset:6144
	ds_read_b128 v[190:193], v145 offset:7168
	global_load_lds_dwordx4 v[206:207], off
	v_lshl_add_u64 v[206:207], s[6:7], 0, v[138:139]
	s_mov_b32 m0, s78
	s_nop 0
	global_load_lds_dwordx4 v[206:207], off
	s_waitcnt lgkmcnt(8)
	s_barrier
	s_waitcnt lgkmcnt(0)
	s_setprio 1
	s_waitcnt lgkmcnt(0)
	v_mfma_f32_16x16x32_bf16 v[126:129], v[140:143], v[162:165], v[126:129]
	v_mfma_f32_16x16x32_bf16 v[122:125], v[154:157], v[162:165], v[122:125]
	v_mfma_f32_16x16x32_bf16 v[118:121], v[140:143], v[170:173], v[118:121]
	v_mfma_f32_16x16x32_bf16 v[110:113], v[154:157], v[170:173], v[110:113]
	v_mfma_f32_16x16x32_bf16 v[102:105], v[140:143], v[178:181], v[102:105]
	v_mfma_f32_16x16x32_bf16 v[94:97], v[154:157], v[178:181], v[94:97]
	v_mfma_f32_16x16x32_bf16 v[86:89], v[140:143], v[186:189], v[86:89]
	v_mfma_f32_16x16x32_bf16 v[78:81], v[154:157], v[186:189], v[78:81]
	v_mfma_f32_16x16x32_bf16 v[126:129], v[150:153], v[166:169], v[126:129]
	v_mfma_f32_16x16x32_bf16 v[122:125], v[158:161], v[166:169], v[122:125]
	v_mfma_f32_16x16x32_bf16 v[118:121], v[150:153], v[174:177], v[118:121]
	v_mfma_f32_16x16x32_bf16 v[110:113], v[158:161], v[174:177], v[110:113]
	v_mfma_f32_16x16x32_bf16 v[102:105], v[150:153], v[182:185], v[102:105]
	v_mfma_f32_16x16x32_bf16 v[94:97], v[158:161], v[182:185], v[94:97]
	v_mfma_f32_16x16x32_bf16 v[86:89], v[150:153], v[190:193], v[86:89]
	v_mfma_f32_16x16x32_bf16 v[78:81], v[158:161], v[190:193], v[78:81]
	s_setprio 0
	s_barrier
	v_or_b32_e32 v197, 0x14000, v146
	s_mov_b32 m0, s83
	v_add_u32_e32 v199, 0x14400, v146
	ds_read_b128 v[206:209], v197
	ds_read_b128 v[210:213], v199
	v_add_u32_e32 v197, 0x14800, v146
	v_lshl_add_u64 v[222:223], s[52:53], 0, v[194:195]
	v_add_u32_e32 v199, 0x14c00, v146
	ds_read_b128 v[214:217], v197
	ds_read_b128 v[218:221], v199
	global_load_lds_dwordx4 v[222:223], off
	v_lshl_add_u64 v[224:225], s[52:53], 0, v[134:135]
	s_mov_b32 m0, s54
	s_nop 0
	global_load_lds_dwordx4 v[224:225], off
	s_barrier
	s_waitcnt lgkmcnt(0)
	s_setprio 1
	s_waitcnt lgkmcnt(0)
	v_mfma_f32_16x16x32_bf16 v[114:117], v[206:209], v[162:165], v[114:117]
	v_mfma_f32_16x16x32_bf16 v[106:109], v[214:217], v[162:165], v[106:109]
	v_mfma_f32_16x16x32_bf16 v[98:101], v[206:209], v[170:173], v[98:101]
	v_mfma_f32_16x16x32_bf16 v[90:93], v[214:217], v[170:173], v[90:93]
	v_mfma_f32_16x16x32_bf16 v[82:85], v[206:209], v[178:181], v[82:85]
	v_mfma_f32_16x16x32_bf16 v[74:77], v[214:217], v[178:181], v[74:77]
	v_mfma_f32_16x16x32_bf16 v[70:73], v[206:209], v[186:189], v[70:73]
	v_mfma_f32_16x16x32_bf16 v[66:69], v[214:217], v[186:189], v[66:69]
	v_mfma_f32_16x16x32_bf16 v[114:117], v[210:213], v[166:169], v[114:117]
	v_mfma_f32_16x16x32_bf16 v[106:109], v[218:221], v[166:169], v[106:109]
	v_mfma_f32_16x16x32_bf16 v[98:101], v[210:213], v[174:177], v[98:101]
	v_mfma_f32_16x16x32_bf16 v[90:93], v[218:221], v[174:177], v[90:93]
	v_mfma_f32_16x16x32_bf16 v[82:85], v[210:213], v[182:185], v[82:85]
	v_mfma_f32_16x16x32_bf16 v[74:77], v[218:221], v[182:185], v[74:77]
	v_mfma_f32_16x16x32_bf16 v[70:73], v[210:213], v[190:193], v[70:73]
	v_mfma_f32_16x16x32_bf16 v[66:69], v[218:221], v[190:193], v[66:69]
	s_setprio 0
	s_mov_b32 m0, s55
	v_lshl_add_u64 v[226:227], s[10:11], 0, v[130:131]
	s_barrier
	ds_read_b128 v[162:165], v145 offset:16384
	ds_read_b128 v[166:169], v145 offset:17408
	ds_read_b128 v[170:173], v145 offset:18432
	ds_read_b128 v[174:177], v145 offset:19456
	ds_read_b128 v[178:181], v145 offset:20480
	ds_read_b128 v[182:185], v145 offset:21504
	ds_read_b128 v[186:189], v145 offset:22528
	ds_read_b128 v[190:193], v145 offset:23552
	global_load_lds_dwordx4 v[226:227], off
	v_lshl_add_u64 v[228:229], s[10:11], 0, v[132:133]
	s_mov_b32 m0, s34
	s_nop 0
	global_load_lds_dwordx4 v[228:229], off
	s_barrier
	s_waitcnt lgkmcnt(0)
	s_setprio 1
	s_waitcnt lgkmcnt(0)
	v_mfma_f32_16x16x32_bf16 v[62:65], v[140:143], v[162:165], v[62:65]
	v_mfma_f32_16x16x32_bf16 v[58:61], v[154:157], v[162:165], v[58:61]
	v_mfma_f32_16x16x32_bf16 v[54:57], v[140:143], v[170:173], v[54:57]
	v_mfma_f32_16x16x32_bf16 v[46:49], v[154:157], v[170:173], v[46:49]
	v_mfma_f32_16x16x32_bf16 v[38:41], v[140:143], v[178:181], v[38:41]
	v_mfma_f32_16x16x32_bf16 v[30:33], v[154:157], v[178:181], v[30:33]
	v_mfma_f32_16x16x32_bf16 v[22:25], v[140:143], v[186:189], v[22:25]
	v_mfma_f32_16x16x32_bf16 v[14:17], v[154:157], v[186:189], v[14:17]
	v_mfma_f32_16x16x32_bf16 v[62:65], v[150:153], v[166:169], v[62:65]
	v_mfma_f32_16x16x32_bf16 v[58:61], v[158:161], v[166:169], v[58:61]
	v_mfma_f32_16x16x32_bf16 v[54:57], v[150:153], v[174:177], v[54:57]
	v_mfma_f32_16x16x32_bf16 v[46:49], v[158:161], v[174:177], v[46:49]
	v_mfma_f32_16x16x32_bf16 v[38:41], v[150:153], v[182:185], v[38:41]
	v_mfma_f32_16x16x32_bf16 v[30:33], v[158:161], v[182:185], v[30:33]
	v_mfma_f32_16x16x32_bf16 v[22:25], v[150:153], v[190:193], v[22:25]
	v_mfma_f32_16x16x32_bf16 v[14:17], v[158:161], v[190:193], v[14:17]
	s_setprio 0
	s_barrier
	s_add_u32 s58, s52, 0x80000
	s_addc_u32 s59, s53, 0
	s_mov_b32 m0, s4
	v_lshl_add_u64 v[140:141], s[58:59], 0, v[194:195]
	global_load_lds_dwordx4 v[140:141], off
	v_lshl_add_u64 v[140:141], s[58:59], 0, v[134:135]
	s_mov_b32 m0, s5
	s_nop 0
	global_load_lds_dwordx4 v[140:141], off
	s_waitcnt vmcnt(6)
	s_barrier
	s_setprio 1
	v_mfma_f32_16x16x32_bf16 v[50:53], v[206:209], v[162:165], v[50:53]
	v_mfma_f32_16x16x32_bf16 v[42:45], v[214:217], v[162:165], v[42:45]
	v_mfma_f32_16x16x32_bf16 v[34:37], v[206:209], v[170:173], v[34:37]
	v_mfma_f32_16x16x32_bf16 v[26:29], v[214:217], v[170:173], v[26:29]
	v_mfma_f32_16x16x32_bf16 v[18:21], v[206:209], v[178:181], v[18:21]
	v_mfma_f32_16x16x32_bf16 v[10:13], v[214:217], v[178:181], v[10:13]
	v_mfma_f32_16x16x32_bf16 v[6:9], v[206:209], v[186:189], v[6:9]
	v_mfma_f32_16x16x32_bf16 v[2:5], v[214:217], v[186:189], v[2:5]
	v_mfma_f32_16x16x32_bf16 v[50:53], v[210:213], v[166:169], v[50:53]
	v_mfma_f32_16x16x32_bf16 v[42:45], v[218:221], v[166:169], v[42:45]
	v_mfma_f32_16x16x32_bf16 v[34:37], v[210:213], v[174:177], v[34:37]
	v_mfma_f32_16x16x32_bf16 v[26:29], v[218:221], v[174:177], v[26:29]
	v_mfma_f32_16x16x32_bf16 v[18:21], v[210:213], v[182:185], v[18:21]
	v_mfma_f32_16x16x32_bf16 v[10:13], v[218:221], v[182:185], v[10:13]
	v_mfma_f32_16x16x32_bf16 v[6:9], v[210:213], v[190:193], v[6:9]
	v_mfma_f32_16x16x32_bf16 v[2:5], v[218:221], v[190:193], v[2:5]
	s_setprio 0
	v_or_b32_e32 v140, 0x18000, v146
	v_add_u32_e32 v150, 0x18400, v146
	v_add_u32_e32 v154, 0x18800, v146
	v_add_u32_e32 v158, 0x18c00, v146
	s_barrier
	ds_read_b128 v[140:143], v140
	ds_read_b128 v[150:153], v150
	ds_read_b128 v[154:157], v154
	ds_read_b128 v[158:161], v158
	s_add_u32 s10, s10, 0x80000
	s_addc_u32 s11, s11, 0
	s_mov_b32 m0, s56
	v_lshl_add_u64 v[206:207], s[10:11], 0, v[130:131]
	ds_read_b128 v[162:165], v145 offset:32768
	ds_read_b128 v[166:169], v145 offset:33792
	ds_read_b128 v[170:173], v145 offset:34816
	ds_read_b128 v[174:177], v145 offset:35840
	ds_read_b128 v[178:181], v145 offset:36864
	ds_read_b128 v[182:185], v145 offset:37888
	ds_read_b128 v[186:189], v145 offset:38912
	ds_read_b128 v[190:193], v145 offset:39936
	global_load_lds_dwordx4 v[206:207], off
	v_lshl_add_u64 v[206:207], s[10:11], 0, v[132:133]
	s_mov_b32 m0, s57
	s_nop 0
	global_load_lds_dwordx4 v[206:207], off
	s_waitcnt lgkmcnt(8)
	s_barrier
	s_waitcnt lgkmcnt(0)
	s_setprio 1
	s_waitcnt lgkmcnt(0)
	v_mfma_f32_16x16x32_bf16 v[126:129], v[140:143], v[162:165], v[126:129]
	v_mfma_f32_16x16x32_bf16 v[122:125], v[154:157], v[162:165], v[122:125]
	v_mfma_f32_16x16x32_bf16 v[118:121], v[140:143], v[170:173], v[118:121]
	v_mfma_f32_16x16x32_bf16 v[110:113], v[154:157], v[170:173], v[110:113]
	v_mfma_f32_16x16x32_bf16 v[102:105], v[140:143], v[178:181], v[102:105]
	v_mfma_f32_16x16x32_bf16 v[94:97], v[154:157], v[178:181], v[94:97]
	v_mfma_f32_16x16x32_bf16 v[86:89], v[140:143], v[186:189], v[86:89]
	v_mfma_f32_16x16x32_bf16 v[78:81], v[154:157], v[186:189], v[78:81]
	v_mfma_f32_16x16x32_bf16 v[126:129], v[150:153], v[166:169], v[126:129]
	v_mfma_f32_16x16x32_bf16 v[122:125], v[158:161], v[166:169], v[122:125]
	v_mfma_f32_16x16x32_bf16 v[118:121], v[150:153], v[174:177], v[118:121]
	v_mfma_f32_16x16x32_bf16 v[110:113], v[158:161], v[174:177], v[110:113]
	v_mfma_f32_16x16x32_bf16 v[102:105], v[150:153], v[182:185], v[102:105]
	v_mfma_f32_16x16x32_bf16 v[94:97], v[158:161], v[182:185], v[94:97]
	v_mfma_f32_16x16x32_bf16 v[86:89], v[150:153], v[190:193], v[86:89]
	v_mfma_f32_16x16x32_bf16 v[78:81], v[158:161], v[190:193], v[78:81]
	s_setprio 0
	s_barrier
	v_or_b32_e32 v197, 0x1c000, v146
	s_mov_b32 m0, s70
	v_add_u32_e32 v199, 0x1c400, v146
	ds_read_b128 v[206:209], v197
	ds_read_b128 v[210:213], v199
	v_add_u32_e32 v197, 0x1c800, v146
	v_lshl_add_u64 v[222:223], v[222:223], 0, s[76:77]
	v_add_u32_e32 v199, 0x1cc00, v146
	ds_read_b128 v[214:217], v197
	ds_read_b128 v[218:221], v199
	global_load_lds_dwordx4 v[222:223], off
	v_lshl_add_u64 v[222:223], v[224:225], 0, s[76:77]
	s_mov_b32 m0, s71
	s_nop 0
	global_load_lds_dwordx4 v[222:223], off
	s_barrier
	s_waitcnt lgkmcnt(0)
	s_setprio 1
	s_waitcnt lgkmcnt(0)
	v_mfma_f32_16x16x32_bf16 v[114:117], v[206:209], v[162:165], v[114:117]
	v_mfma_f32_16x16x32_bf16 v[106:109], v[214:217], v[162:165], v[106:109]
	v_mfma_f32_16x16x32_bf16 v[98:101], v[206:209], v[170:173], v[98:101]
	v_mfma_f32_16x16x32_bf16 v[90:93], v[214:217], v[170:173], v[90:93]
	v_mfma_f32_16x16x32_bf16 v[82:85], v[206:209], v[178:181], v[82:85]
	v_mfma_f32_16x16x32_bf16 v[74:77], v[214:217], v[178:181], v[74:77]
	v_mfma_f32_16x16x32_bf16 v[70:73], v[206:209], v[186:189], v[70:73]
	v_mfma_f32_16x16x32_bf16 v[66:69], v[214:217], v[186:189], v[66:69]
	v_mfma_f32_16x16x32_bf16 v[114:117], v[210:213], v[166:169], v[114:117]
	v_mfma_f32_16x16x32_bf16 v[106:109], v[218:221], v[166:169], v[106:109]
	v_mfma_f32_16x16x32_bf16 v[98:101], v[210:213], v[174:177], v[98:101]
	v_mfma_f32_16x16x32_bf16 v[90:93], v[218:221], v[174:177], v[90:93]
	v_mfma_f32_16x16x32_bf16 v[82:85], v[210:213], v[182:185], v[82:85]
	v_mfma_f32_16x16x32_bf16 v[74:77], v[218:221], v[182:185], v[74:77]
	v_mfma_f32_16x16x32_bf16 v[70:73], v[210:213], v[190:193], v[70:73]
	v_mfma_f32_16x16x32_bf16 v[66:69], v[218:221], v[190:193], v[66:69]
	s_setprio 0
	s_mov_b32 m0, s33
	v_lshl_add_u64 v[222:223], v[226:227], 0, s[76:77]
	s_barrier
	ds_read_b128 v[162:165], v145 offset:49152
	ds_read_b128 v[166:169], v145 offset:50176
	ds_read_b128 v[170:173], v145 offset:51200
	ds_read_b128 v[174:177], v145 offset:52224
	ds_read_b128 v[178:181], v145 offset:53248
	ds_read_b128 v[182:185], v145 offset:54272
	ds_read_b128 v[186:189], v145 offset:55296
	ds_read_b128 v[190:193], v145 offset:56320
	global_load_lds_dwordx4 v[222:223], off
	v_lshl_add_u64 v[222:223], v[228:229], 0, s[76:77]
	s_mov_b32 m0, s35
	s_nop 0
	global_load_lds_dwordx4 v[222:223], off
	s_barrier
	s_waitcnt lgkmcnt(0)
	s_setprio 1
	s_waitcnt lgkmcnt(0)
	v_mfma_f32_16x16x32_bf16 v[62:65], v[140:143], v[162:165], v[62:65]
	v_mfma_f32_16x16x32_bf16 v[58:61], v[154:157], v[162:165], v[58:61]
	v_mfma_f32_16x16x32_bf16 v[54:57], v[140:143], v[170:173], v[54:57]
	v_mfma_f32_16x16x32_bf16 v[46:49], v[154:157], v[170:173], v[46:49]
	v_mfma_f32_16x16x32_bf16 v[38:41], v[140:143], v[178:181], v[38:41]
	v_mfma_f32_16x16x32_bf16 v[30:33], v[154:157], v[178:181], v[30:33]
	v_mfma_f32_16x16x32_bf16 v[22:25], v[140:143], v[186:189], v[22:25]
	v_mfma_f32_16x16x32_bf16 v[14:17], v[154:157], v[186:189], v[14:17]
	v_mfma_f32_16x16x32_bf16 v[62:65], v[150:153], v[166:169], v[62:65]
	v_mfma_f32_16x16x32_bf16 v[58:61], v[158:161], v[166:169], v[58:61]
	v_mfma_f32_16x16x32_bf16 v[54:57], v[150:153], v[174:177], v[54:57]
	v_mfma_f32_16x16x32_bf16 v[46:49], v[158:161], v[174:177], v[46:49]
	v_mfma_f32_16x16x32_bf16 v[38:41], v[150:153], v[182:185], v[38:41]
	v_mfma_f32_16x16x32_bf16 v[30:33], v[158:161], v[182:185], v[30:33]
	v_mfma_f32_16x16x32_bf16 v[22:25], v[150:153], v[190:193], v[22:25]
	v_mfma_f32_16x16x32_bf16 v[14:17], v[158:161], v[190:193], v[14:17]
	s_setprio 0
	s_barrier
	s_add_u32 s10, s52, 0x80080
	s_addc_u32 s11, s53, 0
	s_mov_b32 m0, s67
	v_lshl_add_u64 v[140:141], s[10:11], 0, v[194:195]
	global_load_lds_dwordx4 v[140:141], off
	v_lshl_add_u64 v[140:141], s[10:11], 0, v[134:135]
	s_mov_b32 m0, s17
	s_nop 0
	global_load_lds_dwordx4 v[140:141], off
	s_waitcnt vmcnt(6)
	s_barrier
	s_setprio 1
	v_mfma_f32_16x16x32_bf16 v[50:53], v[206:209], v[162:165], v[50:53]
	v_mfma_f32_16x16x32_bf16 v[42:45], v[214:217], v[162:165], v[42:45]
	v_mfma_f32_16x16x32_bf16 v[34:37], v[206:209], v[170:173], v[34:37]
	v_mfma_f32_16x16x32_bf16 v[26:29], v[214:217], v[170:173], v[26:29]
	v_mfma_f32_16x16x32_bf16 v[18:21], v[206:209], v[178:181], v[18:21]
	v_mfma_f32_16x16x32_bf16 v[10:13], v[214:217], v[178:181], v[10:13]
	v_mfma_f32_16x16x32_bf16 v[6:9], v[206:209], v[186:189], v[6:9]
	v_mfma_f32_16x16x32_bf16 v[2:5], v[214:217], v[186:189], v[2:5]
	v_mfma_f32_16x16x32_bf16 v[50:53], v[210:213], v[166:169], v[50:53]
	v_mfma_f32_16x16x32_bf16 v[42:45], v[218:221], v[166:169], v[42:45]
	v_mfma_f32_16x16x32_bf16 v[34:37], v[210:213], v[174:177], v[34:37]
	v_mfma_f32_16x16x32_bf16 v[26:29], v[218:221], v[174:177], v[26:29]
	v_mfma_f32_16x16x32_bf16 v[18:21], v[210:213], v[182:185], v[18:21]
	v_mfma_f32_16x16x32_bf16 v[10:13], v[218:221], v[182:185], v[10:13]
	v_mfma_f32_16x16x32_bf16 v[6:9], v[210:213], v[190:193], v[6:9]
	v_mfma_f32_16x16x32_bf16 v[2:5], v[218:221], v[190:193], v[2:5]
	s_setprio 0
	s_add_i32 s41, s41, 2
	s_add_u32 s6, s6, 0x100
	s_addc_u32 s7, s7, 0
	s_add_u32 s28, s28, 0x100
	s_addc_u32 s29, s29, 0
	s_cmp_gt_u32 s41, 29
	s_barrier
	s_cbranch_scc0 .LBB0_139
	s_cmp_gt_i32 s79, 3
	s_mov_b64 s[6:7], -1
	s_cbranch_scc0 .LBB0_146
	s_lshl_b32 s10, s82, 8
	v_lshl_or_b32 v140, s80, 8, v149
	s_cmp_lg_u32 s79, 4
	v_ashrrev_i32_e32 v141, 31, v140
	s_cbranch_scc0 .LBB0_143
	v_readlane_b32 s6, v252, 55
	v_readlane_b32 s7, v252, 56
	v_add_u32_e32 v150, s10, v147
	s_nop 0
	v_mov_b64_e32 v[142:143], s[6:7]
	s_mov_b32 s6, 0x9000
	v_mad_i64_i32 v[142:143], s[6:7], v150, s6, v[142:143]
	v_lshl_add_u64 v[142:143], v[140:141], 1, v[142:143]
	v_cvt_pk_bf16_f32 v150, v126, v127
	v_cvt_pk_bf16_f32 v151, v128, v129
	v_cvt_pk_bf16_f32 v152, v122, v123
	v_cvt_pk_bf16_f32 v153, v124, v125
	global_store_dwordx4 v[142:143], v[150:153], off nt
	v_add_co_u32_e32 v154, vcc, s44, v142
	s_nop 0
	v_cvt_pk_bf16_f32 v150, v114, v115
	v_cvt_pk_bf16_f32 v151, v116, v117
	v_cvt_pk_bf16_f32 v152, v106, v107
	v_cvt_pk_bf16_f32 v153, v108, v109
	global_store_dwordx4 v[142:143], v[150:153], off offset:256 nt
	v_addc_co_u32_e32 v155, vcc, 0, v143, vcc
	s_nop 0
	v_cvt_pk_bf16_f32 v150, v118, v119
	v_cvt_pk_bf16_f32 v151, v120, v121
	v_cvt_pk_bf16_f32 v152, v110, v111
	v_cvt_pk_bf16_f32 v153, v112, v113
	global_store_dwordx4 v[154:155], v[150:153], off nt
	s_mov_b64 s[6:7], 0
	s_nop 0
	v_cvt_pk_bf16_f32 v150, v98, v99
	v_cvt_pk_bf16_f32 v151, v100, v101
	v_cvt_pk_bf16_f32 v152, v90, v91
	v_cvt_pk_bf16_f32 v153, v92, v93
	global_store_dwordx4 v[154:155], v[150:153], off offset:256 nt
	v_add_co_u32_e32 v154, vcc, s45, v142
	s_nop 0
	v_cvt_pk_bf16_f32 v150, v102, v103
	v_cvt_pk_bf16_f32 v151, v104, v105
	v_cvt_pk_bf16_f32 v152, v94, v95
	v_cvt_pk_bf16_f32 v153, v96, v97
	s_nop 0
	v_addc_co_u32_e32 v155, vcc, 0, v143, vcc
	global_store_dwordx4 v[154:155], v[150:153], off nt
	s_nop 1
	v_cvt_pk_bf16_f32 v150, v82, v83
	v_cvt_pk_bf16_f32 v151, v84, v85
	v_cvt_pk_bf16_f32 v152, v74, v75
	v_cvt_pk_bf16_f32 v153, v76, v77
	global_store_dwordx4 v[154:155], v[150:153], off offset:256 nt
	v_add_co_u32_e32 v154, vcc, s90, v142
	s_nop 0
	v_cvt_pk_bf16_f32 v150, v86, v87
	v_cvt_pk_bf16_f32 v151, v88, v89
	v_cvt_pk_bf16_f32 v152, v78, v79
	v_cvt_pk_bf16_f32 v153, v80, v81
	s_nop 0
	v_addc_co_u32_e32 v155, vcc, 0, v143, vcc
	global_store_dwordx4 v[154:155], v[150:153], off nt
	s_nop 1
	v_cvt_pk_bf16_f32 v150, v70, v71
	v_cvt_pk_bf16_f32 v151, v72, v73
	v_cvt_pk_bf16_f32 v152, v66, v67
	v_cvt_pk_bf16_f32 v153, v68, v69
	global_store_dwordx4 v[154:155], v[150:153], off offset:256 nt
	v_add_co_u32_e32 v154, vcc, s20, v142
	s_nop 0
	v_cvt_pk_bf16_f32 v150, v62, v63
	v_cvt_pk_bf16_f32 v151, v64, v65
	v_cvt_pk_bf16_f32 v152, v58, v59
	v_cvt_pk_bf16_f32 v153, v60, v61
	s_nop 0
	v_addc_co_u32_e32 v155, vcc, 0, v143, vcc
	global_store_dwordx4 v[154:155], v[150:153], off nt
	s_nop 1
	v_cvt_pk_bf16_f32 v150, v50, v51
	v_cvt_pk_bf16_f32 v151, v52, v53
	v_cvt_pk_bf16_f32 v152, v42, v43
	v_cvt_pk_bf16_f32 v153, v44, v45
	global_store_dwordx4 v[154:155], v[150:153], off offset:256 nt
	v_add_co_u32_e32 v154, vcc, s21, v142
	s_nop 0
	v_cvt_pk_bf16_f32 v150, v54, v55
	v_cvt_pk_bf16_f32 v151, v56, v57
	v_cvt_pk_bf16_f32 v152, v46, v47
	v_cvt_pk_bf16_f32 v153, v48, v49
	s_nop 0
	v_addc_co_u32_e32 v155, vcc, 0, v143, vcc
	global_store_dwordx4 v[154:155], v[150:153], off nt
	s_nop 1
	v_cvt_pk_bf16_f32 v150, v34, v35
	v_cvt_pk_bf16_f32 v151, v36, v37
	v_cvt_pk_bf16_f32 v152, v26, v27
	v_cvt_pk_bf16_f32 v153, v28, v29
	global_store_dwordx4 v[154:155], v[150:153], off offset:256 nt
	v_add_co_u32_e32 v154, vcc, s22, v142
	s_nop 0
	v_cvt_pk_bf16_f32 v150, v38, v39
	v_cvt_pk_bf16_f32 v151, v40, v41
	v_cvt_pk_bf16_f32 v152, v30, v31
	v_cvt_pk_bf16_f32 v153, v32, v33
	s_nop 0
	v_addc_co_u32_e32 v155, vcc, 0, v143, vcc
	global_store_dwordx4 v[154:155], v[150:153], off nt
	v_add_co_u32_e32 v142, vcc, s23, v142
	s_nop 0
	v_cvt_pk_bf16_f32 v150, v18, v19
	v_cvt_pk_bf16_f32 v151, v20, v21
	v_cvt_pk_bf16_f32 v152, v10, v11
	v_cvt_pk_bf16_f32 v153, v12, v13
	global_store_dwordx4 v[154:155], v[150:153], off offset:256 nt
	v_addc_co_u32_e32 v143, vcc, 0, v143, vcc
	s_nop 0
	v_cvt_pk_bf16_f32 v150, v22, v23
	v_cvt_pk_bf16_f32 v151, v24, v25
	v_cvt_pk_bf16_f32 v152, v14, v15
	v_cvt_pk_bf16_f32 v153, v16, v17
	global_store_dwordx4 v[142:143], v[150:153], off nt
	s_nop 1
	v_cvt_pk_bf16_f32 v150, v6, v7
	v_cvt_pk_bf16_f32 v151, v8, v9
	v_cvt_pk_bf16_f32 v152, v2, v3
	v_cvt_pk_bf16_f32 v153, v4, v5
	global_store_dwordx4 v[142:143], v[150:153], off offset:256 nt
.LBB0_143:
	s_andn2_b64 vcc, exec, s[6:7]
	s_cbranch_vccnz .LBB0_145
	v_readlane_b32 s6, v252, 53
	v_readlane_b32 s7, v252, 54
	v_add_u32_e32 v150, s10, v148
	v_mul_f32_e32 v154, 0x3d372713, v93
	v_mov_b64_e32 v[142:143], s[6:7]
	s_mov_b32 s6, 0x9000
	v_mad_i64_i32 v[142:143], s[6:7], v150, s6, v[142:143]
	v_lshl_add_u64 v[140:141], v[140:141], 1, v[142:143]
	v_mul_f32_e32 v142, 0x3d372713, v126
	v_mul_f32_e32 v142, v126, v142
	v_mul_f32_e32 v143, 0x3d372713, v127
	v_fma_f32 v142, v126, v142, v126
	v_mul_f32_e32 v143, v127, v143
	v_mul_f32_e32 v142, 0x3fcc422a, v142
	v_fma_f32 v143, v127, v143, v127
	v_mul_f32_e32 v142, 0xbfb8aa3b, v142
	v_mul_f32_e32 v143, 0x3fcc422a, v143
	v_exp_f32_e32 v142, v142
	v_mul_f32_e32 v143, 0xbfb8aa3b, v143
	v_exp_f32_e32 v143, v143
	v_mul_f32_e32 v154, v93, v154
	v_add_f32_e32 v142, 1.0, v142
	v_rcp_f32_e32 v142, v142
	v_add_f32_e32 v143, 1.0, v143
	v_rcp_f32_e32 v143, v143
	v_fma_f32 v154, v93, v154, v93
	v_mul_f32_e32 v142, v126, v142
	v_mul_f32_e32 v154, 0x3fcc422a, v154
	v_mul_f32_e32 v143, v127, v143
	v_cvt_pk_bf16_f32 v150, v142, v143
	v_mul_f32_e32 v142, 0x3d372713, v128
	v_mul_f32_e32 v142, v128, v142
	v_mul_f32_e32 v143, 0x3d372713, v129
	v_fma_f32 v142, v128, v142, v128
	v_mul_f32_e32 v143, v129, v143
	v_mul_f32_e32 v142, 0x3fcc422a, v142
	v_fma_f32 v143, v129, v143, v129
	v_mul_f32_e32 v142, 0xbfb8aa3b, v142
	v_mul_f32_e32 v143, 0x3fcc422a, v143
	v_exp_f32_e32 v142, v142
	v_mul_f32_e32 v143, 0xbfb8aa3b, v143
	v_exp_f32_e32 v143, v143
	v_mul_f32_e32 v154, 0xbfb8aa3b, v154
	v_add_f32_e32 v142, 1.0, v142
	v_rcp_f32_e32 v142, v142
	v_add_f32_e32 v143, 1.0, v143
	v_rcp_f32_e32 v143, v143
	v_exp_f32_e32 v154, v154
	v_mul_f32_e32 v142, v128, v142
	v_mul_f32_e32 v143, v129, v143
	v_cvt_pk_bf16_f32 v151, v142, v143
	v_mul_f32_e32 v142, 0x3d372713, v122
	v_mul_f32_e32 v142, v122, v142
	v_mul_f32_e32 v143, 0x3d372713, v123
	v_fma_f32 v142, v122, v142, v122
	v_mul_f32_e32 v143, v123, v143
	v_mul_f32_e32 v142, 0x3fcc422a, v142
	v_fma_f32 v143, v123, v143, v123
	v_mul_f32_e32 v142, 0xbfb8aa3b, v142
	v_mul_f32_e32 v143, 0x3fcc422a, v143
	v_exp_f32_e32 v142, v142
	v_mul_f32_e32 v143, 0xbfb8aa3b, v143
	v_exp_f32_e32 v143, v143
	v_add_f32_e32 v154, 1.0, v154
	v_add_f32_e32 v142, 1.0, v142
	v_rcp_f32_e32 v142, v142
	v_add_f32_e32 v143, 1.0, v143
	v_rcp_f32_e32 v143, v143
	v_rcp_f32_e32 v154, v154
	v_mul_f32_e32 v142, v122, v142
	v_mul_f32_e32 v143, v123, v143
	v_cvt_pk_bf16_f32 v152, v142, v143
	v_mul_f32_e32 v142, 0x3d372713, v124
	v_mul_f32_e32 v142, v124, v142
	v_mul_f32_e32 v143, 0x3d372713, v125
	v_fma_f32 v142, v124, v142, v124
	v_mul_f32_e32 v143, v125, v143
	v_mul_f32_e32 v142, 0x3fcc422a, v142
	v_fma_f32 v143, v125, v143, v125
	v_mul_f32_e32 v142, 0xbfb8aa3b, v142
	v_mul_f32_e32 v143, 0x3fcc422a, v143
	v_exp_f32_e32 v142, v142
	v_mul_f32_e32 v143, 0xbfb8aa3b, v143
	v_exp_f32_e32 v143, v143
	v_mul_f32_e32 v154, v93, v154
	v_add_f32_e32 v142, 1.0, v142
	v_rcp_f32_e32 v142, v142
	v_add_f32_e32 v143, 1.0, v143
	v_rcp_f32_e32 v143, v143
	v_mul_f32_e32 v142, v124, v142
	v_mul_f32_e32 v143, v125, v143
	v_cvt_pk_bf16_f32 v153, v142, v143
	v_mul_f32_e32 v142, 0x3d372713, v114
	v_mul_f32_e32 v142, v114, v142
	v_mul_f32_e32 v143, 0x3d372713, v115
	v_fma_f32 v142, v114, v142, v114
	v_mul_f32_e32 v143, v115, v143
	v_mul_f32_e32 v142, 0x3fcc422a, v142
	v_fma_f32 v143, v115, v143, v115
	v_mul_f32_e32 v142, 0xbfb8aa3b, v142
	v_mul_f32_e32 v143, 0x3fcc422a, v143
	v_exp_f32_e32 v142, v142
	v_mul_f32_e32 v143, 0xbfb8aa3b, v143
	v_exp_f32_e32 v143, v143
	global_store_dwordx4 v[140:141], v[150:153], off nt
	v_add_f32_e32 v142, 1.0, v142
	v_rcp_f32_e32 v142, v142
	v_add_f32_e32 v143, 1.0, v143
	v_rcp_f32_e32 v143, v143
	v_mul_f32_e32 v142, v114, v142
	v_mul_f32_e32 v143, v115, v143
	v_cvt_pk_bf16_f32 v150, v142, v143
	v_mul_f32_e32 v142, 0x3d372713, v116
	v_mul_f32_e32 v142, v116, v142
	v_mul_f32_e32 v143, 0x3d372713, v117
	v_fma_f32 v142, v116, v142, v116
	v_mul_f32_e32 v143, v117, v143
	v_mul_f32_e32 v142, 0x3fcc422a, v142
	v_fma_f32 v143, v117, v143, v117
	v_mul_f32_e32 v142, 0xbfb8aa3b, v142
	v_mul_f32_e32 v143, 0x3fcc422a, v143
	v_exp_f32_e32 v142, v142
	v_mul_f32_e32 v143, 0xbfb8aa3b, v143
	v_exp_f32_e32 v143, v143
	v_add_f32_e32 v142, 1.0, v142
	v_rcp_f32_e32 v142, v142
	v_add_f32_e32 v143, 1.0, v143
	v_rcp_f32_e32 v143, v143
	v_mul_f32_e32 v142, v116, v142
	v_mul_f32_e32 v143, v117, v143
	v_cvt_pk_bf16_f32 v151, v142, v143
	v_mul_f32_e32 v142, 0x3d372713, v106
	v_mul_f32_e32 v142, v106, v142
	v_mul_f32_e32 v143, 0x3d372713, v107
	v_fma_f32 v142, v106, v142, v106
	v_mul_f32_e32 v143, v107, v143
	v_mul_f32_e32 v142, 0x3fcc422a, v142
	v_fma_f32 v143, v107, v143, v107
	v_mul_f32_e32 v142, 0xbfb8aa3b, v142
	v_mul_f32_e32 v143, 0x3fcc422a, v143
	v_exp_f32_e32 v142, v142
	v_mul_f32_e32 v143, 0xbfb8aa3b, v143
	v_exp_f32_e32 v143, v143
	v_add_f32_e32 v142, 1.0, v142
	v_rcp_f32_e32 v142, v142
	v_add_f32_e32 v143, 1.0, v143
	v_rcp_f32_e32 v143, v143
	v_mul_f32_e32 v142, v106, v142
	v_mul_f32_e32 v143, v107, v143
	v_cvt_pk_bf16_f32 v152, v142, v143
	v_mul_f32_e32 v142, 0x3d372713, v108
	v_mul_f32_e32 v142, v108, v142
	v_mul_f32_e32 v143, 0x3d372713, v109
	v_fma_f32 v142, v108, v142, v108
	v_mul_f32_e32 v143, v109, v143
	v_mul_f32_e32 v142, 0x3fcc422a, v142
	v_fma_f32 v143, v109, v143, v109
	v_mul_f32_e32 v142, 0xbfb8aa3b, v142
	v_mul_f32_e32 v143, 0x3fcc422a, v143
	v_exp_f32_e32 v142, v142
	v_mul_f32_e32 v143, 0xbfb8aa3b, v143
	v_exp_f32_e32 v143, v143
	v_add_f32_e32 v142, 1.0, v142
	v_rcp_f32_e32 v142, v142
	v_add_f32_e32 v143, 1.0, v143
	v_rcp_f32_e32 v143, v143
	v_mul_f32_e32 v142, v108, v142
	v_mul_f32_e32 v143, v109, v143
	v_cvt_pk_bf16_f32 v153, v142, v143
	v_mul_f32_e32 v142, 0x3d372713, v118
	v_mul_f32_e32 v142, v118, v142
	v_mul_f32_e32 v143, 0x3d372713, v119
	v_fma_f32 v142, v118, v142, v118
	v_mul_f32_e32 v143, v119, v143
	v_mul_f32_e32 v142, 0x3fcc422a, v142
	v_fma_f32 v143, v119, v143, v119
	v_mul_f32_e32 v142, 0xbfb8aa3b, v142
	v_mul_f32_e32 v143, 0x3fcc422a, v143
	v_exp_f32_e32 v142, v142
	v_mul_f32_e32 v143, 0xbfb8aa3b, v143
	v_exp_f32_e32 v143, v143
	global_store_dwordx4 v[140:141], v[150:153], off offset:256 nt
	v_add_f32_e32 v142, 1.0, v142
	v_rcp_f32_e32 v142, v142
	v_add_f32_e32 v143, 1.0, v143
	v_rcp_f32_e32 v143, v143
	v_mul_f32_e32 v142, v118, v142
	v_mul_f32_e32 v143, v119, v143
	v_cvt_pk_bf16_f32 v150, v142, v143
	v_mul_f32_e32 v142, 0x3d372713, v120
	v_mul_f32_e32 v142, v120, v142
	v_mul_f32_e32 v143, 0x3d372713, v121
	v_fma_f32 v142, v120, v142, v120
	v_mul_f32_e32 v143, v121, v143
	v_mul_f32_e32 v142, 0x3fcc422a, v142
	v_fma_f32 v143, v121, v143, v121
	v_mul_f32_e32 v142, 0xbfb8aa3b, v142
	v_mul_f32_e32 v143, 0x3fcc422a, v143
	v_exp_f32_e32 v142, v142
	v_mul_f32_e32 v143, 0xbfb8aa3b, v143
	v_exp_f32_e32 v143, v143
	v_add_f32_e32 v142, 1.0, v142
	v_rcp_f32_e32 v142, v142
	v_add_f32_e32 v143, 1.0, v143
	v_rcp_f32_e32 v143, v143
	v_mul_f32_e32 v142, v120, v142
	v_mul_f32_e32 v143, v121, v143
	v_cvt_pk_bf16_f32 v151, v142, v143
	v_mul_f32_e32 v142, 0x3d372713, v110
	v_mul_f32_e32 v142, v110, v142
	v_mul_f32_e32 v143, 0x3d372713, v111
	v_fma_f32 v142, v110, v142, v110
	v_mul_f32_e32 v143, v111, v143
	v_mul_f32_e32 v142, 0x3fcc422a, v142
	v_fma_f32 v143, v111, v143, v111
	v_mul_f32_e32 v142, 0xbfb8aa3b, v142
	v_mul_f32_e32 v143, 0x3fcc422a, v143
	v_exp_f32_e32 v142, v142
	v_mul_f32_e32 v143, 0xbfb8aa3b, v143
	v_exp_f32_e32 v143, v143
	v_add_f32_e32 v142, 1.0, v142
	v_rcp_f32_e32 v142, v142
	v_add_f32_e32 v143, 1.0, v143
	v_rcp_f32_e32 v143, v143
	v_mul_f32_e32 v142, v110, v142
	v_mul_f32_e32 v143, v111, v143
	v_cvt_pk_bf16_f32 v152, v142, v143
	v_mul_f32_e32 v142, 0x3d372713, v112
	v_mul_f32_e32 v142, v112, v142
	v_mul_f32_e32 v143, 0x3d372713, v113
	v_fma_f32 v142, v112, v142, v112
	v_mul_f32_e32 v143, v113, v143
	v_mul_f32_e32 v142, 0x3fcc422a, v142
	v_fma_f32 v143, v113, v143, v113
	v_mul_f32_e32 v142, 0xbfb8aa3b, v142
	v_mul_f32_e32 v143, 0x3fcc422a, v143
	v_exp_f32_e32 v142, v142
	v_mul_f32_e32 v143, 0xbfb8aa3b, v143
	v_exp_f32_e32 v143, v143
	v_add_f32_e32 v142, 1.0, v142
	v_rcp_f32_e32 v142, v142
	v_add_f32_e32 v143, 1.0, v143
	v_rcp_f32_e32 v143, v143
	v_mul_f32_e32 v142, v112, v142
	v_mul_f32_e32 v143, v113, v143
	v_cvt_pk_bf16_f32 v153, v142, v143
	v_add_co_u32_e32 v142, vcc, s44, v140
	s_nop 1
	v_addc_co_u32_e32 v143, vcc, 0, v141, vcc
	global_store_dwordx4 v[142:143], v[150:153], off nt
	s_nop 1
	v_mul_f32_e32 v150, 0x3d372713, v98
	v_mul_f32_e32 v151, 0x3d372713, v99
	v_mul_f32_e32 v150, v98, v150
	v_mul_f32_e32 v151, v99, v151
	v_fma_f32 v150, v98, v150, v98
	v_fma_f32 v151, v99, v151, v99
	v_mul_f32_e32 v150, 0x3fcc422a, v150
	v_mul_f32_e32 v151, 0x3fcc422a, v151
	v_mul_f32_e32 v150, 0xbfb8aa3b, v150
	v_mul_f32_e32 v151, 0xbfb8aa3b, v151
	v_exp_f32_e32 v150, v150
	v_exp_f32_e32 v151, v151
	v_mul_f32_e32 v152, 0x3d372713, v101
	v_mul_f32_e32 v152, v101, v152
	v_add_f32_e32 v150, 1.0, v150
	v_add_f32_e32 v151, 1.0, v151
	v_rcp_f32_e32 v150, v150
	v_rcp_f32_e32 v151, v151
	v_fma_f32 v152, v101, v152, v101
	v_mul_f32_e32 v152, 0x3fcc422a, v152
	v_mul_f32_e32 v150, v98, v150
	v_mul_f32_e32 v151, v99, v151
	v_cvt_pk_bf16_f32 v150, v150, v151
	v_mul_f32_e32 v151, 0x3d372713, v100
	v_mul_f32_e32 v151, v100, v151
	v_fma_f32 v151, v100, v151, v100
	v_mul_f32_e32 v151, 0x3fcc422a, v151
	v_mul_f32_e32 v151, 0xbfb8aa3b, v151
	v_mul_f32_e32 v152, 0xbfb8aa3b, v152
	v_exp_f32_e32 v151, v151
	v_exp_f32_e32 v152, v152
	v_mul_f32_e32 v153, 0x3d372713, v91
	v_mul_f32_e32 v153, v91, v153
	v_add_f32_e32 v151, 1.0, v151
	v_add_f32_e32 v152, 1.0, v152
	v_rcp_f32_e32 v151, v151
	v_rcp_f32_e32 v152, v152
	v_fma_f32 v153, v91, v153, v91
	v_mul_f32_e32 v153, 0x3fcc422a, v153
	v_mul_f32_e32 v151, v100, v151
	v_mul_f32_e32 v152, v101, v152
	v_cvt_pk_bf16_f32 v151, v151, v152
	v_mul_f32_e32 v152, 0x3d372713, v90
	v_mul_f32_e32 v152, v90, v152
	v_fma_f32 v152, v90, v152, v90
	v_mul_f32_e32 v152, 0x3fcc422a, v152
	v_mul_f32_e32 v152, 0xbfb8aa3b, v152
	v_mul_f32_e32 v153, 0xbfb8aa3b, v153
	v_exp_f32_e32 v152, v152
	v_exp_f32_e32 v153, v153
	v_add_f32_e32 v152, 1.0, v152
	v_add_f32_e32 v153, 1.0, v153
	v_rcp_f32_e32 v152, v152
	v_rcp_f32_e32 v153, v153
	v_mul_f32_e32 v152, v90, v152
	v_mul_f32_e32 v153, v91, v153
	v_cvt_pk_bf16_f32 v152, v152, v153
	v_mul_f32_e32 v153, 0x3d372713, v92
	v_mul_f32_e32 v153, v92, v153
	v_fma_f32 v153, v92, v153, v92
	v_mul_f32_e32 v153, 0x3fcc422a, v153
	v_mul_f32_e32 v153, 0xbfb8aa3b, v153
	v_exp_f32_e32 v153, v153
	s_nop 0
	v_add_f32_e32 v153, 1.0, v153
	v_rcp_f32_e32 v153, v153
	s_nop 0
	v_mul_f32_e32 v153, v92, v153
	v_cvt_pk_bf16_f32 v153, v153, v154
	global_store_dwordx4 v[142:143], v[150:153], off offset:256 nt
	v_mul_f32_e32 v142, 0x3d372713, v102
	v_mul_f32_e32 v142, v102, v142
	v_mul_f32_e32 v143, 0x3d372713, v103
	v_fma_f32 v142, v102, v142, v102
	v_mul_f32_e32 v143, v103, v143
	v_mul_f32_e32 v142, 0x3fcc422a, v142
	v_fma_f32 v143, v103, v143, v103
	v_mul_f32_e32 v142, 0xbfb8aa3b, v142
	v_mul_f32_e32 v143, 0x3fcc422a, v143
	v_exp_f32_e32 v142, v142
	v_mul_f32_e32 v143, 0xbfb8aa3b, v143
	v_exp_f32_e32 v143, v143
	v_mul_f32_e32 v154, 0x3d372713, v77
	v_add_f32_e32 v142, 1.0, v142
	v_rcp_f32_e32 v142, v142
	v_add_f32_e32 v143, 1.0, v143
	v_rcp_f32_e32 v143, v143
	v_mul_f32_e32 v154, v77, v154
	v_mul_f32_e32 v142, v102, v142
	v_fma_f32 v154, v77, v154, v77
	v_mul_f32_e32 v143, v103, v143
	v_cvt_pk_bf16_f32 v150, v142, v143
	v_mul_f32_e32 v142, 0x3d372713, v104
	v_mul_f32_e32 v142, v104, v142
	v_mul_f32_e32 v143, 0x3d372713, v105
	v_fma_f32 v142, v104, v142, v104
	v_mul_f32_e32 v143, v105, v143
	v_mul_f32_e32 v142, 0x3fcc422a, v142
	v_fma_f32 v143, v105, v143, v105
	v_mul_f32_e32 v142, 0xbfb8aa3b, v142
	v_mul_f32_e32 v143, 0x3fcc422a, v143
	v_exp_f32_e32 v142, v142
	v_mul_f32_e32 v143, 0xbfb8aa3b, v143
	v_exp_f32_e32 v143, v143
	v_mul_f32_e32 v154, 0x3fcc422a, v154
	v_add_f32_e32 v142, 1.0, v142
	v_rcp_f32_e32 v142, v142
	v_add_f32_e32 v143, 1.0, v143
	v_rcp_f32_e32 v143, v143
	v_mul_f32_e32 v154, 0xbfb8aa3b, v154
	v_mul_f32_e32 v142, v104, v142
	v_exp_f32_e32 v154, v154
	v_mul_f32_e32 v143, v105, v143
	v_cvt_pk_bf16_f32 v151, v142, v143
	v_mul_f32_e32 v142, 0x3d372713, v94
	v_mul_f32_e32 v142, v94, v142
	v_mul_f32_e32 v143, 0x3d372713, v95
	v_fma_f32 v142, v94, v142, v94
	v_mul_f32_e32 v143, v95, v143
	v_mul_f32_e32 v142, 0x3fcc422a, v142
	v_fma_f32 v143, v95, v143, v95
	v_mul_f32_e32 v142, 0xbfb8aa3b, v142
	v_mul_f32_e32 v143, 0x3fcc422a, v143
	v_exp_f32_e32 v142, v142
	v_mul_f32_e32 v143, 0xbfb8aa3b, v143
	v_exp_f32_e32 v143, v143
	v_add_f32_e32 v154, 1.0, v154
	v_add_f32_e32 v142, 1.0, v142
	v_rcp_f32_e32 v142, v142
	v_add_f32_e32 v143, 1.0, v143
	v_rcp_f32_e32 v143, v143
	v_rcp_f32_e32 v154, v154
	v_mul_f32_e32 v142, v94, v142
	v_mul_f32_e32 v143, v95, v143
	v_cvt_pk_bf16_f32 v152, v142, v143
	v_mul_f32_e32 v142, 0x3d372713, v96
	v_mul_f32_e32 v142, v96, v142
	v_mul_f32_e32 v143, 0x3d372713, v97
	v_fma_f32 v142, v96, v142, v96
	v_mul_f32_e32 v143, v97, v143
	v_mul_f32_e32 v142, 0x3fcc422a, v142
	v_fma_f32 v143, v97, v143, v97
	v_mul_f32_e32 v142, 0xbfb8aa3b, v142
	v_mul_f32_e32 v143, 0x3fcc422a, v143
	v_exp_f32_e32 v142, v142
	v_mul_f32_e32 v143, 0xbfb8aa3b, v143
	v_exp_f32_e32 v143, v143
	v_mul_f32_e32 v154, v77, v154
	v_add_f32_e32 v142, 1.0, v142
	v_rcp_f32_e32 v142, v142
	v_add_f32_e32 v143, 1.0, v143
	v_rcp_f32_e32 v143, v143
	v_mul_f32_e32 v142, v96, v142
	v_mul_f32_e32 v143, v97, v143
	v_cvt_pk_bf16_f32 v153, v142, v143
	v_add_co_u32_e32 v142, vcc, s45, v140
	s_nop 1
	v_addc_co_u32_e32 v143, vcc, 0, v141, vcc
	global_store_dwordx4 v[142:143], v[150:153], off nt
	s_nop 1
	v_mul_f32_e32 v150, 0x3d372713, v82
	v_mul_f32_e32 v151, 0x3d372713, v83
	v_mul_f32_e32 v150, v82, v150
	v_mul_f32_e32 v151, v83, v151
	v_fma_f32 v150, v82, v150, v82
	v_fma_f32 v151, v83, v151, v83
	v_mul_f32_e32 v150, 0x3fcc422a, v150
	v_mul_f32_e32 v151, 0x3fcc422a, v151
	v_mul_f32_e32 v150, 0xbfb8aa3b, v150
	v_mul_f32_e32 v151, 0xbfb8aa3b, v151
	v_exp_f32_e32 v150, v150
	v_exp_f32_e32 v151, v151
	v_mul_f32_e32 v152, 0x3d372713, v85
	v_mul_f32_e32 v152, v85, v152
	v_add_f32_e32 v150, 1.0, v150
	v_add_f32_e32 v151, 1.0, v151
	v_rcp_f32_e32 v150, v150
	v_rcp_f32_e32 v151, v151
	v_fma_f32 v152, v85, v152, v85
	v_mul_f32_e32 v152, 0x3fcc422a, v152
	v_mul_f32_e32 v150, v82, v150
	v_mul_f32_e32 v151, v83, v151
	v_cvt_pk_bf16_f32 v150, v150, v151
	v_mul_f32_e32 v151, 0x3d372713, v84
	v_mul_f32_e32 v151, v84, v151
	v_fma_f32 v151, v84, v151, v84
	v_mul_f32_e32 v151, 0x3fcc422a, v151
	v_mul_f32_e32 v151, 0xbfb8aa3b, v151
	v_mul_f32_e32 v152, 0xbfb8aa3b, v152
	v_exp_f32_e32 v151, v151
	v_exp_f32_e32 v152, v152
	v_mul_f32_e32 v153, 0x3d372713, v75
	v_mul_f32_e32 v153, v75, v153
	v_add_f32_e32 v151, 1.0, v151
	v_add_f32_e32 v152, 1.0, v152
	v_rcp_f32_e32 v151, v151
	v_rcp_f32_e32 v152, v152
	v_fma_f32 v153, v75, v153, v75
	v_mul_f32_e32 v153, 0x3fcc422a, v153
	v_mul_f32_e32 v151, v84, v151
	v_mul_f32_e32 v152, v85, v152
	v_cvt_pk_bf16_f32 v151, v151, v152
	v_mul_f32_e32 v152, 0x3d372713, v74
	v_mul_f32_e32 v152, v74, v152
	v_fma_f32 v152, v74, v152, v74
	v_mul_f32_e32 v152, 0x3fcc422a, v152
	v_mul_f32_e32 v152, 0xbfb8aa3b, v152
	v_mul_f32_e32 v153, 0xbfb8aa3b, v153
	v_exp_f32_e32 v152, v152
	v_exp_f32_e32 v153, v153
	v_add_f32_e32 v152, 1.0, v152
	v_add_f32_e32 v153, 1.0, v153
	v_rcp_f32_e32 v152, v152
	v_rcp_f32_e32 v153, v153
	v_mul_f32_e32 v152, v74, v152
	v_mul_f32_e32 v153, v75, v153
	v_cvt_pk_bf16_f32 v152, v152, v153
	v_mul_f32_e32 v153, 0x3d372713, v76
	v_mul_f32_e32 v153, v76, v153
	v_fma_f32 v153, v76, v153, v76
	v_mul_f32_e32 v153, 0x3fcc422a, v153
	v_mul_f32_e32 v153, 0xbfb8aa3b, v153
	v_exp_f32_e32 v153, v153
	s_nop 0
	v_add_f32_e32 v153, 1.0, v153
	v_rcp_f32_e32 v153, v153
	s_nop 0
	v_mul_f32_e32 v153, v76, v153
	v_cvt_pk_bf16_f32 v153, v153, v154
	global_store_dwordx4 v[142:143], v[150:153], off offset:256 nt
	v_mul_f32_e32 v142, 0x3d372713, v86
	v_mul_f32_e32 v142, v86, v142
	v_mul_f32_e32 v143, 0x3d372713, v87
	v_fma_f32 v142, v86, v142, v86
	v_mul_f32_e32 v143, v87, v143
	v_mul_f32_e32 v142, 0x3fcc422a, v142
	v_fma_f32 v143, v87, v143, v87
	v_mul_f32_e32 v142, 0xbfb8aa3b, v142
	v_mul_f32_e32 v143, 0x3fcc422a, v143
	v_exp_f32_e32 v142, v142
	v_mul_f32_e32 v143, 0xbfb8aa3b, v143
	v_exp_f32_e32 v143, v143
	v_mul_f32_e32 v154, 0x3d372713, v69
	v_add_f32_e32 v142, 1.0, v142
	v_rcp_f32_e32 v142, v142
	v_add_f32_e32 v143, 1.0, v143
	v_rcp_f32_e32 v143, v143
	v_mul_f32_e32 v154, v69, v154
	v_mul_f32_e32 v142, v86, v142
	v_fma_f32 v154, v69, v154, v69
	v_mul_f32_e32 v143, v87, v143
	v_cvt_pk_bf16_f32 v150, v142, v143
	v_mul_f32_e32 v142, 0x3d372713, v88
	v_mul_f32_e32 v142, v88, v142
	v_mul_f32_e32 v143, 0x3d372713, v89
	v_fma_f32 v142, v88, v142, v88
	v_mul_f32_e32 v143, v89, v143
	v_mul_f32_e32 v142, 0x3fcc422a, v142
	v_fma_f32 v143, v89, v143, v89
	v_mul_f32_e32 v142, 0xbfb8aa3b, v142
	v_mul_f32_e32 v143, 0x3fcc422a, v143
	v_exp_f32_e32 v142, v142
	v_mul_f32_e32 v143, 0xbfb8aa3b, v143
	v_exp_f32_e32 v143, v143
	v_mul_f32_e32 v154, 0x3fcc422a, v154
	v_add_f32_e32 v142, 1.0, v142
	v_rcp_f32_e32 v142, v142
	v_add_f32_e32 v143, 1.0, v143
	v_rcp_f32_e32 v143, v143
	v_mul_f32_e32 v154, 0xbfb8aa3b, v154
	v_mul_f32_e32 v142, v88, v142
	v_exp_f32_e32 v154, v154
	v_mul_f32_e32 v143, v89, v143
	v_cvt_pk_bf16_f32 v151, v142, v143
	v_mul_f32_e32 v142, 0x3d372713, v78
	v_mul_f32_e32 v142, v78, v142
	v_mul_f32_e32 v143, 0x3d372713, v79
	v_fma_f32 v142, v78, v142, v78
	v_mul_f32_e32 v143, v79, v143
	v_mul_f32_e32 v142, 0x3fcc422a, v142
	v_fma_f32 v143, v79, v143, v79
	v_mul_f32_e32 v142, 0xbfb8aa3b, v142
	v_mul_f32_e32 v143, 0x3fcc422a, v143
	v_exp_f32_e32 v142, v142
	v_mul_f32_e32 v143, 0xbfb8aa3b, v143
	v_exp_f32_e32 v143, v143
	v_add_f32_e32 v154, 1.0, v154
	v_add_f32_e32 v142, 1.0, v142
	v_rcp_f32_e32 v142, v142
	v_add_f32_e32 v143, 1.0, v143
	v_rcp_f32_e32 v143, v143
	v_rcp_f32_e32 v154, v154
	v_mul_f32_e32 v142, v78, v142
	v_mul_f32_e32 v143, v79, v143
	v_cvt_pk_bf16_f32 v152, v142, v143
	v_mul_f32_e32 v142, 0x3d372713, v80
	v_mul_f32_e32 v142, v80, v142
	v_mul_f32_e32 v143, 0x3d372713, v81
	v_fma_f32 v142, v80, v142, v80
	v_mul_f32_e32 v143, v81, v143
	v_mul_f32_e32 v142, 0x3fcc422a, v142
	v_fma_f32 v143, v81, v143, v81
	v_mul_f32_e32 v142, 0xbfb8aa3b, v142
	v_mul_f32_e32 v143, 0x3fcc422a, v143
	v_exp_f32_e32 v142, v142
	v_mul_f32_e32 v143, 0xbfb8aa3b, v143
	v_exp_f32_e32 v143, v143
	v_mul_f32_e32 v154, v69, v154
	v_add_f32_e32 v142, 1.0, v142
	v_rcp_f32_e32 v142, v142
	v_add_f32_e32 v143, 1.0, v143
	v_rcp_f32_e32 v143, v143
	v_mul_f32_e32 v142, v80, v142
	v_mul_f32_e32 v143, v81, v143
	v_cvt_pk_bf16_f32 v153, v142, v143
	v_add_co_u32_e32 v142, vcc, s90, v140
	s_nop 1
	v_addc_co_u32_e32 v143, vcc, 0, v141, vcc
	global_store_dwordx4 v[142:143], v[150:153], off nt
	s_nop 1
	v_mul_f32_e32 v150, 0x3d372713, v70
	v_mul_f32_e32 v151, 0x3d372713, v71
	v_mul_f32_e32 v150, v70, v150
	v_mul_f32_e32 v151, v71, v151
	v_fma_f32 v150, v70, v150, v70
	v_fma_f32 v151, v71, v151, v71
	v_mul_f32_e32 v150, 0x3fcc422a, v150
	v_mul_f32_e32 v151, 0x3fcc422a, v151
	v_mul_f32_e32 v150, 0xbfb8aa3b, v150
	v_mul_f32_e32 v151, 0xbfb8aa3b, v151
	v_exp_f32_e32 v150, v150
	v_exp_f32_e32 v151, v151
	v_mul_f32_e32 v152, 0x3d372713, v73
	v_mul_f32_e32 v152, v73, v152
	v_add_f32_e32 v150, 1.0, v150
	v_add_f32_e32 v151, 1.0, v151
	v_rcp_f32_e32 v150, v150
	v_rcp_f32_e32 v151, v151
	v_fma_f32 v152, v73, v152, v73
	v_mul_f32_e32 v152, 0x3fcc422a, v152
	v_mul_f32_e32 v150, v70, v150
	v_mul_f32_e32 v151, v71, v151
	v_cvt_pk_bf16_f32 v150, v150, v151
	v_mul_f32_e32 v151, 0x3d372713, v72
	v_mul_f32_e32 v151, v72, v151
	v_fma_f32 v151, v72, v151, v72
	v_mul_f32_e32 v151, 0x3fcc422a, v151
	v_mul_f32_e32 v151, 0xbfb8aa3b, v151
	v_mul_f32_e32 v152, 0xbfb8aa3b, v152
	v_exp_f32_e32 v151, v151
	v_exp_f32_e32 v152, v152
	v_mul_f32_e32 v153, 0x3d372713, v67
	v_mul_f32_e32 v153, v67, v153
	v_add_f32_e32 v151, 1.0, v151
	v_add_f32_e32 v152, 1.0, v152
	v_rcp_f32_e32 v151, v151
	v_rcp_f32_e32 v152, v152
	v_fma_f32 v153, v67, v153, v67
	v_mul_f32_e32 v153, 0x3fcc422a, v153
	v_mul_f32_e32 v151, v72, v151
	v_mul_f32_e32 v152, v73, v152
	v_cvt_pk_bf16_f32 v151, v151, v152
	v_mul_f32_e32 v152, 0x3d372713, v66
	v_mul_f32_e32 v152, v66, v152
	v_fma_f32 v152, v66, v152, v66
	v_mul_f32_e32 v152, 0x3fcc422a, v152
	v_mul_f32_e32 v152, 0xbfb8aa3b, v152
	v_mul_f32_e32 v153, 0xbfb8aa3b, v153
	v_exp_f32_e32 v152, v152
	v_exp_f32_e32 v153, v153
	v_add_f32_e32 v152, 1.0, v152
	v_add_f32_e32 v153, 1.0, v153
	v_rcp_f32_e32 v152, v152
	v_rcp_f32_e32 v153, v153
	v_mul_f32_e32 v152, v66, v152
	v_mul_f32_e32 v153, v67, v153
	v_cvt_pk_bf16_f32 v152, v152, v153
	v_mul_f32_e32 v153, 0x3d372713, v68
	v_mul_f32_e32 v153, v68, v153
	v_fma_f32 v153, v68, v153, v68
	v_mul_f32_e32 v153, 0x3fcc422a, v153
	v_mul_f32_e32 v153, 0xbfb8aa3b, v153
	v_exp_f32_e32 v153, v153
	s_nop 0
	v_add_f32_e32 v153, 1.0, v153
	v_rcp_f32_e32 v153, v153
	s_nop 0
	v_mul_f32_e32 v153, v68, v153
	v_cvt_pk_bf16_f32 v153, v153, v154
	global_store_dwordx4 v[142:143], v[150:153], off offset:256 nt
	v_mul_f32_e32 v142, 0x3d372713, v62
	v_mul_f32_e32 v142, v62, v142
	v_mul_f32_e32 v143, 0x3d372713, v63
	v_fma_f32 v142, v62, v142, v62
	v_mul_f32_e32 v143, v63, v143
	v_mul_f32_e32 v142, 0x3fcc422a, v142
	v_fma_f32 v143, v63, v143, v63
	v_mul_f32_e32 v142, 0xbfb8aa3b, v142
	v_mul_f32_e32 v143, 0x3fcc422a, v143
	v_exp_f32_e32 v142, v142
	v_mul_f32_e32 v143, 0xbfb8aa3b, v143
	v_exp_f32_e32 v143, v143
	v_mul_f32_e32 v154, 0x3d372713, v45
	v_add_f32_e32 v142, 1.0, v142
	v_rcp_f32_e32 v142, v142
	v_add_f32_e32 v143, 1.0, v143
	v_rcp_f32_e32 v143, v143
	v_mul_f32_e32 v154, v45, v154
	v_mul_f32_e32 v142, v62, v142
	v_fma_f32 v154, v45, v154, v45
	v_mul_f32_e32 v143, v63, v143
	v_cvt_pk_bf16_f32 v150, v142, v143
	v_mul_f32_e32 v142, 0x3d372713, v64
	v_mul_f32_e32 v142, v64, v142
	v_mul_f32_e32 v143, 0x3d372713, v65
	v_fma_f32 v142, v64, v142, v64
	v_mul_f32_e32 v143, v65, v143
	v_mul_f32_e32 v142, 0x3fcc422a, v142
	v_fma_f32 v143, v65, v143, v65
	v_mul_f32_e32 v142, 0xbfb8aa3b, v142
	v_mul_f32_e32 v143, 0x3fcc422a, v143
	v_exp_f32_e32 v142, v142
	v_mul_f32_e32 v143, 0xbfb8aa3b, v143
	v_exp_f32_e32 v143, v143
	v_mul_f32_e32 v154, 0x3fcc422a, v154
	v_add_f32_e32 v142, 1.0, v142
	v_rcp_f32_e32 v142, v142
	v_add_f32_e32 v143, 1.0, v143
	v_rcp_f32_e32 v143, v143
	v_mul_f32_e32 v154, 0xbfb8aa3b, v154
	v_mul_f32_e32 v142, v64, v142
	v_exp_f32_e32 v154, v154
	v_mul_f32_e32 v143, v65, v143
	v_cvt_pk_bf16_f32 v151, v142, v143
	v_mul_f32_e32 v142, 0x3d372713, v58
	v_mul_f32_e32 v142, v58, v142
	v_mul_f32_e32 v143, 0x3d372713, v59
	v_fma_f32 v142, v58, v142, v58
	v_mul_f32_e32 v143, v59, v143
	v_mul_f32_e32 v142, 0x3fcc422a, v142
	v_fma_f32 v143, v59, v143, v59
	v_mul_f32_e32 v142, 0xbfb8aa3b, v142
	v_mul_f32_e32 v143, 0x3fcc422a, v143
	v_exp_f32_e32 v142, v142
	v_mul_f32_e32 v143, 0xbfb8aa3b, v143
	v_exp_f32_e32 v143, v143
	v_add_f32_e32 v154, 1.0, v154
	v_add_f32_e32 v142, 1.0, v142
	v_rcp_f32_e32 v142, v142
	v_add_f32_e32 v143, 1.0, v143
	v_rcp_f32_e32 v143, v143
	v_rcp_f32_e32 v154, v154
	v_mul_f32_e32 v142, v58, v142
	v_mul_f32_e32 v143, v59, v143
	v_cvt_pk_bf16_f32 v152, v142, v143
	v_mul_f32_e32 v142, 0x3d372713, v60
	v_mul_f32_e32 v142, v60, v142
	v_mul_f32_e32 v143, 0x3d372713, v61
	v_fma_f32 v142, v60, v142, v60
	v_mul_f32_e32 v143, v61, v143
	v_mul_f32_e32 v142, 0x3fcc422a, v142
	v_fma_f32 v143, v61, v143, v61
	v_mul_f32_e32 v142, 0xbfb8aa3b, v142
	v_mul_f32_e32 v143, 0x3fcc422a, v143
	v_exp_f32_e32 v142, v142
	v_mul_f32_e32 v143, 0xbfb8aa3b, v143
	v_exp_f32_e32 v143, v143
	v_mul_f32_e32 v154, v45, v154
	v_add_f32_e32 v142, 1.0, v142
	v_rcp_f32_e32 v142, v142
	v_add_f32_e32 v143, 1.0, v143
	v_rcp_f32_e32 v143, v143
	v_mul_f32_e32 v142, v60, v142
	v_mul_f32_e32 v143, v61, v143
	v_cvt_pk_bf16_f32 v153, v142, v143
	v_add_co_u32_e32 v142, vcc, s20, v140
	s_nop 1
	v_addc_co_u32_e32 v143, vcc, 0, v141, vcc
	global_store_dwordx4 v[142:143], v[150:153], off nt
	s_nop 1
	v_mul_f32_e32 v150, 0x3d372713, v50
	v_mul_f32_e32 v151, 0x3d372713, v51
	v_mul_f32_e32 v150, v50, v150
	v_mul_f32_e32 v151, v51, v151
	v_fma_f32 v150, v50, v150, v50
	v_fma_f32 v151, v51, v151, v51
	v_mul_f32_e32 v150, 0x3fcc422a, v150
	v_mul_f32_e32 v151, 0x3fcc422a, v151
	v_mul_f32_e32 v150, 0xbfb8aa3b, v150
	v_mul_f32_e32 v151, 0xbfb8aa3b, v151
	v_exp_f32_e32 v150, v150
	v_exp_f32_e32 v151, v151
	v_mul_f32_e32 v152, 0x3d372713, v53
	v_mul_f32_e32 v152, v53, v152
	v_add_f32_e32 v150, 1.0, v150
	v_add_f32_e32 v151, 1.0, v151
	v_rcp_f32_e32 v150, v150
	v_rcp_f32_e32 v151, v151
	v_fma_f32 v152, v53, v152, v53
	v_mul_f32_e32 v152, 0x3fcc422a, v152
	v_mul_f32_e32 v150, v50, v150
	v_mul_f32_e32 v151, v51, v151
	v_cvt_pk_bf16_f32 v150, v150, v151
	v_mul_f32_e32 v151, 0x3d372713, v52
	v_mul_f32_e32 v151, v52, v151
	v_fma_f32 v151, v52, v151, v52
	v_mul_f32_e32 v151, 0x3fcc422a, v151
	v_mul_f32_e32 v151, 0xbfb8aa3b, v151
	v_mul_f32_e32 v152, 0xbfb8aa3b, v152
	v_exp_f32_e32 v151, v151
	v_exp_f32_e32 v152, v152
	v_mul_f32_e32 v153, 0x3d372713, v43
	v_mul_f32_e32 v153, v43, v153
	v_add_f32_e32 v151, 1.0, v151
	v_add_f32_e32 v152, 1.0, v152
	v_rcp_f32_e32 v151, v151
	v_rcp_f32_e32 v152, v152
	v_fma_f32 v153, v43, v153, v43
	v_mul_f32_e32 v153, 0x3fcc422a, v153
	v_mul_f32_e32 v151, v52, v151
	v_mul_f32_e32 v152, v53, v152
	v_cvt_pk_bf16_f32 v151, v151, v152
	v_mul_f32_e32 v152, 0x3d372713, v42
	v_mul_f32_e32 v152, v42, v152
	v_fma_f32 v152, v42, v152, v42
	v_mul_f32_e32 v152, 0x3fcc422a, v152
	v_mul_f32_e32 v152, 0xbfb8aa3b, v152
	v_mul_f32_e32 v153, 0xbfb8aa3b, v153
	v_exp_f32_e32 v152, v152
	v_exp_f32_e32 v153, v153
	v_add_f32_e32 v152, 1.0, v152
	v_add_f32_e32 v153, 1.0, v153
	v_rcp_f32_e32 v152, v152
	v_rcp_f32_e32 v153, v153
	v_mul_f32_e32 v152, v42, v152
	v_mul_f32_e32 v153, v43, v153
	v_cvt_pk_bf16_f32 v152, v152, v153
	v_mul_f32_e32 v153, 0x3d372713, v44
	v_mul_f32_e32 v153, v44, v153
	v_fma_f32 v153, v44, v153, v44
	v_mul_f32_e32 v153, 0x3fcc422a, v153
	v_mul_f32_e32 v153, 0xbfb8aa3b, v153
	v_exp_f32_e32 v153, v153
	s_nop 0
	v_add_f32_e32 v153, 1.0, v153
	v_rcp_f32_e32 v153, v153
	s_nop 0
	v_mul_f32_e32 v153, v44, v153
	v_cvt_pk_bf16_f32 v153, v153, v154
	global_store_dwordx4 v[142:143], v[150:153], off offset:256 nt
	v_mul_f32_e32 v142, 0x3d372713, v54
	v_mul_f32_e32 v142, v54, v142
	v_mul_f32_e32 v143, 0x3d372713, v55
	v_fma_f32 v142, v54, v142, v54
	v_mul_f32_e32 v143, v55, v143
	v_mul_f32_e32 v142, 0x3fcc422a, v142
	v_fma_f32 v143, v55, v143, v55
	v_mul_f32_e32 v142, 0xbfb8aa3b, v142
	v_mul_f32_e32 v143, 0x3fcc422a, v143
	v_exp_f32_e32 v142, v142
	v_mul_f32_e32 v143, 0xbfb8aa3b, v143
	v_exp_f32_e32 v143, v143
	v_mul_f32_e32 v154, 0x3d372713, v29
	v_add_f32_e32 v142, 1.0, v142
	v_rcp_f32_e32 v142, v142
	v_add_f32_e32 v143, 1.0, v143
	v_rcp_f32_e32 v143, v143
	v_mul_f32_e32 v154, v29, v154
	v_mul_f32_e32 v142, v54, v142
	v_fma_f32 v154, v29, v154, v29
	v_mul_f32_e32 v143, v55, v143
	v_cvt_pk_bf16_f32 v150, v142, v143
	v_mul_f32_e32 v142, 0x3d372713, v56
	v_mul_f32_e32 v142, v56, v142
	v_mul_f32_e32 v143, 0x3d372713, v57
	v_fma_f32 v142, v56, v142, v56
	v_mul_f32_e32 v143, v57, v143
	v_mul_f32_e32 v142, 0x3fcc422a, v142
	v_fma_f32 v143, v57, v143, v57
	v_mul_f32_e32 v142, 0xbfb8aa3b, v142
	v_mul_f32_e32 v143, 0x3fcc422a, v143
	v_exp_f32_e32 v142, v142
	v_mul_f32_e32 v143, 0xbfb8aa3b, v143
	v_exp_f32_e32 v143, v143
	v_mul_f32_e32 v154, 0x3fcc422a, v154
	v_add_f32_e32 v142, 1.0, v142
	v_rcp_f32_e32 v142, v142
	v_add_f32_e32 v143, 1.0, v143
	v_rcp_f32_e32 v143, v143
	v_mul_f32_e32 v154, 0xbfb8aa3b, v154
	v_mul_f32_e32 v142, v56, v142
	v_exp_f32_e32 v154, v154
	v_mul_f32_e32 v143, v57, v143
	v_cvt_pk_bf16_f32 v151, v142, v143
	v_mul_f32_e32 v142, 0x3d372713, v46
	v_mul_f32_e32 v142, v46, v142
	v_mul_f32_e32 v143, 0x3d372713, v47
	v_fma_f32 v142, v46, v142, v46
	v_mul_f32_e32 v143, v47, v143
	v_mul_f32_e32 v142, 0x3fcc422a, v142
	v_fma_f32 v143, v47, v143, v47
	v_mul_f32_e32 v142, 0xbfb8aa3b, v142
	v_mul_f32_e32 v143, 0x3fcc422a, v143
	v_exp_f32_e32 v142, v142
	v_mul_f32_e32 v143, 0xbfb8aa3b, v143
	v_exp_f32_e32 v143, v143
	v_add_f32_e32 v154, 1.0, v154
	v_add_f32_e32 v142, 1.0, v142
	v_rcp_f32_e32 v142, v142
	v_add_f32_e32 v143, 1.0, v143
	v_rcp_f32_e32 v143, v143
	v_rcp_f32_e32 v154, v154
	v_mul_f32_e32 v142, v46, v142
	v_mul_f32_e32 v143, v47, v143
	v_cvt_pk_bf16_f32 v152, v142, v143
	v_mul_f32_e32 v142, 0x3d372713, v48
	v_mul_f32_e32 v142, v48, v142
	v_mul_f32_e32 v143, 0x3d372713, v49
	v_fma_f32 v142, v48, v142, v48
	v_mul_f32_e32 v143, v49, v143
	v_mul_f32_e32 v142, 0x3fcc422a, v142
	v_fma_f32 v143, v49, v143, v49
	v_mul_f32_e32 v142, 0xbfb8aa3b, v142
	v_mul_f32_e32 v143, 0x3fcc422a, v143
	v_exp_f32_e32 v142, v142
	v_mul_f32_e32 v143, 0xbfb8aa3b, v143
	v_exp_f32_e32 v143, v143
	v_mul_f32_e32 v154, v29, v154
	v_add_f32_e32 v142, 1.0, v142
	v_rcp_f32_e32 v142, v142
	v_add_f32_e32 v143, 1.0, v143
	v_rcp_f32_e32 v143, v143
	v_mul_f32_e32 v142, v48, v142
	v_mul_f32_e32 v143, v49, v143
	v_cvt_pk_bf16_f32 v153, v142, v143
	v_add_co_u32_e32 v142, vcc, s21, v140
	s_nop 1
	v_addc_co_u32_e32 v143, vcc, 0, v141, vcc
	global_store_dwordx4 v[142:143], v[150:153], off nt
	s_nop 1
	v_mul_f32_e32 v150, 0x3d372713, v34
	v_mul_f32_e32 v151, 0x3d372713, v35
	v_mul_f32_e32 v150, v34, v150
	v_mul_f32_e32 v151, v35, v151
	v_fma_f32 v150, v34, v150, v34
	v_fma_f32 v151, v35, v151, v35
	v_mul_f32_e32 v150, 0x3fcc422a, v150
	v_mul_f32_e32 v151, 0x3fcc422a, v151
	v_mul_f32_e32 v150, 0xbfb8aa3b, v150
	v_mul_f32_e32 v151, 0xbfb8aa3b, v151
	v_exp_f32_e32 v150, v150
	v_exp_f32_e32 v151, v151
	v_mul_f32_e32 v152, 0x3d372713, v37
	v_mul_f32_e32 v152, v37, v152
	v_add_f32_e32 v150, 1.0, v150
	v_add_f32_e32 v151, 1.0, v151
	v_rcp_f32_e32 v150, v150
	v_rcp_f32_e32 v151, v151
	v_fma_f32 v152, v37, v152, v37
	v_mul_f32_e32 v152, 0x3fcc422a, v152
	v_mul_f32_e32 v150, v34, v150
	v_mul_f32_e32 v151, v35, v151
	v_cvt_pk_bf16_f32 v150, v150, v151
	v_mul_f32_e32 v151, 0x3d372713, v36
	v_mul_f32_e32 v151, v36, v151
	v_fma_f32 v151, v36, v151, v36
	v_mul_f32_e32 v151, 0x3fcc422a, v151
	v_mul_f32_e32 v151, 0xbfb8aa3b, v151
	v_mul_f32_e32 v152, 0xbfb8aa3b, v152
	v_exp_f32_e32 v151, v151
	v_exp_f32_e32 v152, v152
	v_mul_f32_e32 v153, 0x3d372713, v27
	v_mul_f32_e32 v153, v27, v153
	v_add_f32_e32 v151, 1.0, v151
	v_add_f32_e32 v152, 1.0, v152
	v_rcp_f32_e32 v151, v151
	v_rcp_f32_e32 v152, v152
	v_fma_f32 v153, v27, v153, v27
	v_mul_f32_e32 v153, 0x3fcc422a, v153
	v_mul_f32_e32 v151, v36, v151
	v_mul_f32_e32 v152, v37, v152
	v_cvt_pk_bf16_f32 v151, v151, v152
	v_mul_f32_e32 v152, 0x3d372713, v26
	v_mul_f32_e32 v152, v26, v152
	v_fma_f32 v152, v26, v152, v26
	v_mul_f32_e32 v152, 0x3fcc422a, v152
	v_mul_f32_e32 v152, 0xbfb8aa3b, v152
	v_mul_f32_e32 v153, 0xbfb8aa3b, v153
	v_exp_f32_e32 v152, v152
	v_exp_f32_e32 v153, v153
	v_add_f32_e32 v152, 1.0, v152
	v_add_f32_e32 v153, 1.0, v153
	v_rcp_f32_e32 v152, v152
	v_rcp_f32_e32 v153, v153
	v_mul_f32_e32 v152, v26, v152
	v_mul_f32_e32 v153, v27, v153
	v_cvt_pk_bf16_f32 v152, v152, v153
	v_mul_f32_e32 v153, 0x3d372713, v28
	v_mul_f32_e32 v153, v28, v153
	v_fma_f32 v153, v28, v153, v28
	v_mul_f32_e32 v153, 0x3fcc422a, v153
	v_mul_f32_e32 v153, 0xbfb8aa3b, v153
	v_exp_f32_e32 v153, v153
	s_nop 0
	v_add_f32_e32 v153, 1.0, v153
	v_rcp_f32_e32 v153, v153
	s_nop 0
	v_mul_f32_e32 v153, v28, v153
	v_cvt_pk_bf16_f32 v153, v153, v154
	global_store_dwordx4 v[142:143], v[150:153], off offset:256 nt
	v_mul_f32_e32 v142, 0x3d372713, v38
	v_mul_f32_e32 v142, v38, v142
	v_mul_f32_e32 v143, 0x3d372713, v39
	v_fma_f32 v142, v38, v142, v38
	v_mul_f32_e32 v143, v39, v143
	v_mul_f32_e32 v142, 0x3fcc422a, v142
	v_fma_f32 v143, v39, v143, v39
	v_mul_f32_e32 v142, 0xbfb8aa3b, v142
	v_mul_f32_e32 v143, 0x3fcc422a, v143
	v_exp_f32_e32 v142, v142
	v_mul_f32_e32 v143, 0xbfb8aa3b, v143
	v_exp_f32_e32 v143, v143
	v_mul_f32_e32 v154, 0x3d372713, v13
	v_add_f32_e32 v142, 1.0, v142
	v_rcp_f32_e32 v142, v142
	v_add_f32_e32 v143, 1.0, v143
	v_rcp_f32_e32 v143, v143
	v_mul_f32_e32 v154, v13, v154
	v_mul_f32_e32 v142, v38, v142
	v_fma_f32 v154, v13, v154, v13
	v_mul_f32_e32 v143, v39, v143
	v_cvt_pk_bf16_f32 v150, v142, v143
	v_mul_f32_e32 v142, 0x3d372713, v40
	v_mul_f32_e32 v142, v40, v142
	v_mul_f32_e32 v143, 0x3d372713, v41
	v_fma_f32 v142, v40, v142, v40
	v_mul_f32_e32 v143, v41, v143
	v_mul_f32_e32 v142, 0x3fcc422a, v142
	v_fma_f32 v143, v41, v143, v41
	v_mul_f32_e32 v142, 0xbfb8aa3b, v142
	v_mul_f32_e32 v143, 0x3fcc422a, v143
	v_exp_f32_e32 v142, v142
	v_mul_f32_e32 v143, 0xbfb8aa3b, v143
	v_exp_f32_e32 v143, v143
	v_mul_f32_e32 v154, 0x3fcc422a, v154
	v_add_f32_e32 v142, 1.0, v142
	v_rcp_f32_e32 v142, v142
	v_add_f32_e32 v143, 1.0, v143
	v_rcp_f32_e32 v143, v143
	v_mul_f32_e32 v154, 0xbfb8aa3b, v154
	v_mul_f32_e32 v142, v40, v142
	v_exp_f32_e32 v154, v154
	v_mul_f32_e32 v143, v41, v143
	v_cvt_pk_bf16_f32 v151, v142, v143
	v_mul_f32_e32 v142, 0x3d372713, v30
	v_mul_f32_e32 v142, v30, v142
	v_mul_f32_e32 v143, 0x3d372713, v31
	v_fma_f32 v142, v30, v142, v30
	v_mul_f32_e32 v143, v31, v143
	v_mul_f32_e32 v142, 0x3fcc422a, v142
	v_fma_f32 v143, v31, v143, v31
	v_mul_f32_e32 v142, 0xbfb8aa3b, v142
	v_mul_f32_e32 v143, 0x3fcc422a, v143
	v_exp_f32_e32 v142, v142
	v_mul_f32_e32 v143, 0xbfb8aa3b, v143
	v_exp_f32_e32 v143, v143
	v_add_f32_e32 v154, 1.0, v154
	v_add_f32_e32 v142, 1.0, v142
	v_rcp_f32_e32 v142, v142
	v_add_f32_e32 v143, 1.0, v143
	v_rcp_f32_e32 v143, v143
	v_rcp_f32_e32 v154, v154
	v_mul_f32_e32 v142, v30, v142
	v_mul_f32_e32 v143, v31, v143
	v_cvt_pk_bf16_f32 v152, v142, v143
	v_mul_f32_e32 v142, 0x3d372713, v32
	v_mul_f32_e32 v142, v32, v142
	v_mul_f32_e32 v143, 0x3d372713, v33
	v_fma_f32 v142, v32, v142, v32
	v_mul_f32_e32 v143, v33, v143
	v_mul_f32_e32 v142, 0x3fcc422a, v142
	v_fma_f32 v143, v33, v143, v33
	v_mul_f32_e32 v142, 0xbfb8aa3b, v142
	v_mul_f32_e32 v143, 0x3fcc422a, v143
	v_exp_f32_e32 v142, v142
	v_mul_f32_e32 v143, 0xbfb8aa3b, v143
	v_exp_f32_e32 v143, v143
	v_mul_f32_e32 v154, v13, v154
	v_add_f32_e32 v142, 1.0, v142
	v_rcp_f32_e32 v142, v142
	v_add_f32_e32 v143, 1.0, v143
	v_rcp_f32_e32 v143, v143
	v_mul_f32_e32 v142, v32, v142
	v_mul_f32_e32 v143, v33, v143
	v_cvt_pk_bf16_f32 v153, v142, v143
	v_add_co_u32_e32 v142, vcc, s22, v140
	s_nop 1
	v_addc_co_u32_e32 v143, vcc, 0, v141, vcc
	global_store_dwordx4 v[142:143], v[150:153], off nt
	s_nop 1
	v_mul_f32_e32 v150, 0x3d372713, v18
	v_mul_f32_e32 v151, 0x3d372713, v19
	v_mul_f32_e32 v150, v18, v150
	v_mul_f32_e32 v151, v19, v151
	v_fma_f32 v150, v18, v150, v18
	v_fma_f32 v151, v19, v151, v19
	v_mul_f32_e32 v150, 0x3fcc422a, v150
	v_mul_f32_e32 v151, 0x3fcc422a, v151
	v_mul_f32_e32 v150, 0xbfb8aa3b, v150
	v_mul_f32_e32 v151, 0xbfb8aa3b, v151
	v_exp_f32_e32 v150, v150
	v_exp_f32_e32 v151, v151
	v_mul_f32_e32 v152, 0x3d372713, v21
	v_mul_f32_e32 v152, v21, v152
	v_add_f32_e32 v150, 1.0, v150
	v_add_f32_e32 v151, 1.0, v151
	v_rcp_f32_e32 v150, v150
	v_rcp_f32_e32 v151, v151
	v_fma_f32 v152, v21, v152, v21
	v_mul_f32_e32 v152, 0x3fcc422a, v152
	v_mul_f32_e32 v150, v18, v150
	v_mul_f32_e32 v151, v19, v151
	v_cvt_pk_bf16_f32 v150, v150, v151
	v_mul_f32_e32 v151, 0x3d372713, v20
	v_mul_f32_e32 v151, v20, v151
	v_fma_f32 v151, v20, v151, v20
	v_mul_f32_e32 v151, 0x3fcc422a, v151
	v_mul_f32_e32 v151, 0xbfb8aa3b, v151
	v_mul_f32_e32 v152, 0xbfb8aa3b, v152
	v_exp_f32_e32 v151, v151
	v_exp_f32_e32 v152, v152
	v_mul_f32_e32 v153, 0x3d372713, v11
	v_mul_f32_e32 v153, v11, v153
	v_add_f32_e32 v151, 1.0, v151
	v_add_f32_e32 v152, 1.0, v152
	v_rcp_f32_e32 v151, v151
	v_rcp_f32_e32 v152, v152
	v_fma_f32 v153, v11, v153, v11
	v_mul_f32_e32 v153, 0x3fcc422a, v153
	v_mul_f32_e32 v151, v20, v151
	v_mul_f32_e32 v152, v21, v152
	v_cvt_pk_bf16_f32 v151, v151, v152
	v_mul_f32_e32 v152, 0x3d372713, v10
	v_mul_f32_e32 v152, v10, v152
	v_fma_f32 v152, v10, v152, v10
	v_mul_f32_e32 v152, 0x3fcc422a, v152
	v_mul_f32_e32 v152, 0xbfb8aa3b, v152
	v_mul_f32_e32 v153, 0xbfb8aa3b, v153
	v_exp_f32_e32 v152, v152
	v_exp_f32_e32 v153, v153
	v_add_f32_e32 v152, 1.0, v152
	v_add_f32_e32 v153, 1.0, v153
	v_rcp_f32_e32 v152, v152
	v_rcp_f32_e32 v153, v153
	v_mul_f32_e32 v152, v10, v152
	v_mul_f32_e32 v153, v11, v153
	v_cvt_pk_bf16_f32 v152, v152, v153
	v_mul_f32_e32 v153, 0x3d372713, v12
	v_mul_f32_e32 v153, v12, v153
	v_fma_f32 v153, v12, v153, v12
	v_mul_f32_e32 v153, 0x3fcc422a, v153
	v_mul_f32_e32 v153, 0xbfb8aa3b, v153
	v_exp_f32_e32 v153, v153
	s_nop 0
	v_add_f32_e32 v153, 1.0, v153
	v_rcp_f32_e32 v153, v153
	s_nop 0
	v_mul_f32_e32 v153, v12, v153
	v_cvt_pk_bf16_f32 v153, v153, v154
	global_store_dwordx4 v[142:143], v[150:153], off offset:256 nt
	v_mul_f32_e32 v142, 0x3d372713, v22
	v_mul_f32_e32 v142, v22, v142
	v_mul_f32_e32 v143, 0x3d372713, v23
	v_fma_f32 v142, v22, v142, v22
	v_mul_f32_e32 v143, v23, v143
	v_mul_f32_e32 v142, 0x3fcc422a, v142
	v_fma_f32 v143, v23, v143, v23
	v_mul_f32_e32 v142, 0xbfb8aa3b, v142
	v_mul_f32_e32 v143, 0x3fcc422a, v143
	v_exp_f32_e32 v142, v142
	v_mul_f32_e32 v143, 0xbfb8aa3b, v143
	v_exp_f32_e32 v143, v143
	v_add_co_u32_e32 v154, vcc, s23, v140
	v_add_f32_e32 v142, 1.0, v142
	v_rcp_f32_e32 v142, v142
	v_add_f32_e32 v143, 1.0, v143
	v_rcp_f32_e32 v143, v143
	v_addc_co_u32_e32 v155, vcc, 0, v141, vcc
	v_mul_f32_e32 v142, v22, v142
	v_mul_f32_e32 v143, v23, v143
	v_cvt_pk_bf16_f32 v150, v142, v143
	v_mul_f32_e32 v142, 0x3d372713, v24
	v_mul_f32_e32 v142, v24, v142
	v_mul_f32_e32 v143, 0x3d372713, v25
	v_fma_f32 v142, v24, v142, v24
	v_mul_f32_e32 v143, v25, v143
	v_mul_f32_e32 v142, 0x3fcc422a, v142
	v_fma_f32 v143, v25, v143, v25
	v_mul_f32_e32 v142, 0xbfb8aa3b, v142
	v_mul_f32_e32 v143, 0x3fcc422a, v143
	v_exp_f32_e32 v142, v142
	v_mul_f32_e32 v143, 0xbfb8aa3b, v143
	v_exp_f32_e32 v143, v143
	v_mul_f32_e32 v140, 0x3d372713, v6
	v_add_f32_e32 v142, 1.0, v142
	v_rcp_f32_e32 v142, v142
	v_add_f32_e32 v143, 1.0, v143
	v_rcp_f32_e32 v143, v143
	v_mul_f32_e32 v141, 0x3d372713, v7
	v_mul_f32_e32 v142, v24, v142
	v_mul_f32_e32 v140, v6, v140
	v_mul_f32_e32 v143, v25, v143
	v_cvt_pk_bf16_f32 v151, v142, v143
	v_mul_f32_e32 v142, 0x3d372713, v14
	v_mul_f32_e32 v142, v14, v142
	v_mul_f32_e32 v143, 0x3d372713, v15
	v_fma_f32 v142, v14, v142, v14
	v_mul_f32_e32 v143, v15, v143
	v_mul_f32_e32 v142, 0x3fcc422a, v142
	v_fma_f32 v143, v15, v143, v15
	v_mul_f32_e32 v142, 0xbfb8aa3b, v142
	v_mul_f32_e32 v143, 0x3fcc422a, v143
	v_exp_f32_e32 v142, v142
	v_mul_f32_e32 v143, 0xbfb8aa3b, v143
	v_exp_f32_e32 v143, v143
	v_mul_f32_e32 v141, v7, v141
	v_add_f32_e32 v142, 1.0, v142
	v_rcp_f32_e32 v142, v142
	v_add_f32_e32 v143, 1.0, v143
	v_rcp_f32_e32 v143, v143
	v_fma_f32 v140, v6, v140, v6
	v_mul_f32_e32 v142, v14, v142
	v_fma_f32 v141, v7, v141, v7
	v_mul_f32_e32 v143, v15, v143
	v_cvt_pk_bf16_f32 v152, v142, v143
	v_mul_f32_e32 v142, 0x3d372713, v16
	v_mul_f32_e32 v142, v16, v142
	v_mul_f32_e32 v143, 0x3d372713, v17
	v_fma_f32 v142, v16, v142, v16
	v_mul_f32_e32 v143, v17, v143
	v_mul_f32_e32 v142, 0x3fcc422a, v142
	v_fma_f32 v143, v17, v143, v17
	v_mul_f32_e32 v140, 0x3fcc422a, v140
	v_mul_f32_e32 v141, 0x3fcc422a, v141
	v_mul_f32_e32 v142, 0xbfb8aa3b, v142
	v_mul_f32_e32 v143, 0x3fcc422a, v143
	v_mul_f32_e32 v140, 0xbfb8aa3b, v140
	v_mul_f32_e32 v141, 0xbfb8aa3b, v141
	v_exp_f32_e32 v142, v142
	v_mul_f32_e32 v143, 0xbfb8aa3b, v143
	v_exp_f32_e32 v140, v140
	v_exp_f32_e32 v141, v141
	v_exp_f32_e32 v143, v143
	v_add_f32_e32 v142, 1.0, v142
	v_add_f32_e32 v140, 1.0, v140
	v_add_f32_e32 v141, 1.0, v141
	v_rcp_f32_e32 v142, v142
	v_add_f32_e32 v143, 1.0, v143
	v_rcp_f32_e32 v140, v140
	v_rcp_f32_e32 v141, v141
	v_rcp_f32_e32 v143, v143
	v_mul_f32_e32 v142, v16, v142
	v_mul_f32_e32 v140, v6, v140
	v_mul_f32_e32 v141, v7, v141
	v_mul_f32_e32 v143, v17, v143
	v_cvt_pk_bf16_f32 v153, v142, v143
	global_store_dwordx4 v[154:155], v[150:153], off nt
	v_cvt_pk_bf16_f32 v140, v140, v141
	v_mul_f32_e32 v141, 0x3d372713, v8
	v_mul_f32_e32 v142, 0x3d372713, v9
	v_mul_f32_e32 v141, v8, v141
	v_mul_f32_e32 v142, v9, v142
	v_fma_f32 v141, v8, v141, v8
	v_fma_f32 v142, v9, v142, v9
	v_mul_f32_e32 v141, 0x3fcc422a, v141
	v_mul_f32_e32 v142, 0x3fcc422a, v142
	v_mul_f32_e32 v141, 0xbfb8aa3b, v141
	v_mul_f32_e32 v142, 0xbfb8aa3b, v142
	v_exp_f32_e32 v141, v141
	v_exp_f32_e32 v142, v142
	v_mul_f32_e32 v143, 0x3d372713, v3
	v_mul_f32_e32 v143, v3, v143
	v_add_f32_e32 v141, 1.0, v141
	v_add_f32_e32 v142, 1.0, v142
	v_rcp_f32_e32 v141, v141
	v_rcp_f32_e32 v142, v142
	v_fma_f32 v143, v3, v143, v3
	v_mul_f32_e32 v143, 0x3fcc422a, v143
	v_mul_f32_e32 v141, v8, v141
	v_mul_f32_e32 v142, v9, v142
	v_cvt_pk_bf16_f32 v141, v141, v142
	v_mul_f32_e32 v142, 0x3d372713, v2
	v_mul_f32_e32 v142, v2, v142
	v_fma_f32 v142, v2, v142, v2
	v_mul_f32_e32 v142, 0x3fcc422a, v142
	v_mul_f32_e32 v142, 0xbfb8aa3b, v142
	v_mul_f32_e32 v143, 0xbfb8aa3b, v143
	v_exp_f32_e32 v142, v142
	v_exp_f32_e32 v143, v143
	v_mul_f32_e32 v150, 0x3d372713, v5
	v_mul_f32_e32 v150, v5, v150
	v_add_f32_e32 v142, 1.0, v142
	v_add_f32_e32 v143, 1.0, v143
	v_rcp_f32_e32 v142, v142
	v_rcp_f32_e32 v143, v143
	v_fma_f32 v150, v5, v150, v5
	v_mul_f32_e32 v150, 0x3fcc422a, v150
	v_mul_f32_e32 v142, v2, v142
	v_mul_f32_e32 v143, v3, v143
	v_cvt_pk_bf16_f32 v142, v142, v143
	v_mul_f32_e32 v143, 0x3d372713, v4
	v_mul_f32_e32 v143, v4, v143
	v_fma_f32 v143, v4, v143, v4
	v_mul_f32_e32 v143, 0x3fcc422a, v143
	v_mul_f32_e32 v143, 0xbfb8aa3b, v143
	v_exp_f32_e32 v143, v143
	v_mul_f32_e32 v150, 0xbfb8aa3b, v150
	v_exp_f32_e32 v150, v150
	v_add_f32_e32 v143, 1.0, v143
	v_rcp_f32_e32 v143, v143
	v_add_f32_e32 v150, 1.0, v150
	v_rcp_f32_e32 v150, v150
	v_mul_f32_e32 v143, v4, v143
	v_mul_f32_e32 v150, v5, v150
	v_cvt_pk_bf16_f32 v143, v143, v150
	global_store_dwordx4 v[154:155], v[140:143], off offset:256 nt

.LBB0_157:
	s_cmp_gt_i32 s79, 1
	s_cbranch_scc0 .LBB0_161
	s_cmp_eq_u32 s79, 2
	s_mov_b64 s[52:53], -1
	s_cbranch_scc0 .LBB0_160
	v_mul_f32_e32 v142, 0xbfb8aa3b, v126
	v_exp_f32_e32 v142, v142
	v_mul_f32_e32 v143, 0xbfb8aa3b, v127
	v_exp_f32_e32 v143, v143
	v_mul_f32_e32 v154, 0xbfb8aa3b, v93
	v_add_f32_e32 v142, 1.0, v142
	v_rcp_f32_e32 v142, v142
	v_add_f32_e32 v143, 1.0, v143
	v_rcp_f32_e32 v143, v143
	v_exp_f32_e32 v154, v154
	v_mul_f32_e32 v142, v126, v142
	s_mov_b32 s6, 0x3a8000
	v_mul_f32_e32 v143, v127, v143
	v_cvt_pk_bf16_f32 v150, v142, v143
	v_mul_f32_e32 v142, 0xbfb8aa3b, v128
	v_exp_f32_e32 v142, v142
	v_mul_f32_e32 v143, 0xbfb8aa3b, v129
	v_exp_f32_e32 v143, v143
	v_add_f32_e32 v154, 1.0, v154
	v_add_f32_e32 v142, 1.0, v142
	v_rcp_f32_e32 v142, v142
	v_add_f32_e32 v143, 1.0, v143
	v_rcp_f32_e32 v143, v143
	v_rcp_f32_e32 v154, v154
	v_mul_f32_e32 v142, v128, v142
	s_mov_b64 s[52:53], 0
	v_mul_f32_e32 v143, v129, v143
	v_cvt_pk_bf16_f32 v151, v142, v143
	v_mul_f32_e32 v142, 0xbfb8aa3b, v122
	v_exp_f32_e32 v142, v142
	v_mul_f32_e32 v143, 0xbfb8aa3b, v123
	v_exp_f32_e32 v143, v143
	v_mul_f32_e32 v154, v93, v154
	v_add_f32_e32 v142, 1.0, v142
	v_rcp_f32_e32 v142, v142
	v_add_f32_e32 v143, 1.0, v143
	v_rcp_f32_e32 v143, v143
	v_mul_f32_e32 v142, v122, v142
	v_mul_f32_e32 v143, v123, v143
	v_cvt_pk_bf16_f32 v152, v142, v143
	v_mul_f32_e32 v142, 0xbfb8aa3b, v124
	v_exp_f32_e32 v142, v142
	v_mul_f32_e32 v143, 0xbfb8aa3b, v125
	v_exp_f32_e32 v143, v143
	v_add_f32_e32 v142, 1.0, v142
	v_rcp_f32_e32 v142, v142
	v_add_f32_e32 v143, 1.0, v143
	v_rcp_f32_e32 v143, v143
	v_mul_f32_e32 v142, v124, v142
	v_mul_f32_e32 v143, v125, v143
	v_cvt_pk_bf16_f32 v153, v142, v143
	v_mul_f32_e32 v142, 0xbfb8aa3b, v114
	v_exp_f32_e32 v142, v142
	v_mul_f32_e32 v143, 0xbfb8aa3b, v115
	v_exp_f32_e32 v143, v143
	global_store_dwordx4 v[140:141], v[150:153], off nt
	v_add_f32_e32 v142, 1.0, v142
	v_rcp_f32_e32 v142, v142
	v_add_f32_e32 v143, 1.0, v143
	v_rcp_f32_e32 v143, v143
	v_mul_f32_e32 v142, v114, v142
	v_mul_f32_e32 v143, v115, v143
	v_cvt_pk_bf16_f32 v150, v142, v143
	v_mul_f32_e32 v142, 0xbfb8aa3b, v116
	v_exp_f32_e32 v142, v142
	v_mul_f32_e32 v143, 0xbfb8aa3b, v117
	v_exp_f32_e32 v143, v143
	v_add_f32_e32 v142, 1.0, v142
	v_rcp_f32_e32 v142, v142
	v_add_f32_e32 v143, 1.0, v143
	v_rcp_f32_e32 v143, v143
	v_mul_f32_e32 v142, v116, v142
	v_mul_f32_e32 v143, v117, v143
	v_cvt_pk_bf16_f32 v151, v142, v143
	v_mul_f32_e32 v142, 0xbfb8aa3b, v106
	v_exp_f32_e32 v142, v142
	v_mul_f32_e32 v143, 0xbfb8aa3b, v107
	v_exp_f32_e32 v143, v143
	v_add_f32_e32 v142, 1.0, v142
	v_rcp_f32_e32 v142, v142
	v_add_f32_e32 v143, 1.0, v143
	v_rcp_f32_e32 v143, v143
	v_mul_f32_e32 v142, v106, v142
	v_mul_f32_e32 v143, v107, v143
	v_cvt_pk_bf16_f32 v152, v142, v143
	v_mul_f32_e32 v142, 0xbfb8aa3b, v108
	v_exp_f32_e32 v142, v142
	v_mul_f32_e32 v143, 0xbfb8aa3b, v109
	v_exp_f32_e32 v143, v143
	v_add_f32_e32 v142, 1.0, v142
	v_rcp_f32_e32 v142, v142
	v_add_f32_e32 v143, 1.0, v143
	v_rcp_f32_e32 v143, v143
	v_mul_f32_e32 v142, v108, v142
	v_mul_f32_e32 v143, v109, v143
	v_cvt_pk_bf16_f32 v153, v142, v143
	v_mul_f32_e32 v142, 0xbfb8aa3b, v118
	v_exp_f32_e32 v142, v142
	v_mul_f32_e32 v143, 0xbfb8aa3b, v119
	v_exp_f32_e32 v143, v143
	global_store_dwordx4 v[140:141], v[150:153], off offset:256 nt
	v_add_f32_e32 v142, 1.0, v142
	v_rcp_f32_e32 v142, v142
	v_add_f32_e32 v143, 1.0, v143
	v_rcp_f32_e32 v143, v143
	v_mul_f32_e32 v142, v118, v142
	v_mul_f32_e32 v143, v119, v143
	v_cvt_pk_bf16_f32 v150, v142, v143
	v_mul_f32_e32 v142, 0xbfb8aa3b, v120
	v_exp_f32_e32 v142, v142
	v_mul_f32_e32 v143, 0xbfb8aa3b, v121
	v_exp_f32_e32 v143, v143
	v_add_f32_e32 v142, 1.0, v142
	v_rcp_f32_e32 v142, v142
	v_add_f32_e32 v143, 1.0, v143
	v_rcp_f32_e32 v143, v143
	v_mul_f32_e32 v142, v120, v142
	v_mul_f32_e32 v143, v121, v143
	v_cvt_pk_bf16_f32 v151, v142, v143
	v_mul_f32_e32 v142, 0xbfb8aa3b, v110
	v_exp_f32_e32 v142, v142
	v_mul_f32_e32 v143, 0xbfb8aa3b, v111
	v_exp_f32_e32 v143, v143
	v_add_f32_e32 v142, 1.0, v142
	v_rcp_f32_e32 v142, v142
	v_add_f32_e32 v143, 1.0, v143
	v_rcp_f32_e32 v143, v143
	v_mul_f32_e32 v142, v110, v142
	v_mul_f32_e32 v143, v111, v143
	v_cvt_pk_bf16_f32 v152, v142, v143
	v_mul_f32_e32 v142, 0xbfb8aa3b, v112
	v_exp_f32_e32 v142, v142
	v_mul_f32_e32 v143, 0xbfb8aa3b, v113
	v_exp_f32_e32 v143, v143
	v_add_f32_e32 v142, 1.0, v142
	v_rcp_f32_e32 v142, v142
	v_add_f32_e32 v143, 1.0, v143
	v_rcp_f32_e32 v143, v143
	v_mul_f32_e32 v142, v112, v142
	v_mul_f32_e32 v143, v113, v143
	v_cvt_pk_bf16_f32 v153, v142, v143
	v_add_co_u32_e32 v142, vcc, s24, v140
	s_nop 1
	v_addc_co_u32_e32 v143, vcc, 0, v141, vcc
	global_store_dwordx4 v[142:143], v[150:153], off nt
	s_nop 1
	v_mul_f32_e32 v150, 0xbfb8aa3b, v98
	v_mul_f32_e32 v151, 0xbfb8aa3b, v99
	v_exp_f32_e32 v150, v150
	v_exp_f32_e32 v151, v151
	v_mul_f32_e32 v152, 0xbfb8aa3b, v101
	v_exp_f32_e32 v152, v152
	v_add_f32_e32 v150, 1.0, v150
	v_add_f32_e32 v151, 1.0, v151
	v_rcp_f32_e32 v150, v150
	v_rcp_f32_e32 v151, v151
	v_add_f32_e32 v152, 1.0, v152
	v_rcp_f32_e32 v152, v152
	v_mul_f32_e32 v150, v98, v150
	v_mul_f32_e32 v151, v99, v151
	v_cvt_pk_bf16_f32 v150, v150, v151
	v_mul_f32_e32 v151, 0xbfb8aa3b, v100
	v_exp_f32_e32 v151, v151
	v_mul_f32_e32 v152, v101, v152
	v_mul_f32_e32 v153, 0xbfb8aa3b, v91
	v_exp_f32_e32 v153, v153
	v_add_f32_e32 v151, 1.0, v151
	v_rcp_f32_e32 v151, v151
	v_add_f32_e32 v153, 1.0, v153
	v_rcp_f32_e32 v153, v153
	v_mul_f32_e32 v151, v100, v151
	v_cvt_pk_bf16_f32 v151, v151, v152
	v_mul_f32_e32 v152, 0xbfb8aa3b, v90
	v_exp_f32_e32 v152, v152
	v_mul_f32_e32 v153, v91, v153
	v_add_f32_e32 v152, 1.0, v152
	v_rcp_f32_e32 v152, v152
	s_nop 0
	v_mul_f32_e32 v152, v90, v152
	v_cvt_pk_bf16_f32 v152, v152, v153
	v_mul_f32_e32 v153, 0xbfb8aa3b, v92
	v_exp_f32_e32 v153, v153
	s_nop 0
	v_add_f32_e32 v153, 1.0, v153
	v_rcp_f32_e32 v153, v153
	s_nop 0
	v_mul_f32_e32 v153, v92, v153
	v_cvt_pk_bf16_f32 v153, v153, v154
	global_store_dwordx4 v[142:143], v[150:153], off offset:256 nt
	v_mul_f32_e32 v142, 0xbfb8aa3b, v102
	v_exp_f32_e32 v142, v142
	v_mul_f32_e32 v143, 0xbfb8aa3b, v103
	v_exp_f32_e32 v143, v143
	v_mul_f32_e32 v154, 0xbfb8aa3b, v77
	v_add_f32_e32 v142, 1.0, v142
	v_rcp_f32_e32 v142, v142
	v_add_f32_e32 v143, 1.0, v143
	v_rcp_f32_e32 v143, v143
	v_exp_f32_e32 v154, v154
	v_mul_f32_e32 v142, v102, v142
	v_mul_f32_e32 v143, v103, v143
	v_cvt_pk_bf16_f32 v150, v142, v143
	v_mul_f32_e32 v142, 0xbfb8aa3b, v104
	v_exp_f32_e32 v142, v142
	v_mul_f32_e32 v143, 0xbfb8aa3b, v105
	v_exp_f32_e32 v143, v143
	v_add_f32_e32 v154, 1.0, v154
	v_add_f32_e32 v142, 1.0, v142
	v_rcp_f32_e32 v142, v142
	v_add_f32_e32 v143, 1.0, v143
	v_rcp_f32_e32 v143, v143
	v_rcp_f32_e32 v154, v154
	v_mul_f32_e32 v142, v104, v142
	v_mul_f32_e32 v143, v105, v143
	v_cvt_pk_bf16_f32 v151, v142, v143
	v_mul_f32_e32 v142, 0xbfb8aa3b, v94
	v_exp_f32_e32 v142, v142
	v_mul_f32_e32 v143, 0xbfb8aa3b, v95
	v_exp_f32_e32 v143, v143
	v_mul_f32_e32 v154, v77, v154
	v_add_f32_e32 v142, 1.0, v142
	v_rcp_f32_e32 v142, v142
	v_add_f32_e32 v143, 1.0, v143
	v_rcp_f32_e32 v143, v143
	v_mul_f32_e32 v142, v94, v142
	v_mul_f32_e32 v143, v95, v143
	v_cvt_pk_bf16_f32 v152, v142, v143
	v_mul_f32_e32 v142, 0xbfb8aa3b, v96
	v_exp_f32_e32 v142, v142
	v_mul_f32_e32 v143, 0xbfb8aa3b, v97
	v_exp_f32_e32 v143, v143
	v_add_f32_e32 v142, 1.0, v142
	v_rcp_f32_e32 v142, v142
	v_add_f32_e32 v143, 1.0, v143
	v_rcp_f32_e32 v143, v143
	v_mul_f32_e32 v142, v96, v142
	v_mul_f32_e32 v143, v97, v143
	v_cvt_pk_bf16_f32 v153, v142, v143
	v_add_co_u32_e32 v142, vcc, s25, v140
	s_nop 1
	v_addc_co_u32_e32 v143, vcc, 0, v141, vcc
	global_store_dwordx4 v[142:143], v[150:153], off nt
	s_nop 1
	v_mul_f32_e32 v150, 0xbfb8aa3b, v82
	v_mul_f32_e32 v151, 0xbfb8aa3b, v83
	v_exp_f32_e32 v150, v150
	v_exp_f32_e32 v151, v151
	v_mul_f32_e32 v152, 0xbfb8aa3b, v85
	v_exp_f32_e32 v152, v152
	v_add_f32_e32 v150, 1.0, v150
	v_add_f32_e32 v151, 1.0, v151
	v_rcp_f32_e32 v150, v150
	v_rcp_f32_e32 v151, v151
	v_add_f32_e32 v152, 1.0, v152
	v_rcp_f32_e32 v152, v152
	v_mul_f32_e32 v150, v82, v150
	v_mul_f32_e32 v151, v83, v151
	v_cvt_pk_bf16_f32 v150, v150, v151
	v_mul_f32_e32 v151, 0xbfb8aa3b, v84
	v_exp_f32_e32 v151, v151
	v_mul_f32_e32 v152, v85, v152
	v_mul_f32_e32 v153, 0xbfb8aa3b, v75
	v_exp_f32_e32 v153, v153
	v_add_f32_e32 v151, 1.0, v151
	v_rcp_f32_e32 v151, v151
	v_add_f32_e32 v153, 1.0, v153
	v_rcp_f32_e32 v153, v153
	v_mul_f32_e32 v151, v84, v151
	v_cvt_pk_bf16_f32 v151, v151, v152
	v_mul_f32_e32 v152, 0xbfb8aa3b, v74
	v_exp_f32_e32 v152, v152
	v_mul_f32_e32 v153, v75, v153
	v_add_f32_e32 v152, 1.0, v152
	v_rcp_f32_e32 v152, v152
	s_nop 0
	v_mul_f32_e32 v152, v74, v152
	v_cvt_pk_bf16_f32 v152, v152, v153
	v_mul_f32_e32 v153, 0xbfb8aa3b, v76
	v_exp_f32_e32 v153, v153
	s_nop 0
	v_add_f32_e32 v153, 1.0, v153
	v_rcp_f32_e32 v153, v153
	s_nop 0
	v_mul_f32_e32 v153, v76, v153
	v_cvt_pk_bf16_f32 v153, v153, v154
	global_store_dwordx4 v[142:143], v[150:153], off offset:256 nt
	v_mul_f32_e32 v142, 0xbfb8aa3b, v86
	v_exp_f32_e32 v142, v142
	v_mul_f32_e32 v143, 0xbfb8aa3b, v87
	v_exp_f32_e32 v143, v143
	v_mul_f32_e32 v154, 0xbfb8aa3b, v69
	v_add_f32_e32 v142, 1.0, v142
	v_rcp_f32_e32 v142, v142
	v_add_f32_e32 v143, 1.0, v143
	v_rcp_f32_e32 v143, v143
	v_exp_f32_e32 v154, v154
	v_mul_f32_e32 v142, v86, v142
	v_mul_f32_e32 v143, v87, v143
	v_cvt_pk_bf16_f32 v150, v142, v143
	v_mul_f32_e32 v142, 0xbfb8aa3b, v88
	v_exp_f32_e32 v142, v142
	v_mul_f32_e32 v143, 0xbfb8aa3b, v89
	v_exp_f32_e32 v143, v143
	v_add_f32_e32 v154, 1.0, v154
	v_add_f32_e32 v142, 1.0, v142
	v_rcp_f32_e32 v142, v142
	v_add_f32_e32 v143, 1.0, v143
	v_rcp_f32_e32 v143, v143
	v_rcp_f32_e32 v154, v154
	v_mul_f32_e32 v142, v88, v142
	v_mul_f32_e32 v143, v89, v143
	v_cvt_pk_bf16_f32 v151, v142, v143
	v_mul_f32_e32 v142, 0xbfb8aa3b, v78
	v_exp_f32_e32 v142, v142
	v_mul_f32_e32 v143, 0xbfb8aa3b, v79
	v_exp_f32_e32 v143, v143
	v_mul_f32_e32 v154, v69, v154
	v_add_f32_e32 v142, 1.0, v142
	v_rcp_f32_e32 v142, v142
	v_add_f32_e32 v143, 1.0, v143
	v_rcp_f32_e32 v143, v143
	v_mul_f32_e32 v142, v78, v142
	v_mul_f32_e32 v143, v79, v143
	v_cvt_pk_bf16_f32 v152, v142, v143
	v_mul_f32_e32 v142, 0xbfb8aa3b, v80
	v_exp_f32_e32 v142, v142
	v_mul_f32_e32 v143, 0xbfb8aa3b, v81
	v_exp_f32_e32 v143, v143
	v_add_f32_e32 v142, 1.0, v142
	v_rcp_f32_e32 v142, v142
	v_add_f32_e32 v143, 1.0, v143
	v_rcp_f32_e32 v143, v143
	v_mul_f32_e32 v142, v80, v142
	v_mul_f32_e32 v143, v81, v143
	v_cvt_pk_bf16_f32 v153, v142, v143
	v_add_co_u32_e32 v142, vcc, s27, v140
	s_nop 1
	v_addc_co_u32_e32 v143, vcc, 0, v141, vcc
	global_store_dwordx4 v[142:143], v[150:153], off nt
	s_nop 1
	v_mul_f32_e32 v150, 0xbfb8aa3b, v70
	v_mul_f32_e32 v151, 0xbfb8aa3b, v71
	v_exp_f32_e32 v150, v150
	v_exp_f32_e32 v151, v151
	v_mul_f32_e32 v152, 0xbfb8aa3b, v73
	v_exp_f32_e32 v152, v152
	v_add_f32_e32 v150, 1.0, v150
	v_add_f32_e32 v151, 1.0, v151
	v_rcp_f32_e32 v150, v150
	v_rcp_f32_e32 v151, v151
	v_add_f32_e32 v152, 1.0, v152
	v_rcp_f32_e32 v152, v152
	v_mul_f32_e32 v150, v70, v150
	v_mul_f32_e32 v151, v71, v151
	v_cvt_pk_bf16_f32 v150, v150, v151
	v_mul_f32_e32 v151, 0xbfb8aa3b, v72
	v_exp_f32_e32 v151, v151
	v_mul_f32_e32 v152, v73, v152
	v_mul_f32_e32 v153, 0xbfb8aa3b, v67
	v_exp_f32_e32 v153, v153
	v_add_f32_e32 v151, 1.0, v151
	v_rcp_f32_e32 v151, v151
	v_add_f32_e32 v153, 1.0, v153
	v_rcp_f32_e32 v153, v153
	v_mul_f32_e32 v151, v72, v151
	v_cvt_pk_bf16_f32 v151, v151, v152
	v_mul_f32_e32 v152, 0xbfb8aa3b, v66
	v_exp_f32_e32 v152, v152
	v_mul_f32_e32 v153, v67, v153
	v_add_f32_e32 v152, 1.0, v152
	v_rcp_f32_e32 v152, v152
	s_nop 0
	v_mul_f32_e32 v152, v66, v152
	v_cvt_pk_bf16_f32 v152, v152, v153
	v_mul_f32_e32 v153, 0xbfb8aa3b, v68
	v_exp_f32_e32 v153, v153
	s_nop 0
	v_add_f32_e32 v153, 1.0, v153
	v_rcp_f32_e32 v153, v153
	s_nop 0
	v_mul_f32_e32 v153, v68, v153
	v_cvt_pk_bf16_f32 v153, v153, v154
	global_store_dwordx4 v[142:143], v[150:153], off offset:256 nt
	v_mul_f32_e32 v142, 0xbfb8aa3b, v62
	v_exp_f32_e32 v142, v142
	v_mul_f32_e32 v143, 0xbfb8aa3b, v63
	v_exp_f32_e32 v143, v143
	v_mul_f32_e32 v154, 0xbfb8aa3b, v45
	v_add_f32_e32 v142, 1.0, v142
	v_rcp_f32_e32 v142, v142
	v_add_f32_e32 v143, 1.0, v143
	v_rcp_f32_e32 v143, v143
	v_exp_f32_e32 v154, v154
	v_mul_f32_e32 v142, v62, v142
	v_mul_f32_e32 v143, v63, v143
	v_cvt_pk_bf16_f32 v150, v142, v143
	v_mul_f32_e32 v142, 0xbfb8aa3b, v64
	v_exp_f32_e32 v142, v142
	v_mul_f32_e32 v143, 0xbfb8aa3b, v65
	v_exp_f32_e32 v143, v143
	v_add_f32_e32 v154, 1.0, v154
	v_add_f32_e32 v142, 1.0, v142
	v_rcp_f32_e32 v142, v142
	v_add_f32_e32 v143, 1.0, v143
	v_rcp_f32_e32 v143, v143
	v_rcp_f32_e32 v154, v154
	v_mul_f32_e32 v142, v64, v142
	v_mul_f32_e32 v143, v65, v143
	v_cvt_pk_bf16_f32 v151, v142, v143
	v_mul_f32_e32 v142, 0xbfb8aa3b, v58
	v_exp_f32_e32 v142, v142
	v_mul_f32_e32 v143, 0xbfb8aa3b, v59
	v_exp_f32_e32 v143, v143
	v_mul_f32_e32 v154, v45, v154
	v_add_f32_e32 v142, 1.0, v142
	v_rcp_f32_e32 v142, v142
	v_add_f32_e32 v143, 1.0, v143
	v_rcp_f32_e32 v143, v143
	v_mul_f32_e32 v142, v58, v142
	v_mul_f32_e32 v143, v59, v143
	v_cvt_pk_bf16_f32 v152, v142, v143
	v_mul_f32_e32 v142, 0xbfb8aa3b, v60
	v_exp_f32_e32 v142, v142
	v_mul_f32_e32 v143, 0xbfb8aa3b, v61
	v_exp_f32_e32 v143, v143
	v_add_f32_e32 v142, 1.0, v142
	v_rcp_f32_e32 v142, v142
	v_add_f32_e32 v143, 1.0, v143
	v_rcp_f32_e32 v143, v143
	v_mul_f32_e32 v142, v60, v142
	v_mul_f32_e32 v143, v61, v143
	v_cvt_pk_bf16_f32 v153, v142, v143
	v_add_co_u32_e32 v142, vcc, s3, v140
	s_nop 1
	v_addc_co_u32_e32 v143, vcc, 0, v141, vcc
	global_store_dwordx4 v[142:143], v[150:153], off nt
	s_nop 1
	v_mul_f32_e32 v150, 0xbfb8aa3b, v50
	v_mul_f32_e32 v151, 0xbfb8aa3b, v51
	v_exp_f32_e32 v150, v150
	v_exp_f32_e32 v151, v151
	v_mul_f32_e32 v152, 0xbfb8aa3b, v53
	v_exp_f32_e32 v152, v152
	v_add_f32_e32 v150, 1.0, v150
	v_add_f32_e32 v151, 1.0, v151
	v_rcp_f32_e32 v150, v150
	v_rcp_f32_e32 v151, v151
	v_add_f32_e32 v152, 1.0, v152
	v_rcp_f32_e32 v152, v152
	v_mul_f32_e32 v150, v50, v150
	v_mul_f32_e32 v151, v51, v151
	v_cvt_pk_bf16_f32 v150, v150, v151
	v_mul_f32_e32 v151, 0xbfb8aa3b, v52
	v_exp_f32_e32 v151, v151
	v_mul_f32_e32 v152, v53, v152
	v_mul_f32_e32 v153, 0xbfb8aa3b, v43
	v_exp_f32_e32 v153, v153
	v_add_f32_e32 v151, 1.0, v151
	v_rcp_f32_e32 v151, v151
	v_add_f32_e32 v153, 1.0, v153
	v_rcp_f32_e32 v153, v153
	v_mul_f32_e32 v151, v52, v151
	v_cvt_pk_bf16_f32 v151, v151, v152
	v_mul_f32_e32 v152, 0xbfb8aa3b, v42
	v_exp_f32_e32 v152, v152
	v_mul_f32_e32 v153, v43, v153
	v_add_f32_e32 v152, 1.0, v152
	v_rcp_f32_e32 v152, v152
	s_nop 0
	v_mul_f32_e32 v152, v42, v152
	v_cvt_pk_bf16_f32 v152, v152, v153
	v_mul_f32_e32 v153, 0xbfb8aa3b, v44
	v_exp_f32_e32 v153, v153
	s_nop 0
	v_add_f32_e32 v153, 1.0, v153
	v_rcp_f32_e32 v153, v153
	s_nop 0
	v_mul_f32_e32 v153, v44, v153
	v_cvt_pk_bf16_f32 v153, v153, v154
	global_store_dwordx4 v[142:143], v[150:153], off offset:256 nt
	v_mul_f32_e32 v142, 0xbfb8aa3b, v54
	v_exp_f32_e32 v142, v142
	v_mul_f32_e32 v143, 0xbfb8aa3b, v55
	v_exp_f32_e32 v143, v143
	v_mul_f32_e32 v154, 0xbfb8aa3b, v29
	v_add_f32_e32 v142, 1.0, v142
	v_rcp_f32_e32 v142, v142
	v_add_f32_e32 v143, 1.0, v143
	v_rcp_f32_e32 v143, v143
	v_exp_f32_e32 v154, v154
	v_mul_f32_e32 v142, v54, v142
	v_mul_f32_e32 v143, v55, v143
	v_cvt_pk_bf16_f32 v150, v142, v143
	v_mul_f32_e32 v142, 0xbfb8aa3b, v56
	v_exp_f32_e32 v142, v142
	v_mul_f32_e32 v143, 0xbfb8aa3b, v57
	v_exp_f32_e32 v143, v143
	v_add_f32_e32 v154, 1.0, v154
	v_add_f32_e32 v142, 1.0, v142
	v_rcp_f32_e32 v142, v142
	v_add_f32_e32 v143, 1.0, v143
	v_rcp_f32_e32 v143, v143
	v_rcp_f32_e32 v154, v154
	v_mul_f32_e32 v142, v56, v142
	v_mul_f32_e32 v143, v57, v143
	v_cvt_pk_bf16_f32 v151, v142, v143
	v_mul_f32_e32 v142, 0xbfb8aa3b, v46
	v_exp_f32_e32 v142, v142
	v_mul_f32_e32 v143, 0xbfb8aa3b, v47
	v_exp_f32_e32 v143, v143
	v_mul_f32_e32 v154, v29, v154
	v_add_f32_e32 v142, 1.0, v142
	v_rcp_f32_e32 v142, v142
	v_add_f32_e32 v143, 1.0, v143
	v_rcp_f32_e32 v143, v143
	v_mul_f32_e32 v142, v46, v142
	v_mul_f32_e32 v143, v47, v143
	v_cvt_pk_bf16_f32 v152, v142, v143
	v_mul_f32_e32 v142, 0xbfb8aa3b, v48
	v_exp_f32_e32 v142, v142
	v_mul_f32_e32 v143, 0xbfb8aa3b, v49
	v_exp_f32_e32 v143, v143
	v_add_f32_e32 v142, 1.0, v142
	v_rcp_f32_e32 v142, v142
	v_add_f32_e32 v143, 1.0, v143
	v_rcp_f32_e32 v143, v143
	v_mul_f32_e32 v142, v48, v142
	v_mul_f32_e32 v143, v49, v143
	v_cvt_pk_bf16_f32 v153, v142, v143
	v_add_co_u32_e32 v142, vcc, s6, v140
	s_mov_b32 s6, 0x410000
	s_nop 0
	v_addc_co_u32_e32 v143, vcc, 0, v141, vcc
	global_store_dwordx4 v[142:143], v[150:153], off nt
	s_nop 1
	v_mul_f32_e32 v150, 0xbfb8aa3b, v34
	v_mul_f32_e32 v151, 0xbfb8aa3b, v35
	v_exp_f32_e32 v150, v150
	v_exp_f32_e32 v151, v151
	v_mul_f32_e32 v152, 0xbfb8aa3b, v37
	v_exp_f32_e32 v152, v152
	v_add_f32_e32 v150, 1.0, v150
	v_add_f32_e32 v151, 1.0, v151
	v_rcp_f32_e32 v150, v150
	v_rcp_f32_e32 v151, v151
	v_add_f32_e32 v152, 1.0, v152
	v_rcp_f32_e32 v152, v152
	v_mul_f32_e32 v150, v34, v150
	v_mul_f32_e32 v151, v35, v151
	v_cvt_pk_bf16_f32 v150, v150, v151
	v_mul_f32_e32 v151, 0xbfb8aa3b, v36
	v_exp_f32_e32 v151, v151
	v_mul_f32_e32 v152, v37, v152
	v_mul_f32_e32 v153, 0xbfb8aa3b, v27
	v_exp_f32_e32 v153, v153
	v_add_f32_e32 v151, 1.0, v151
	v_rcp_f32_e32 v151, v151
	v_add_f32_e32 v153, 1.0, v153
	v_rcp_f32_e32 v153, v153
	v_mul_f32_e32 v151, v36, v151
	v_cvt_pk_bf16_f32 v151, v151, v152
	v_mul_f32_e32 v152, 0xbfb8aa3b, v26
	v_exp_f32_e32 v152, v152
	v_mul_f32_e32 v153, v27, v153
	v_add_f32_e32 v152, 1.0, v152
	v_rcp_f32_e32 v152, v152
	s_nop 0
	v_mul_f32_e32 v152, v26, v152
	v_cvt_pk_bf16_f32 v152, v152, v153
	v_mul_f32_e32 v153, 0xbfb8aa3b, v28
	v_exp_f32_e32 v153, v153
	s_nop 0
	v_add_f32_e32 v153, 1.0, v153
	v_rcp_f32_e32 v153, v153
	s_nop 0
	v_mul_f32_e32 v153, v28, v153
	v_cvt_pk_bf16_f32 v153, v153, v154
	global_store_dwordx4 v[142:143], v[150:153], off offset:256 nt
	v_mul_f32_e32 v142, 0xbfb8aa3b, v38
	v_exp_f32_e32 v142, v142
	v_mul_f32_e32 v143, 0xbfb8aa3b, v39
	v_exp_f32_e32 v143, v143
	v_mul_f32_e32 v154, 0xbfb8aa3b, v13
	v_add_f32_e32 v142, 1.0, v142
	v_rcp_f32_e32 v142, v142
	v_add_f32_e32 v143, 1.0, v143
	v_rcp_f32_e32 v143, v143
	v_exp_f32_e32 v154, v154
	v_mul_f32_e32 v142, v38, v142
	v_mul_f32_e32 v143, v39, v143
	v_cvt_pk_bf16_f32 v150, v142, v143
	v_mul_f32_e32 v142, 0xbfb8aa3b, v40
	v_exp_f32_e32 v142, v142
	v_mul_f32_e32 v143, 0xbfb8aa3b, v41
	v_exp_f32_e32 v143, v143
	v_add_f32_e32 v154, 1.0, v154
	v_add_f32_e32 v142, 1.0, v142
	v_rcp_f32_e32 v142, v142
	v_add_f32_e32 v143, 1.0, v143
	v_rcp_f32_e32 v143, v143
	v_rcp_f32_e32 v154, v154
	v_mul_f32_e32 v142, v40, v142
	v_mul_f32_e32 v143, v41, v143
	v_cvt_pk_bf16_f32 v151, v142, v143
	v_mul_f32_e32 v142, 0xbfb8aa3b, v30
	v_exp_f32_e32 v142, v142
	v_mul_f32_e32 v143, 0xbfb8aa3b, v31
	v_exp_f32_e32 v143, v143
	v_mul_f32_e32 v154, v13, v154
	v_add_f32_e32 v142, 1.0, v142
	v_rcp_f32_e32 v142, v142
	v_add_f32_e32 v143, 1.0, v143
	v_rcp_f32_e32 v143, v143
	v_mul_f32_e32 v142, v30, v142
	v_mul_f32_e32 v143, v31, v143
	v_cvt_pk_bf16_f32 v152, v142, v143
	v_mul_f32_e32 v142, 0xbfb8aa3b, v32
	v_exp_f32_e32 v142, v142
	v_mul_f32_e32 v143, 0xbfb8aa3b, v33
	v_exp_f32_e32 v143, v143
	v_add_f32_e32 v142, 1.0, v142
	v_rcp_f32_e32 v142, v142
	v_add_f32_e32 v143, 1.0, v143
	v_rcp_f32_e32 v143, v143
	v_mul_f32_e32 v142, v32, v142
	v_mul_f32_e32 v143, v33, v143
	v_cvt_pk_bf16_f32 v153, v142, v143
	v_add_co_u32_e32 v142, vcc, s6, v140
	s_mov_b32 s6, 0x478000
	s_nop 0
	v_addc_co_u32_e32 v143, vcc, 0, v141, vcc
	global_store_dwordx4 v[142:143], v[150:153], off nt
	s_nop 1
	v_mul_f32_e32 v150, 0xbfb8aa3b, v18
	v_mul_f32_e32 v151, 0xbfb8aa3b, v19
	v_exp_f32_e32 v150, v150
	v_exp_f32_e32 v151, v151
	v_mul_f32_e32 v152, 0xbfb8aa3b, v21
	v_exp_f32_e32 v152, v152
	v_add_f32_e32 v150, 1.0, v150
	v_add_f32_e32 v151, 1.0, v151
	v_rcp_f32_e32 v150, v150
	v_rcp_f32_e32 v151, v151
	v_add_f32_e32 v152, 1.0, v152
	v_rcp_f32_e32 v152, v152
	v_mul_f32_e32 v150, v18, v150
	v_mul_f32_e32 v151, v19, v151
	v_cvt_pk_bf16_f32 v150, v150, v151
	v_mul_f32_e32 v151, 0xbfb8aa3b, v20
	v_exp_f32_e32 v151, v151
	v_mul_f32_e32 v152, v21, v152
	v_mul_f32_e32 v153, 0xbfb8aa3b, v11
	v_exp_f32_e32 v153, v153
	v_add_f32_e32 v151, 1.0, v151
	v_rcp_f32_e32 v151, v151
	v_add_f32_e32 v153, 1.0, v153
	v_rcp_f32_e32 v153, v153
	v_mul_f32_e32 v151, v20, v151
	v_cvt_pk_bf16_f32 v151, v151, v152
	v_mul_f32_e32 v152, 0xbfb8aa3b, v10
	v_exp_f32_e32 v152, v152
	v_mul_f32_e32 v153, v11, v153
	v_add_f32_e32 v152, 1.0, v152
	v_rcp_f32_e32 v152, v152
	s_nop 0
	v_mul_f32_e32 v152, v10, v152
	v_cvt_pk_bf16_f32 v152, v152, v153
	v_mul_f32_e32 v153, 0xbfb8aa3b, v12
	v_exp_f32_e32 v153, v153
	s_nop 0
	v_add_f32_e32 v153, 1.0, v153
	v_rcp_f32_e32 v153, v153
	s_nop 0
	v_mul_f32_e32 v153, v12, v153
	v_cvt_pk_bf16_f32 v153, v153, v154
	global_store_dwordx4 v[142:143], v[150:153], off offset:256 nt
	v_mul_f32_e32 v142, 0xbfb8aa3b, v22
	v_exp_f32_e32 v142, v142
	v_mul_f32_e32 v143, 0xbfb8aa3b, v23
	v_exp_f32_e32 v143, v143
	v_mul_f32_e32 v154, 0xbfb8aa3b, v5
	v_add_f32_e32 v142, 1.0, v142
	v_rcp_f32_e32 v142, v142
	v_add_f32_e32 v143, 1.0, v143
	v_rcp_f32_e32 v143, v143
	v_exp_f32_e32 v154, v154
	v_mul_f32_e32 v142, v22, v142
	v_mul_f32_e32 v143, v23, v143
	v_cvt_pk_bf16_f32 v150, v142, v143
	v_mul_f32_e32 v142, 0xbfb8aa3b, v24
	v_exp_f32_e32 v142, v142
	v_mul_f32_e32 v143, 0xbfb8aa3b, v25
	v_exp_f32_e32 v143, v143
	v_add_f32_e32 v154, 1.0, v154
	v_add_f32_e32 v142, 1.0, v142
	v_rcp_f32_e32 v142, v142
	v_add_f32_e32 v143, 1.0, v143
	v_rcp_f32_e32 v143, v143
	v_rcp_f32_e32 v154, v154
	v_mul_f32_e32 v142, v24, v142
	v_mul_f32_e32 v143, v25, v143
	v_cvt_pk_bf16_f32 v151, v142, v143
	v_mul_f32_e32 v142, 0xbfb8aa3b, v14
	v_exp_f32_e32 v142, v142
	v_mul_f32_e32 v143, 0xbfb8aa3b, v15
	v_exp_f32_e32 v143, v143
	v_mul_f32_e32 v154, v5, v154
	v_add_f32_e32 v142, 1.0, v142
	v_rcp_f32_e32 v142, v142
	v_add_f32_e32 v143, 1.0, v143
	v_rcp_f32_e32 v143, v143
	v_mul_f32_e32 v142, v14, v142
	v_mul_f32_e32 v143, v15, v143
	v_cvt_pk_bf16_f32 v152, v142, v143
	v_mul_f32_e32 v142, 0xbfb8aa3b, v16
	v_exp_f32_e32 v142, v142
	v_mul_f32_e32 v143, 0xbfb8aa3b, v17
	v_exp_f32_e32 v143, v143
	v_add_f32_e32 v142, 1.0, v142
	v_rcp_f32_e32 v142, v142
	v_add_f32_e32 v143, 1.0, v143
	v_rcp_f32_e32 v143, v143
	v_mul_f32_e32 v142, v16, v142
	v_mul_f32_e32 v143, v17, v143
	v_cvt_pk_bf16_f32 v153, v142, v143
	v_add_co_u32_e32 v142, vcc, s6, v140
	s_nop 1
	v_addc_co_u32_e32 v143, vcc, 0, v141, vcc
	global_store_dwordx4 v[142:143], v[150:153], off nt
	s_nop 1
	v_mul_f32_e32 v150, 0xbfb8aa3b, v6
	v_mul_f32_e32 v151, 0xbfb8aa3b, v7
	v_exp_f32_e32 v150, v150
	v_exp_f32_e32 v151, v151
	v_mul_f32_e32 v152, 0xbfb8aa3b, v9
	v_exp_f32_e32 v152, v152
	v_add_f32_e32 v150, 1.0, v150
	v_add_f32_e32 v151, 1.0, v151
	v_rcp_f32_e32 v150, v150
	v_rcp_f32_e32 v151, v151
	v_add_f32_e32 v152, 1.0, v152
	v_rcp_f32_e32 v152, v152
	v_mul_f32_e32 v150, v6, v150
	v_mul_f32_e32 v151, v7, v151
	v_cvt_pk_bf16_f32 v150, v150, v151
	v_mul_f32_e32 v151, 0xbfb8aa3b, v8
	v_exp_f32_e32 v151, v151
	v_mul_f32_e32 v152, v9, v152
	v_mul_f32_e32 v153, 0xbfb8aa3b, v3
	v_exp_f32_e32 v153, v153
	v_add_f32_e32 v151, 1.0, v151
	v_rcp_f32_e32 v151, v151
	v_add_f32_e32 v153, 1.0, v153
	v_rcp_f32_e32 v153, v153
	v_mul_f32_e32 v151, v8, v151
	v_cvt_pk_bf16_f32 v151, v151, v152
	v_mul_f32_e32 v152, 0xbfb8aa3b, v2
	v_exp_f32_e32 v152, v152
	v_mul_f32_e32 v153, v3, v153
	v_add_f32_e32 v152, 1.0, v152
	v_rcp_f32_e32 v152, v152
	s_nop 0
	v_mul_f32_e32 v152, v2, v152
	v_cvt_pk_bf16_f32 v152, v152, v153
	v_mul_f32_e32 v153, 0xbfb8aa3b, v4
	v_exp_f32_e32 v153, v153
	s_nop 0
	v_add_f32_e32 v153, 1.0, v153
	v_rcp_f32_e32 v153, v153
	s_nop 0
	v_mul_f32_e32 v153, v4, v153
	v_cvt_pk_bf16_f32 v153, v153, v154
	global_store_dwordx4 v[142:143], v[150:153], off offset:256 nt

.LBB0_161:
	s_and_b64 vcc, exec, s[6:7]
	s_cbranch_vccz .LBB0_163
	v_mul_f32_e32 v142, 0x3d372713, v126
	v_mul_f32_e32 v142, v126, v142
	v_mul_f32_e32 v143, 0x3d372713, v127
	v_fma_f32 v142, v126, v142, v126
	v_mul_f32_e32 v143, v127, v143
	v_mul_f32_e32 v142, 0x3fcc422a, v142
	v_fma_f32 v143, v127, v143, v127
	v_mul_f32_e32 v142, 0xbfb8aa3b, v142
	v_mul_f32_e32 v143, 0x3fcc422a, v143
	v_exp_f32_e32 v142, v142
	v_mul_f32_e32 v143, 0xbfb8aa3b, v143
	v_exp_f32_e32 v143, v143
	v_mul_f32_e32 v154, 0x3d372713, v93
	v_add_f32_e32 v142, 1.0, v142
	v_rcp_f32_e32 v142, v142
	v_add_f32_e32 v143, 1.0, v143
	v_rcp_f32_e32 v143, v143
	v_mul_f32_e32 v154, v93, v154
	v_mul_f32_e32 v142, v126, v142
	v_fma_f32 v154, v93, v154, v93
	v_mul_f32_e32 v143, v127, v143
	v_cvt_pk_bf16_f32 v150, v142, v143
	v_mul_f32_e32 v142, 0x3d372713, v128
	v_mul_f32_e32 v142, v128, v142
	v_mul_f32_e32 v143, 0x3d372713, v129
	v_fma_f32 v142, v128, v142, v128
	v_mul_f32_e32 v143, v129, v143
	v_mul_f32_e32 v142, 0x3fcc422a, v142
	v_fma_f32 v143, v129, v143, v129
	v_mul_f32_e32 v142, 0xbfb8aa3b, v142
	v_mul_f32_e32 v143, 0x3fcc422a, v143
	v_exp_f32_e32 v142, v142
	v_mul_f32_e32 v143, 0xbfb8aa3b, v143
	v_exp_f32_e32 v143, v143
	v_mul_f32_e32 v154, 0x3fcc422a, v154
	v_add_f32_e32 v142, 1.0, v142
	v_rcp_f32_e32 v142, v142
	v_add_f32_e32 v143, 1.0, v143
	v_rcp_f32_e32 v143, v143
	v_mul_f32_e32 v154, 0xbfb8aa3b, v154
	v_mul_f32_e32 v142, v128, v142
	v_exp_f32_e32 v154, v154
	v_mul_f32_e32 v143, v129, v143
	v_cvt_pk_bf16_f32 v151, v142, v143
	v_mul_f32_e32 v142, 0x3d372713, v122
	v_mul_f32_e32 v142, v122, v142
	v_mul_f32_e32 v143, 0x3d372713, v123
	v_fma_f32 v142, v122, v142, v122
	v_mul_f32_e32 v143, v123, v143
	v_mul_f32_e32 v142, 0x3fcc422a, v142
	v_fma_f32 v143, v123, v143, v123
	v_mul_f32_e32 v142, 0xbfb8aa3b, v142
	v_mul_f32_e32 v143, 0x3fcc422a, v143
	v_exp_f32_e32 v142, v142
	v_mul_f32_e32 v143, 0xbfb8aa3b, v143
	v_exp_f32_e32 v143, v143
	v_add_f32_e32 v154, 1.0, v154
	v_add_f32_e32 v142, 1.0, v142
	v_rcp_f32_e32 v142, v142
	v_add_f32_e32 v143, 1.0, v143
	v_rcp_f32_e32 v143, v143
	v_rcp_f32_e32 v154, v154
	v_mul_f32_e32 v142, v122, v142
	s_mov_b32 s6, 0x3a8000
	v_mul_f32_e32 v143, v123, v143
	v_cvt_pk_bf16_f32 v152, v142, v143
	v_mul_f32_e32 v142, 0x3d372713, v124
	v_mul_f32_e32 v142, v124, v142
	v_mul_f32_e32 v143, 0x3d372713, v125
	v_fma_f32 v142, v124, v142, v124
	v_mul_f32_e32 v143, v125, v143
	v_mul_f32_e32 v142, 0x3fcc422a, v142
	v_fma_f32 v143, v125, v143, v125
	v_mul_f32_e32 v142, 0xbfb8aa3b, v142
	v_mul_f32_e32 v143, 0x3fcc422a, v143
	v_exp_f32_e32 v142, v142
	v_mul_f32_e32 v143, 0xbfb8aa3b, v143
	v_exp_f32_e32 v143, v143
	v_mul_f32_e32 v154, v93, v154
	v_add_f32_e32 v142, 1.0, v142
	v_rcp_f32_e32 v142, v142
	v_add_f32_e32 v143, 1.0, v143
	v_rcp_f32_e32 v143, v143
	v_mul_f32_e32 v142, v124, v142
	v_mul_f32_e32 v143, v125, v143
	v_cvt_pk_bf16_f32 v153, v142, v143
	v_mul_f32_e32 v142, 0x3d372713, v114
	v_mul_f32_e32 v142, v114, v142
	v_mul_f32_e32 v143, 0x3d372713, v115
	v_fma_f32 v142, v114, v142, v114
	v_mul_f32_e32 v143, v115, v143
	v_mul_f32_e32 v142, 0x3fcc422a, v142
	v_fma_f32 v143, v115, v143, v115
	v_mul_f32_e32 v142, 0xbfb8aa3b, v142
	v_mul_f32_e32 v143, 0x3fcc422a, v143
	v_exp_f32_e32 v142, v142
	v_mul_f32_e32 v143, 0xbfb8aa3b, v143
	v_exp_f32_e32 v143, v143
	global_store_dwordx4 v[140:141], v[150:153], off nt
	v_add_f32_e32 v142, 1.0, v142
	v_rcp_f32_e32 v142, v142
	v_add_f32_e32 v143, 1.0, v143
	v_rcp_f32_e32 v143, v143
	v_mul_f32_e32 v142, v114, v142
	v_mul_f32_e32 v143, v115, v143
	v_cvt_pk_bf16_f32 v150, v142, v143
	v_mul_f32_e32 v142, 0x3d372713, v116
	v_mul_f32_e32 v142, v116, v142
	v_mul_f32_e32 v143, 0x3d372713, v117
	v_fma_f32 v142, v116, v142, v116
	v_mul_f32_e32 v143, v117, v143
	v_mul_f32_e32 v142, 0x3fcc422a, v142
	v_fma_f32 v143, v117, v143, v117
	v_mul_f32_e32 v142, 0xbfb8aa3b, v142
	v_mul_f32_e32 v143, 0x3fcc422a, v143
	v_exp_f32_e32 v142, v142
	v_mul_f32_e32 v143, 0xbfb8aa3b, v143
	v_exp_f32_e32 v143, v143
	v_add_f32_e32 v142, 1.0, v142
	v_rcp_f32_e32 v142, v142
	v_add_f32_e32 v143, 1.0, v143
	v_rcp_f32_e32 v143, v143
	v_mul_f32_e32 v142, v116, v142
	v_mul_f32_e32 v143, v117, v143
	v_cvt_pk_bf16_f32 v151, v142, v143
	v_mul_f32_e32 v142, 0x3d372713, v106
	v_mul_f32_e32 v142, v106, v142
	v_mul_f32_e32 v143, 0x3d372713, v107
	v_fma_f32 v142, v106, v142, v106
	v_mul_f32_e32 v143, v107, v143
	v_mul_f32_e32 v142, 0x3fcc422a, v142
	v_fma_f32 v143, v107, v143, v107
	v_mul_f32_e32 v142, 0xbfb8aa3b, v142
	v_mul_f32_e32 v143, 0x3fcc422a, v143
	v_exp_f32_e32 v142, v142
	v_mul_f32_e32 v143, 0xbfb8aa3b, v143
	v_exp_f32_e32 v143, v143
	v_add_f32_e32 v142, 1.0, v142
	v_rcp_f32_e32 v142, v142
	v_add_f32_e32 v143, 1.0, v143
	v_rcp_f32_e32 v143, v143
	v_mul_f32_e32 v142, v106, v142
	v_mul_f32_e32 v143, v107, v143
	v_cvt_pk_bf16_f32 v152, v142, v143
	v_mul_f32_e32 v142, 0x3d372713, v108
	v_mul_f32_e32 v142, v108, v142
	v_mul_f32_e32 v143, 0x3d372713, v109
	v_fma_f32 v142, v108, v142, v108
	v_mul_f32_e32 v143, v109, v143
	v_mul_f32_e32 v142, 0x3fcc422a, v142
	v_fma_f32 v143, v109, v143, v109
	v_mul_f32_e32 v142, 0xbfb8aa3b, v142
	v_mul_f32_e32 v143, 0x3fcc422a, v143
	v_exp_f32_e32 v142, v142
	v_mul_f32_e32 v143, 0xbfb8aa3b, v143
	v_exp_f32_e32 v143, v143
	v_add_f32_e32 v142, 1.0, v142
	v_rcp_f32_e32 v142, v142
	v_add_f32_e32 v143, 1.0, v143
	v_rcp_f32_e32 v143, v143
	v_mul_f32_e32 v142, v108, v142
	v_mul_f32_e32 v143, v109, v143
	v_cvt_pk_bf16_f32 v153, v142, v143
	v_mul_f32_e32 v142, 0x3d372713, v118
	v_mul_f32_e32 v142, v118, v142
	v_mul_f32_e32 v143, 0x3d372713, v119
	v_fma_f32 v142, v118, v142, v118
	v_mul_f32_e32 v143, v119, v143
	v_mul_f32_e32 v142, 0x3fcc422a, v142
	v_fma_f32 v143, v119, v143, v119
	v_mul_f32_e32 v142, 0xbfb8aa3b, v142
	v_mul_f32_e32 v143, 0x3fcc422a, v143
	v_exp_f32_e32 v142, v142
	v_mul_f32_e32 v143, 0xbfb8aa3b, v143
	v_exp_f32_e32 v143, v143
	global_store_dwordx4 v[140:141], v[150:153], off offset:256 nt
	v_add_f32_e32 v142, 1.0, v142
	v_rcp_f32_e32 v142, v142
	v_add_f32_e32 v143, 1.0, v143
	v_rcp_f32_e32 v143, v143
	v_mul_f32_e32 v142, v118, v142
	v_mul_f32_e32 v143, v119, v143
	v_cvt_pk_bf16_f32 v150, v142, v143
	v_mul_f32_e32 v142, 0x3d372713, v120
	v_mul_f32_e32 v142, v120, v142
	v_mul_f32_e32 v143, 0x3d372713, v121
	v_fma_f32 v142, v120, v142, v120
	v_mul_f32_e32 v143, v121, v143
	v_mul_f32_e32 v142, 0x3fcc422a, v142
	v_fma_f32 v143, v121, v143, v121
	v_mul_f32_e32 v142, 0xbfb8aa3b, v142
	v_mul_f32_e32 v143, 0x3fcc422a, v143
	v_exp_f32_e32 v142, v142
	v_mul_f32_e32 v143, 0xbfb8aa3b, v143
	v_exp_f32_e32 v143, v143
	v_add_f32_e32 v142, 1.0, v142
	v_rcp_f32_e32 v142, v142
	v_add_f32_e32 v143, 1.0, v143
	v_rcp_f32_e32 v143, v143
	v_mul_f32_e32 v142, v120, v142
	v_mul_f32_e32 v143, v121, v143
	v_cvt_pk_bf16_f32 v151, v142, v143
	v_mul_f32_e32 v142, 0x3d372713, v110
	v_mul_f32_e32 v142, v110, v142
	v_mul_f32_e32 v143, 0x3d372713, v111
	v_fma_f32 v142, v110, v142, v110
	v_mul_f32_e32 v143, v111, v143
	v_mul_f32_e32 v142, 0x3fcc422a, v142
	v_fma_f32 v143, v111, v143, v111
	v_mul_f32_e32 v142, 0xbfb8aa3b, v142
	v_mul_f32_e32 v143, 0x3fcc422a, v143
	v_exp_f32_e32 v142, v142
	v_mul_f32_e32 v143, 0xbfb8aa3b, v143
	v_exp_f32_e32 v143, v143
	v_add_f32_e32 v142, 1.0, v142
	v_rcp_f32_e32 v142, v142
	v_add_f32_e32 v143, 1.0, v143
	v_rcp_f32_e32 v143, v143
	v_mul_f32_e32 v142, v110, v142
	v_mul_f32_e32 v143, v111, v143
	v_cvt_pk_bf16_f32 v152, v142, v143
	v_mul_f32_e32 v142, 0x3d372713, v112
	v_mul_f32_e32 v142, v112, v142
	v_mul_f32_e32 v143, 0x3d372713, v113
	v_fma_f32 v142, v112, v142, v112
	v_mul_f32_e32 v143, v113, v143
	v_mul_f32_e32 v142, 0x3fcc422a, v142
	v_fma_f32 v143, v113, v143, v113
	v_mul_f32_e32 v142, 0xbfb8aa3b, v142
	v_mul_f32_e32 v143, 0x3fcc422a, v143
	v_exp_f32_e32 v142, v142
	v_mul_f32_e32 v143, 0xbfb8aa3b, v143
	v_exp_f32_e32 v143, v143
	v_add_f32_e32 v142, 1.0, v142
	v_rcp_f32_e32 v142, v142
	v_add_f32_e32 v143, 1.0, v143
	v_rcp_f32_e32 v143, v143
	v_mul_f32_e32 v142, v112, v142
	v_mul_f32_e32 v143, v113, v143
	v_cvt_pk_bf16_f32 v153, v142, v143
	v_add_co_u32_e32 v142, vcc, s24, v140
	s_nop 1
	v_addc_co_u32_e32 v143, vcc, 0, v141, vcc
	global_store_dwordx4 v[142:143], v[150:153], off nt
	s_nop 1
	v_mul_f32_e32 v150, 0x3d372713, v98
	v_mul_f32_e32 v151, 0x3d372713, v99
	v_mul_f32_e32 v150, v98, v150
	v_mul_f32_e32 v151, v99, v151
	v_fma_f32 v150, v98, v150, v98
	v_fma_f32 v151, v99, v151, v99
	v_mul_f32_e32 v150, 0x3fcc422a, v150
	v_mul_f32_e32 v151, 0x3fcc422a, v151
	v_mul_f32_e32 v150, 0xbfb8aa3b, v150
	v_mul_f32_e32 v151, 0xbfb8aa3b, v151
	v_exp_f32_e32 v150, v150
	v_exp_f32_e32 v151, v151
	v_mul_f32_e32 v152, 0x3d372713, v101
	v_mul_f32_e32 v152, v101, v152
	v_add_f32_e32 v150, 1.0, v150
	v_add_f32_e32 v151, 1.0, v151
	v_rcp_f32_e32 v150, v150
	v_rcp_f32_e32 v151, v151
	v_fma_f32 v152, v101, v152, v101
	v_mul_f32_e32 v152, 0x3fcc422a, v152
	v_mul_f32_e32 v150, v98, v150
	v_mul_f32_e32 v151, v99, v151
	v_cvt_pk_bf16_f32 v150, v150, v151
	v_mul_f32_e32 v151, 0x3d372713, v100
	v_mul_f32_e32 v151, v100, v151
	v_fma_f32 v151, v100, v151, v100
	v_mul_f32_e32 v151, 0x3fcc422a, v151
	v_mul_f32_e32 v151, 0xbfb8aa3b, v151
	v_mul_f32_e32 v152, 0xbfb8aa3b, v152
	v_exp_f32_e32 v151, v151
	v_exp_f32_e32 v152, v152
	v_mul_f32_e32 v153, 0x3d372713, v91
	v_mul_f32_e32 v153, v91, v153
	v_add_f32_e32 v151, 1.0, v151
	v_add_f32_e32 v152, 1.0, v152
	v_rcp_f32_e32 v151, v151
	v_rcp_f32_e32 v152, v152
	v_fma_f32 v153, v91, v153, v91
	v_mul_f32_e32 v153, 0x3fcc422a, v153
	v_mul_f32_e32 v151, v100, v151
	v_mul_f32_e32 v152, v101, v152
	v_cvt_pk_bf16_f32 v151, v151, v152
	v_mul_f32_e32 v152, 0x3d372713, v90
	v_mul_f32_e32 v152, v90, v152
	v_fma_f32 v152, v90, v152, v90
	v_mul_f32_e32 v152, 0x3fcc422a, v152
	v_mul_f32_e32 v152, 0xbfb8aa3b, v152
	v_mul_f32_e32 v153, 0xbfb8aa3b, v153
	v_exp_f32_e32 v152, v152
	v_exp_f32_e32 v153, v153
	v_add_f32_e32 v152, 1.0, v152
	v_add_f32_e32 v153, 1.0, v153
	v_rcp_f32_e32 v152, v152
	v_rcp_f32_e32 v153, v153
	v_mul_f32_e32 v152, v90, v152
	v_mul_f32_e32 v153, v91, v153
	v_cvt_pk_bf16_f32 v152, v152, v153
	v_mul_f32_e32 v153, 0x3d372713, v92
	v_mul_f32_e32 v153, v92, v153
	v_fma_f32 v153, v92, v153, v92
	v_mul_f32_e32 v153, 0x3fcc422a, v153
	v_mul_f32_e32 v153, 0xbfb8aa3b, v153
	v_exp_f32_e32 v153, v153
	s_nop 0
	v_add_f32_e32 v153, 1.0, v153
	v_rcp_f32_e32 v153, v153
	s_nop 0
	v_mul_f32_e32 v153, v92, v153
	v_cvt_pk_bf16_f32 v153, v153, v154
	global_store_dwordx4 v[142:143], v[150:153], off offset:256 nt
	v_mul_f32_e32 v142, 0x3d372713, v102
	v_mul_f32_e32 v142, v102, v142
	v_mul_f32_e32 v143, 0x3d372713, v103
	v_fma_f32 v142, v102, v142, v102
	v_mul_f32_e32 v143, v103, v143
	v_mul_f32_e32 v142, 0x3fcc422a, v142
	v_fma_f32 v143, v103, v143, v103
	v_mul_f32_e32 v142, 0xbfb8aa3b, v142
	v_mul_f32_e32 v143, 0x3fcc422a, v143
	v_exp_f32_e32 v142, v142
	v_mul_f32_e32 v143, 0xbfb8aa3b, v143
	v_exp_f32_e32 v143, v143
	v_mul_f32_e32 v154, 0x3d372713, v77
	v_add_f32_e32 v142, 1.0, v142
	v_rcp_f32_e32 v142, v142
	v_add_f32_e32 v143, 1.0, v143
	v_rcp_f32_e32 v143, v143
	v_mul_f32_e32 v154, v77, v154
	v_mul_f32_e32 v142, v102, v142
	v_fma_f32 v154, v77, v154, v77
	v_mul_f32_e32 v143, v103, v143
	v_cvt_pk_bf16_f32 v150, v142, v143
	v_mul_f32_e32 v142, 0x3d372713, v104
	v_mul_f32_e32 v142, v104, v142
	v_mul_f32_e32 v143, 0x3d372713, v105
	v_fma_f32 v142, v104, v142, v104
	v_mul_f32_e32 v143, v105, v143
	v_mul_f32_e32 v142, 0x3fcc422a, v142
	v_fma_f32 v143, v105, v143, v105
	v_mul_f32_e32 v142, 0xbfb8aa3b, v142
	v_mul_f32_e32 v143, 0x3fcc422a, v143
	v_exp_f32_e32 v142, v142
	v_mul_f32_e32 v143, 0xbfb8aa3b, v143
	v_exp_f32_e32 v143, v143
	v_mul_f32_e32 v154, 0x3fcc422a, v154
	v_add_f32_e32 v142, 1.0, v142
	v_rcp_f32_e32 v142, v142
	v_add_f32_e32 v143, 1.0, v143
	v_rcp_f32_e32 v143, v143
	v_mul_f32_e32 v154, 0xbfb8aa3b, v154
	v_mul_f32_e32 v142, v104, v142
	v_exp_f32_e32 v154, v154
	v_mul_f32_e32 v143, v105, v143
	v_cvt_pk_bf16_f32 v151, v142, v143
	v_mul_f32_e32 v142, 0x3d372713, v94
	v_mul_f32_e32 v142, v94, v142
	v_mul_f32_e32 v143, 0x3d372713, v95
	v_fma_f32 v142, v94, v142, v94
	v_mul_f32_e32 v143, v95, v143
	v_mul_f32_e32 v142, 0x3fcc422a, v142
	v_fma_f32 v143, v95, v143, v95
	v_mul_f32_e32 v142, 0xbfb8aa3b, v142
	v_mul_f32_e32 v143, 0x3fcc422a, v143
	v_exp_f32_e32 v142, v142
	v_mul_f32_e32 v143, 0xbfb8aa3b, v143
	v_exp_f32_e32 v143, v143
	v_add_f32_e32 v154, 1.0, v154
	v_add_f32_e32 v142, 1.0, v142
	v_rcp_f32_e32 v142, v142
	v_add_f32_e32 v143, 1.0, v143
	v_rcp_f32_e32 v143, v143
	v_rcp_f32_e32 v154, v154
	v_mul_f32_e32 v142, v94, v142
	v_mul_f32_e32 v143, v95, v143
	v_cvt_pk_bf16_f32 v152, v142, v143
	v_mul_f32_e32 v142, 0x3d372713, v96
	v_mul_f32_e32 v142, v96, v142
	v_mul_f32_e32 v143, 0x3d372713, v97
	v_fma_f32 v142, v96, v142, v96
	v_mul_f32_e32 v143, v97, v143
	v_mul_f32_e32 v142, 0x3fcc422a, v142
	v_fma_f32 v143, v97, v143, v97
	v_mul_f32_e32 v142, 0xbfb8aa3b, v142
	v_mul_f32_e32 v143, 0x3fcc422a, v143
	v_exp_f32_e32 v142, v142
	v_mul_f32_e32 v143, 0xbfb8aa3b, v143
	v_exp_f32_e32 v143, v143
	v_mul_f32_e32 v154, v77, v154
	v_add_f32_e32 v142, 1.0, v142
	v_rcp_f32_e32 v142, v142
	v_add_f32_e32 v143, 1.0, v143
	v_rcp_f32_e32 v143, v143
	v_mul_f32_e32 v142, v96, v142
	v_mul_f32_e32 v143, v97, v143
	v_cvt_pk_bf16_f32 v153, v142, v143
	v_add_co_u32_e32 v142, vcc, s25, v140
	s_nop 1
	v_addc_co_u32_e32 v143, vcc, 0, v141, vcc
	global_store_dwordx4 v[142:143], v[150:153], off nt
	s_nop 1
	v_mul_f32_e32 v150, 0x3d372713, v82
	v_mul_f32_e32 v151, 0x3d372713, v83
	v_mul_f32_e32 v150, v82, v150
	v_mul_f32_e32 v151, v83, v151
	v_fma_f32 v150, v82, v150, v82
	v_fma_f32 v151, v83, v151, v83
	v_mul_f32_e32 v150, 0x3fcc422a, v150
	v_mul_f32_e32 v151, 0x3fcc422a, v151
	v_mul_f32_e32 v150, 0xbfb8aa3b, v150
	v_mul_f32_e32 v151, 0xbfb8aa3b, v151
	v_exp_f32_e32 v150, v150
	v_exp_f32_e32 v151, v151
	v_mul_f32_e32 v152, 0x3d372713, v85
	v_mul_f32_e32 v152, v85, v152
	v_add_f32_e32 v150, 1.0, v150
	v_add_f32_e32 v151, 1.0, v151
	v_rcp_f32_e32 v150, v150
	v_rcp_f32_e32 v151, v151
	v_fma_f32 v152, v85, v152, v85
	v_mul_f32_e32 v152, 0x3fcc422a, v152
	v_mul_f32_e32 v150, v82, v150
	v_mul_f32_e32 v151, v83, v151
	v_cvt_pk_bf16_f32 v150, v150, v151
	v_mul_f32_e32 v151, 0x3d372713, v84
	v_mul_f32_e32 v151, v84, v151
	v_fma_f32 v151, v84, v151, v84
	v_mul_f32_e32 v151, 0x3fcc422a, v151
	v_mul_f32_e32 v151, 0xbfb8aa3b, v151
	v_mul_f32_e32 v152, 0xbfb8aa3b, v152
	v_exp_f32_e32 v151, v151
	v_exp_f32_e32 v152, v152
	v_mul_f32_e32 v153, 0x3d372713, v75
	v_mul_f32_e32 v153, v75, v153
	v_add_f32_e32 v151, 1.0, v151
	v_add_f32_e32 v152, 1.0, v152
	v_rcp_f32_e32 v151, v151
	v_rcp_f32_e32 v152, v152
	v_fma_f32 v153, v75, v153, v75
	v_mul_f32_e32 v153, 0x3fcc422a, v153
	v_mul_f32_e32 v151, v84, v151
	v_mul_f32_e32 v152, v85, v152
	v_cvt_pk_bf16_f32 v151, v151, v152
	v_mul_f32_e32 v152, 0x3d372713, v74
	v_mul_f32_e32 v152, v74, v152
	v_fma_f32 v152, v74, v152, v74
	v_mul_f32_e32 v152, 0x3fcc422a, v152
	v_mul_f32_e32 v152, 0xbfb8aa3b, v152
	v_mul_f32_e32 v153, 0xbfb8aa3b, v153
	v_exp_f32_e32 v152, v152
	v_exp_f32_e32 v153, v153
	v_add_f32_e32 v152, 1.0, v152
	v_add_f32_e32 v153, 1.0, v153
	v_rcp_f32_e32 v152, v152
	v_rcp_f32_e32 v153, v153
	v_mul_f32_e32 v152, v74, v152
	v_mul_f32_e32 v153, v75, v153
	v_cvt_pk_bf16_f32 v152, v152, v153
	v_mul_f32_e32 v153, 0x3d372713, v76
	v_mul_f32_e32 v153, v76, v153
	v_fma_f32 v153, v76, v153, v76
	v_mul_f32_e32 v153, 0x3fcc422a, v153
	v_mul_f32_e32 v153, 0xbfb8aa3b, v153
	v_exp_f32_e32 v153, v153
	s_nop 0
	v_add_f32_e32 v153, 1.0, v153
	v_rcp_f32_e32 v153, v153
	s_nop 0
	v_mul_f32_e32 v153, v76, v153
	v_cvt_pk_bf16_f32 v153, v153, v154
	global_store_dwordx4 v[142:143], v[150:153], off offset:256 nt
	v_mul_f32_e32 v142, 0x3d372713, v86
	v_mul_f32_e32 v142, v86, v142
	v_mul_f32_e32 v143, 0x3d372713, v87
	v_fma_f32 v142, v86, v142, v86
	v_mul_f32_e32 v143, v87, v143
	v_mul_f32_e32 v142, 0x3fcc422a, v142
	v_fma_f32 v143, v87, v143, v87
	v_mul_f32_e32 v142, 0xbfb8aa3b, v142
	v_mul_f32_e32 v143, 0x3fcc422a, v143
	v_exp_f32_e32 v142, v142
	v_mul_f32_e32 v143, 0xbfb8aa3b, v143
	v_exp_f32_e32 v143, v143
	v_mul_f32_e32 v154, 0x3d372713, v69
	v_add_f32_e32 v142, 1.0, v142
	v_rcp_f32_e32 v142, v142
	v_add_f32_e32 v143, 1.0, v143
	v_rcp_f32_e32 v143, v143
	v_mul_f32_e32 v154, v69, v154
	v_mul_f32_e32 v142, v86, v142
	v_fma_f32 v154, v69, v154, v69
	v_mul_f32_e32 v143, v87, v143
	v_cvt_pk_bf16_f32 v150, v142, v143
	v_mul_f32_e32 v142, 0x3d372713, v88
	v_mul_f32_e32 v142, v88, v142
	v_mul_f32_e32 v143, 0x3d372713, v89
	v_fma_f32 v142, v88, v142, v88
	v_mul_f32_e32 v143, v89, v143
	v_mul_f32_e32 v142, 0x3fcc422a, v142
	v_fma_f32 v143, v89, v143, v89
	v_mul_f32_e32 v142, 0xbfb8aa3b, v142
	v_mul_f32_e32 v143, 0x3fcc422a, v143
	v_exp_f32_e32 v142, v142
	v_mul_f32_e32 v143, 0xbfb8aa3b, v143
	v_exp_f32_e32 v143, v143
	v_mul_f32_e32 v154, 0x3fcc422a, v154
	v_add_f32_e32 v142, 1.0, v142
	v_rcp_f32_e32 v142, v142
	v_add_f32_e32 v143, 1.0, v143
	v_rcp_f32_e32 v143, v143
	v_mul_f32_e32 v154, 0xbfb8aa3b, v154
	v_mul_f32_e32 v142, v88, v142
	v_exp_f32_e32 v154, v154
	v_mul_f32_e32 v143, v89, v143
	v_cvt_pk_bf16_f32 v151, v142, v143
	v_mul_f32_e32 v142, 0x3d372713, v78
	v_mul_f32_e32 v142, v78, v142
	v_mul_f32_e32 v143, 0x3d372713, v79
	v_fma_f32 v142, v78, v142, v78
	v_mul_f32_e32 v143, v79, v143
	v_mul_f32_e32 v142, 0x3fcc422a, v142
	v_fma_f32 v143, v79, v143, v79
	v_mul_f32_e32 v142, 0xbfb8aa3b, v142
	v_mul_f32_e32 v143, 0x3fcc422a, v143
	v_exp_f32_e32 v142, v142
	v_mul_f32_e32 v143, 0xbfb8aa3b, v143
	v_exp_f32_e32 v143, v143
	v_add_f32_e32 v154, 1.0, v154
	v_add_f32_e32 v142, 1.0, v142
	v_rcp_f32_e32 v142, v142
	v_add_f32_e32 v143, 1.0, v143
	v_rcp_f32_e32 v143, v143
	v_rcp_f32_e32 v154, v154
	v_mul_f32_e32 v142, v78, v142
	v_mul_f32_e32 v143, v79, v143
	v_cvt_pk_bf16_f32 v152, v142, v143
	v_mul_f32_e32 v142, 0x3d372713, v80
	v_mul_f32_e32 v142, v80, v142
	v_mul_f32_e32 v143, 0x3d372713, v81
	v_fma_f32 v142, v80, v142, v80
	v_mul_f32_e32 v143, v81, v143
	v_mul_f32_e32 v142, 0x3fcc422a, v142
	v_fma_f32 v143, v81, v143, v81
	v_mul_f32_e32 v142, 0xbfb8aa3b, v142
	v_mul_f32_e32 v143, 0x3fcc422a, v143
	v_exp_f32_e32 v142, v142
	v_mul_f32_e32 v143, 0xbfb8aa3b, v143
	v_exp_f32_e32 v143, v143
	v_mul_f32_e32 v154, v69, v154
	v_add_f32_e32 v142, 1.0, v142
	v_rcp_f32_e32 v142, v142
	v_add_f32_e32 v143, 1.0, v143
	v_rcp_f32_e32 v143, v143
	v_mul_f32_e32 v142, v80, v142
	v_mul_f32_e32 v143, v81, v143
	v_cvt_pk_bf16_f32 v153, v142, v143
	v_add_co_u32_e32 v142, vcc, s27, v140
	s_nop 1
	v_addc_co_u32_e32 v143, vcc, 0, v141, vcc
	global_store_dwordx4 v[142:143], v[150:153], off nt
	s_nop 1
	v_mul_f32_e32 v150, 0x3d372713, v70
	v_mul_f32_e32 v151, 0x3d372713, v71
	v_mul_f32_e32 v150, v70, v150
	v_mul_f32_e32 v151, v71, v151
	v_fma_f32 v150, v70, v150, v70
	v_fma_f32 v151, v71, v151, v71
	v_mul_f32_e32 v150, 0x3fcc422a, v150
	v_mul_f32_e32 v151, 0x3fcc422a, v151
	v_mul_f32_e32 v150, 0xbfb8aa3b, v150
	v_mul_f32_e32 v151, 0xbfb8aa3b, v151
	v_exp_f32_e32 v150, v150
	v_exp_f32_e32 v151, v151
	v_mul_f32_e32 v152, 0x3d372713, v73
	v_mul_f32_e32 v152, v73, v152
	v_add_f32_e32 v150, 1.0, v150
	v_add_f32_e32 v151, 1.0, v151
	v_rcp_f32_e32 v150, v150
	v_rcp_f32_e32 v151, v151
	v_fma_f32 v152, v73, v152, v73
	v_mul_f32_e32 v152, 0x3fcc422a, v152
	v_mul_f32_e32 v150, v70, v150
	v_mul_f32_e32 v151, v71, v151
	v_cvt_pk_bf16_f32 v150, v150, v151
	v_mul_f32_e32 v151, 0x3d372713, v72
	v_mul_f32_e32 v151, v72, v151
	v_fma_f32 v151, v72, v151, v72
	v_mul_f32_e32 v151, 0x3fcc422a, v151
	v_mul_f32_e32 v151, 0xbfb8aa3b, v151
	v_mul_f32_e32 v152, 0xbfb8aa3b, v152
	v_exp_f32_e32 v151, v151
	v_exp_f32_e32 v152, v152
	v_mul_f32_e32 v153, 0x3d372713, v67
	v_mul_f32_e32 v153, v67, v153
	v_add_f32_e32 v151, 1.0, v151
	v_add_f32_e32 v152, 1.0, v152
	v_rcp_f32_e32 v151, v151
	v_rcp_f32_e32 v152, v152
	v_fma_f32 v153, v67, v153, v67
	v_mul_f32_e32 v153, 0x3fcc422a, v153
	v_mul_f32_e32 v151, v72, v151
	v_mul_f32_e32 v152, v73, v152
	v_cvt_pk_bf16_f32 v151, v151, v152
	v_mul_f32_e32 v152, 0x3d372713, v66
	v_mul_f32_e32 v152, v66, v152
	v_fma_f32 v152, v66, v152, v66
	v_mul_f32_e32 v152, 0x3fcc422a, v152
	v_mul_f32_e32 v152, 0xbfb8aa3b, v152
	v_mul_f32_e32 v153, 0xbfb8aa3b, v153
	v_exp_f32_e32 v152, v152
	v_exp_f32_e32 v153, v153
	v_add_f32_e32 v152, 1.0, v152
	v_add_f32_e32 v153, 1.0, v153
	v_rcp_f32_e32 v152, v152
	v_rcp_f32_e32 v153, v153
	v_mul_f32_e32 v152, v66, v152
	v_mul_f32_e32 v153, v67, v153
	v_cvt_pk_bf16_f32 v152, v152, v153
	v_mul_f32_e32 v153, 0x3d372713, v68
	v_mul_f32_e32 v153, v68, v153
	v_fma_f32 v153, v68, v153, v68
	v_mul_f32_e32 v153, 0x3fcc422a, v153
	v_mul_f32_e32 v153, 0xbfb8aa3b, v153
	v_exp_f32_e32 v153, v153
	s_nop 0
	v_add_f32_e32 v153, 1.0, v153
	v_rcp_f32_e32 v153, v153
	s_nop 0
	v_mul_f32_e32 v153, v68, v153
	v_cvt_pk_bf16_f32 v153, v153, v154
	global_store_dwordx4 v[142:143], v[150:153], off offset:256 nt
	v_mul_f32_e32 v142, 0x3d372713, v62
	v_mul_f32_e32 v142, v62, v142
	v_mul_f32_e32 v143, 0x3d372713, v63
	v_fma_f32 v142, v62, v142, v62
	v_mul_f32_e32 v143, v63, v143
	v_mul_f32_e32 v142, 0x3fcc422a, v142
	v_fma_f32 v143, v63, v143, v63
	v_mul_f32_e32 v142, 0xbfb8aa3b, v142
	v_mul_f32_e32 v143, 0x3fcc422a, v143
	v_exp_f32_e32 v142, v142
	v_mul_f32_e32 v143, 0xbfb8aa3b, v143
	v_exp_f32_e32 v143, v143
	v_mul_f32_e32 v154, 0x3d372713, v45
	v_add_f32_e32 v142, 1.0, v142
	v_rcp_f32_e32 v142, v142
	v_add_f32_e32 v143, 1.0, v143
	v_rcp_f32_e32 v143, v143
	v_mul_f32_e32 v154, v45, v154
	v_mul_f32_e32 v142, v62, v142
	v_fma_f32 v154, v45, v154, v45
	v_mul_f32_e32 v143, v63, v143
	v_cvt_pk_bf16_f32 v150, v142, v143
	v_mul_f32_e32 v142, 0x3d372713, v64
	v_mul_f32_e32 v142, v64, v142
	v_mul_f32_e32 v143, 0x3d372713, v65
	v_fma_f32 v142, v64, v142, v64
	v_mul_f32_e32 v143, v65, v143
	v_mul_f32_e32 v142, 0x3fcc422a, v142
	v_fma_f32 v143, v65, v143, v65
	v_mul_f32_e32 v142, 0xbfb8aa3b, v142
	v_mul_f32_e32 v143, 0x3fcc422a, v143
	v_exp_f32_e32 v142, v142
	v_mul_f32_e32 v143, 0xbfb8aa3b, v143
	v_exp_f32_e32 v143, v143
	v_mul_f32_e32 v154, 0x3fcc422a, v154
	v_add_f32_e32 v142, 1.0, v142
	v_rcp_f32_e32 v142, v142
	v_add_f32_e32 v143, 1.0, v143
	v_rcp_f32_e32 v143, v143
	v_mul_f32_e32 v154, 0xbfb8aa3b, v154
	v_mul_f32_e32 v142, v64, v142
	v_exp_f32_e32 v154, v154
	v_mul_f32_e32 v143, v65, v143
	v_cvt_pk_bf16_f32 v151, v142, v143
	v_mul_f32_e32 v142, 0x3d372713, v58
	v_mul_f32_e32 v142, v58, v142
	v_mul_f32_e32 v143, 0x3d372713, v59
	v_fma_f32 v142, v58, v142, v58
	v_mul_f32_e32 v143, v59, v143
	v_mul_f32_e32 v142, 0x3fcc422a, v142
	v_fma_f32 v143, v59, v143, v59
	v_mul_f32_e32 v142, 0xbfb8aa3b, v142
	v_mul_f32_e32 v143, 0x3fcc422a, v143
	v_exp_f32_e32 v142, v142
	v_mul_f32_e32 v143, 0xbfb8aa3b, v143
	v_exp_f32_e32 v143, v143
	v_add_f32_e32 v154, 1.0, v154
	v_add_f32_e32 v142, 1.0, v142
	v_rcp_f32_e32 v142, v142
	v_add_f32_e32 v143, 1.0, v143
	v_rcp_f32_e32 v143, v143
	v_rcp_f32_e32 v154, v154
	v_mul_f32_e32 v142, v58, v142
	v_mul_f32_e32 v143, v59, v143
	v_cvt_pk_bf16_f32 v152, v142, v143
	v_mul_f32_e32 v142, 0x3d372713, v60
	v_mul_f32_e32 v142, v60, v142
	v_mul_f32_e32 v143, 0x3d372713, v61
	v_fma_f32 v142, v60, v142, v60
	v_mul_f32_e32 v143, v61, v143
	v_mul_f32_e32 v142, 0x3fcc422a, v142
	v_fma_f32 v143, v61, v143, v61
	v_mul_f32_e32 v142, 0xbfb8aa3b, v142
	v_mul_f32_e32 v143, 0x3fcc422a, v143
	v_exp_f32_e32 v142, v142
	v_mul_f32_e32 v143, 0xbfb8aa3b, v143
	v_exp_f32_e32 v143, v143
	v_mul_f32_e32 v154, v45, v154
	v_add_f32_e32 v142, 1.0, v142
	v_rcp_f32_e32 v142, v142
	v_add_f32_e32 v143, 1.0, v143
	v_rcp_f32_e32 v143, v143
	v_mul_f32_e32 v142, v60, v142
	v_mul_f32_e32 v143, v61, v143
	v_cvt_pk_bf16_f32 v153, v142, v143
	v_add_co_u32_e32 v142, vcc, s3, v140
	s_nop 1
	v_addc_co_u32_e32 v143, vcc, 0, v141, vcc
	global_store_dwordx4 v[142:143], v[150:153], off nt
	s_nop 1
	v_mul_f32_e32 v150, 0x3d372713, v50
	v_mul_f32_e32 v151, 0x3d372713, v51
	v_mul_f32_e32 v150, v50, v150
	v_mul_f32_e32 v151, v51, v151
	v_fma_f32 v150, v50, v150, v50
	v_fma_f32 v151, v51, v151, v51
	v_mul_f32_e32 v150, 0x3fcc422a, v150
	v_mul_f32_e32 v151, 0x3fcc422a, v151
	v_mul_f32_e32 v150, 0xbfb8aa3b, v150
	v_mul_f32_e32 v151, 0xbfb8aa3b, v151
	v_exp_f32_e32 v150, v150
	v_exp_f32_e32 v151, v151
	v_mul_f32_e32 v152, 0x3d372713, v53
	v_mul_f32_e32 v152, v53, v152
	v_add_f32_e32 v150, 1.0, v150
	v_add_f32_e32 v151, 1.0, v151
	v_rcp_f32_e32 v150, v150
	v_rcp_f32_e32 v151, v151
	v_fma_f32 v152, v53, v152, v53
	v_mul_f32_e32 v152, 0x3fcc422a, v152
	v_mul_f32_e32 v150, v50, v150
	v_mul_f32_e32 v151, v51, v151
	v_cvt_pk_bf16_f32 v150, v150, v151
	v_mul_f32_e32 v151, 0x3d372713, v52
	v_mul_f32_e32 v151, v52, v151
	v_fma_f32 v151, v52, v151, v52
	v_mul_f32_e32 v151, 0x3fcc422a, v151
	v_mul_f32_e32 v151, 0xbfb8aa3b, v151
	v_mul_f32_e32 v152, 0xbfb8aa3b, v152
	v_exp_f32_e32 v151, v151
	v_exp_f32_e32 v152, v152
	v_mul_f32_e32 v153, 0x3d372713, v43
	v_mul_f32_e32 v153, v43, v153
	v_add_f32_e32 v151, 1.0, v151
	v_add_f32_e32 v152, 1.0, v152
	v_rcp_f32_e32 v151, v151
	v_rcp_f32_e32 v152, v152
	v_fma_f32 v153, v43, v153, v43
	v_mul_f32_e32 v153, 0x3fcc422a, v153
	v_mul_f32_e32 v151, v52, v151
	v_mul_f32_e32 v152, v53, v152
	v_cvt_pk_bf16_f32 v151, v151, v152
	v_mul_f32_e32 v152, 0x3d372713, v42
	v_mul_f32_e32 v152, v42, v152
	v_fma_f32 v152, v42, v152, v42
	v_mul_f32_e32 v152, 0x3fcc422a, v152
	v_mul_f32_e32 v152, 0xbfb8aa3b, v152
	v_mul_f32_e32 v153, 0xbfb8aa3b, v153
	v_exp_f32_e32 v152, v152
	v_exp_f32_e32 v153, v153
	v_add_f32_e32 v152, 1.0, v152
	v_add_f32_e32 v153, 1.0, v153
	v_rcp_f32_e32 v152, v152
	v_rcp_f32_e32 v153, v153
	v_mul_f32_e32 v152, v42, v152
	v_mul_f32_e32 v153, v43, v153
	v_cvt_pk_bf16_f32 v152, v152, v153
	v_mul_f32_e32 v153, 0x3d372713, v44
	v_mul_f32_e32 v153, v44, v153
	v_fma_f32 v153, v44, v153, v44
	v_mul_f32_e32 v153, 0x3fcc422a, v153
	v_mul_f32_e32 v153, 0xbfb8aa3b, v153
	v_exp_f32_e32 v153, v153
	s_nop 0
	v_add_f32_e32 v153, 1.0, v153
	v_rcp_f32_e32 v153, v153
	s_nop 0
	v_mul_f32_e32 v153, v44, v153
	v_cvt_pk_bf16_f32 v153, v153, v154
	global_store_dwordx4 v[142:143], v[150:153], off offset:256 nt
	v_mul_f32_e32 v142, 0x3d372713, v54
	v_mul_f32_e32 v142, v54, v142
	v_mul_f32_e32 v143, 0x3d372713, v55
	v_fma_f32 v142, v54, v142, v54
	v_mul_f32_e32 v143, v55, v143
	v_mul_f32_e32 v142, 0x3fcc422a, v142
	v_fma_f32 v143, v55, v143, v55
	v_mul_f32_e32 v142, 0xbfb8aa3b, v142
	v_mul_f32_e32 v143, 0x3fcc422a, v143
	v_exp_f32_e32 v142, v142
	v_mul_f32_e32 v143, 0xbfb8aa3b, v143
	v_exp_f32_e32 v143, v143
	v_mul_f32_e32 v154, 0x3d372713, v29
	v_add_f32_e32 v142, 1.0, v142
	v_rcp_f32_e32 v142, v142
	v_add_f32_e32 v143, 1.0, v143
	v_rcp_f32_e32 v143, v143
	v_mul_f32_e32 v154, v29, v154
	v_mul_f32_e32 v142, v54, v142
	v_fma_f32 v154, v29, v154, v29
	v_mul_f32_e32 v143, v55, v143
	v_cvt_pk_bf16_f32 v150, v142, v143
	v_mul_f32_e32 v142, 0x3d372713, v56
	v_mul_f32_e32 v142, v56, v142
	v_mul_f32_e32 v143, 0x3d372713, v57
	v_fma_f32 v142, v56, v142, v56
	v_mul_f32_e32 v143, v57, v143
	v_mul_f32_e32 v142, 0x3fcc422a, v142
	v_fma_f32 v143, v57, v143, v57
	v_mul_f32_e32 v142, 0xbfb8aa3b, v142
	v_mul_f32_e32 v143, 0x3fcc422a, v143
	v_exp_f32_e32 v142, v142
	v_mul_f32_e32 v143, 0xbfb8aa3b, v143
	v_exp_f32_e32 v143, v143
	v_mul_f32_e32 v154, 0x3fcc422a, v154
	v_add_f32_e32 v142, 1.0, v142
	v_rcp_f32_e32 v142, v142
	v_add_f32_e32 v143, 1.0, v143
	v_rcp_f32_e32 v143, v143
	v_mul_f32_e32 v154, 0xbfb8aa3b, v154
	v_mul_f32_e32 v142, v56, v142
	v_exp_f32_e32 v154, v154
	v_mul_f32_e32 v143, v57, v143
	v_cvt_pk_bf16_f32 v151, v142, v143
	v_mul_f32_e32 v142, 0x3d372713, v46
	v_mul_f32_e32 v142, v46, v142
	v_mul_f32_e32 v143, 0x3d372713, v47
	v_fma_f32 v142, v46, v142, v46
	v_mul_f32_e32 v143, v47, v143
	v_mul_f32_e32 v142, 0x3fcc422a, v142
	v_fma_f32 v143, v47, v143, v47
	v_mul_f32_e32 v142, 0xbfb8aa3b, v142
	v_mul_f32_e32 v143, 0x3fcc422a, v143
	v_exp_f32_e32 v142, v142
	v_mul_f32_e32 v143, 0xbfb8aa3b, v143
	v_exp_f32_e32 v143, v143
	v_add_f32_e32 v154, 1.0, v154
	v_add_f32_e32 v142, 1.0, v142
	v_rcp_f32_e32 v142, v142
	v_add_f32_e32 v143, 1.0, v143
	v_rcp_f32_e32 v143, v143
	v_rcp_f32_e32 v154, v154
	v_mul_f32_e32 v142, v46, v142
	v_mul_f32_e32 v143, v47, v143
	v_cvt_pk_bf16_f32 v152, v142, v143
	v_mul_f32_e32 v142, 0x3d372713, v48
	v_mul_f32_e32 v142, v48, v142
	v_mul_f32_e32 v143, 0x3d372713, v49
	v_fma_f32 v142, v48, v142, v48
	v_mul_f32_e32 v143, v49, v143
	v_mul_f32_e32 v142, 0x3fcc422a, v142
	v_fma_f32 v143, v49, v143, v49
	v_mul_f32_e32 v142, 0xbfb8aa3b, v142
	v_mul_f32_e32 v143, 0x3fcc422a, v143
	v_exp_f32_e32 v142, v142
	v_mul_f32_e32 v143, 0xbfb8aa3b, v143
	v_exp_f32_e32 v143, v143
	v_mul_f32_e32 v154, v29, v154
	v_add_f32_e32 v142, 1.0, v142
	v_rcp_f32_e32 v142, v142
	v_add_f32_e32 v143, 1.0, v143
	v_rcp_f32_e32 v143, v143
	v_mul_f32_e32 v142, v48, v142
	v_mul_f32_e32 v143, v49, v143
	v_cvt_pk_bf16_f32 v153, v142, v143
	v_add_co_u32_e32 v142, vcc, s6, v140
	s_mov_b32 s6, 0x410000
	s_nop 0
	v_addc_co_u32_e32 v143, vcc, 0, v141, vcc
	global_store_dwordx4 v[142:143], v[150:153], off nt
	s_nop 1
	v_mul_f32_e32 v150, 0x3d372713, v34
	v_mul_f32_e32 v151, 0x3d372713, v35
	v_mul_f32_e32 v150, v34, v150
	v_mul_f32_e32 v151, v35, v151
	v_fma_f32 v150, v34, v150, v34
	v_fma_f32 v151, v35, v151, v35
	v_mul_f32_e32 v150, 0x3fcc422a, v150
	v_mul_f32_e32 v151, 0x3fcc422a, v151
	v_mul_f32_e32 v150, 0xbfb8aa3b, v150
	v_mul_f32_e32 v151, 0xbfb8aa3b, v151
	v_exp_f32_e32 v150, v150
	v_exp_f32_e32 v151, v151
	v_mul_f32_e32 v152, 0x3d372713, v37
	v_mul_f32_e32 v152, v37, v152
	v_add_f32_e32 v150, 1.0, v150
	v_add_f32_e32 v151, 1.0, v151
	v_rcp_f32_e32 v150, v150
	v_rcp_f32_e32 v151, v151
	v_fma_f32 v152, v37, v152, v37
	v_mul_f32_e32 v152, 0x3fcc422a, v152
	v_mul_f32_e32 v150, v34, v150
	v_mul_f32_e32 v151, v35, v151
	v_cvt_pk_bf16_f32 v150, v150, v151
	v_mul_f32_e32 v151, 0x3d372713, v36
	v_mul_f32_e32 v151, v36, v151
	v_fma_f32 v151, v36, v151, v36
	v_mul_f32_e32 v151, 0x3fcc422a, v151
	v_mul_f32_e32 v151, 0xbfb8aa3b, v151
	v_mul_f32_e32 v152, 0xbfb8aa3b, v152
	v_exp_f32_e32 v151, v151
	v_exp_f32_e32 v152, v152
	v_mul_f32_e32 v153, 0x3d372713, v27
	v_mul_f32_e32 v153, v27, v153
	v_add_f32_e32 v151, 1.0, v151
	v_add_f32_e32 v152, 1.0, v152
	v_rcp_f32_e32 v151, v151
	v_rcp_f32_e32 v152, v152
	v_fma_f32 v153, v27, v153, v27
	v_mul_f32_e32 v153, 0x3fcc422a, v153
	v_mul_f32_e32 v151, v36, v151
	v_mul_f32_e32 v152, v37, v152
	v_cvt_pk_bf16_f32 v151, v151, v152
	v_mul_f32_e32 v152, 0x3d372713, v26
	v_mul_f32_e32 v152, v26, v152
	v_fma_f32 v152, v26, v152, v26
	v_mul_f32_e32 v152, 0x3fcc422a, v152
	v_mul_f32_e32 v152, 0xbfb8aa3b, v152
	v_mul_f32_e32 v153, 0xbfb8aa3b, v153
	v_exp_f32_e32 v152, v152
	v_exp_f32_e32 v153, v153
	v_add_f32_e32 v152, 1.0, v152
	v_add_f32_e32 v153, 1.0, v153
	v_rcp_f32_e32 v152, v152
	v_rcp_f32_e32 v153, v153
	v_mul_f32_e32 v152, v26, v152
	v_mul_f32_e32 v153, v27, v153
	v_cvt_pk_bf16_f32 v152, v152, v153
	v_mul_f32_e32 v153, 0x3d372713, v28
	v_mul_f32_e32 v153, v28, v153
	v_fma_f32 v153, v28, v153, v28
	v_mul_f32_e32 v153, 0x3fcc422a, v153
	v_mul_f32_e32 v153, 0xbfb8aa3b, v153
	v_exp_f32_e32 v153, v153
	s_nop 0
	v_add_f32_e32 v153, 1.0, v153
	v_rcp_f32_e32 v153, v153
	s_nop 0
	v_mul_f32_e32 v153, v28, v153
	v_cvt_pk_bf16_f32 v153, v153, v154
	global_store_dwordx4 v[142:143], v[150:153], off offset:256 nt
	v_mul_f32_e32 v142, 0x3d372713, v38
	v_mul_f32_e32 v142, v38, v142
	v_mul_f32_e32 v143, 0x3d372713, v39
	v_fma_f32 v142, v38, v142, v38
	v_mul_f32_e32 v143, v39, v143
	v_mul_f32_e32 v142, 0x3fcc422a, v142
	v_fma_f32 v143, v39, v143, v39
	v_mul_f32_e32 v142, 0xbfb8aa3b, v142
	v_mul_f32_e32 v143, 0x3fcc422a, v143
	v_exp_f32_e32 v142, v142
	v_mul_f32_e32 v143, 0xbfb8aa3b, v143
	v_exp_f32_e32 v143, v143
	v_mul_f32_e32 v154, 0x3d372713, v13
	v_add_f32_e32 v142, 1.0, v142
	v_rcp_f32_e32 v142, v142
	v_add_f32_e32 v143, 1.0, v143
	v_rcp_f32_e32 v143, v143
	v_mul_f32_e32 v154, v13, v154
	v_mul_f32_e32 v142, v38, v142
	v_fma_f32 v154, v13, v154, v13
	v_mul_f32_e32 v143, v39, v143
	v_cvt_pk_bf16_f32 v150, v142, v143
	v_mul_f32_e32 v142, 0x3d372713, v40
	v_mul_f32_e32 v142, v40, v142
	v_mul_f32_e32 v143, 0x3d372713, v41
	v_fma_f32 v142, v40, v142, v40
	v_mul_f32_e32 v143, v41, v143
	v_mul_f32_e32 v142, 0x3fcc422a, v142
	v_fma_f32 v143, v41, v143, v41
	v_mul_f32_e32 v142, 0xbfb8aa3b, v142
	v_mul_f32_e32 v143, 0x3fcc422a, v143
	v_exp_f32_e32 v142, v142
	v_mul_f32_e32 v143, 0xbfb8aa3b, v143
	v_exp_f32_e32 v143, v143
	v_mul_f32_e32 v154, 0x3fcc422a, v154
	v_add_f32_e32 v142, 1.0, v142
	v_rcp_f32_e32 v142, v142
	v_add_f32_e32 v143, 1.0, v143
	v_rcp_f32_e32 v143, v143
	v_mul_f32_e32 v154, 0xbfb8aa3b, v154
	v_mul_f32_e32 v142, v40, v142
	v_exp_f32_e32 v154, v154
	v_mul_f32_e32 v143, v41, v143
	v_cvt_pk_bf16_f32 v151, v142, v143
	v_mul_f32_e32 v142, 0x3d372713, v30
	v_mul_f32_e32 v142, v30, v142
	v_mul_f32_e32 v143, 0x3d372713, v31
	v_fma_f32 v142, v30, v142, v30
	v_mul_f32_e32 v143, v31, v143
	v_mul_f32_e32 v142, 0x3fcc422a, v142
	v_fma_f32 v143, v31, v143, v31
	v_mul_f32_e32 v142, 0xbfb8aa3b, v142
	v_mul_f32_e32 v143, 0x3fcc422a, v143
	v_exp_f32_e32 v142, v142
	v_mul_f32_e32 v143, 0xbfb8aa3b, v143
	v_exp_f32_e32 v143, v143
	v_add_f32_e32 v154, 1.0, v154
	v_add_f32_e32 v142, 1.0, v142
	v_rcp_f32_e32 v142, v142
	v_add_f32_e32 v143, 1.0, v143
	v_rcp_f32_e32 v143, v143
	v_rcp_f32_e32 v154, v154
	v_mul_f32_e32 v142, v30, v142
	v_mul_f32_e32 v143, v31, v143
	v_cvt_pk_bf16_f32 v152, v142, v143
	v_mul_f32_e32 v142, 0x3d372713, v32
	v_mul_f32_e32 v142, v32, v142
	v_mul_f32_e32 v143, 0x3d372713, v33
	v_fma_f32 v142, v32, v142, v32
	v_mul_f32_e32 v143, v33, v143
	v_mul_f32_e32 v142, 0x3fcc422a, v142
	v_fma_f32 v143, v33, v143, v33
	v_mul_f32_e32 v142, 0xbfb8aa3b, v142
	v_mul_f32_e32 v143, 0x3fcc422a, v143
	v_exp_f32_e32 v142, v142
	v_mul_f32_e32 v143, 0xbfb8aa3b, v143
	v_exp_f32_e32 v143, v143
	v_mul_f32_e32 v154, v13, v154
	v_add_f32_e32 v142, 1.0, v142
	v_rcp_f32_e32 v142, v142
	v_add_f32_e32 v143, 1.0, v143
	v_rcp_f32_e32 v143, v143
	v_mul_f32_e32 v142, v32, v142
	v_mul_f32_e32 v143, v33, v143
	v_cvt_pk_bf16_f32 v153, v142, v143
	v_add_co_u32_e32 v142, vcc, s6, v140
	s_mov_b32 s6, 0x478000
	s_nop 0
	v_addc_co_u32_e32 v143, vcc, 0, v141, vcc
	global_store_dwordx4 v[142:143], v[150:153], off nt
	s_nop 1
	v_mul_f32_e32 v150, 0x3d372713, v18
	v_mul_f32_e32 v151, 0x3d372713, v19
	v_mul_f32_e32 v150, v18, v150
	v_mul_f32_e32 v151, v19, v151
	v_fma_f32 v150, v18, v150, v18
	v_fma_f32 v151, v19, v151, v19
	v_mul_f32_e32 v150, 0x3fcc422a, v150
	v_mul_f32_e32 v151, 0x3fcc422a, v151
	v_mul_f32_e32 v150, 0xbfb8aa3b, v150
	v_mul_f32_e32 v151, 0xbfb8aa3b, v151
	v_exp_f32_e32 v150, v150
	v_exp_f32_e32 v151, v151
	v_mul_f32_e32 v152, 0x3d372713, v21
	v_mul_f32_e32 v152, v21, v152
	v_add_f32_e32 v150, 1.0, v150
	v_add_f32_e32 v151, 1.0, v151
	v_rcp_f32_e32 v150, v150
	v_rcp_f32_e32 v151, v151
	v_fma_f32 v152, v21, v152, v21
	v_mul_f32_e32 v152, 0x3fcc422a, v152
	v_mul_f32_e32 v150, v18, v150
	v_mul_f32_e32 v151, v19, v151
	v_cvt_pk_bf16_f32 v150, v150, v151
	v_mul_f32_e32 v151, 0x3d372713, v20
	v_mul_f32_e32 v151, v20, v151
	v_fma_f32 v151, v20, v151, v20
	v_mul_f32_e32 v151, 0x3fcc422a, v151
	v_mul_f32_e32 v151, 0xbfb8aa3b, v151
	v_mul_f32_e32 v152, 0xbfb8aa3b, v152
	v_exp_f32_e32 v151, v151
	v_exp_f32_e32 v152, v152
	v_mul_f32_e32 v153, 0x3d372713, v11
	v_mul_f32_e32 v153, v11, v153
	v_add_f32_e32 v151, 1.0, v151
	v_add_f32_e32 v152, 1.0, v152
	v_rcp_f32_e32 v151, v151
	v_rcp_f32_e32 v152, v152
	v_fma_f32 v153, v11, v153, v11
	v_mul_f32_e32 v153, 0x3fcc422a, v153
	v_mul_f32_e32 v151, v20, v151
	v_mul_f32_e32 v152, v21, v152
	v_cvt_pk_bf16_f32 v151, v151, v152
	v_mul_f32_e32 v152, 0x3d372713, v10
	v_mul_f32_e32 v152, v10, v152
	v_fma_f32 v152, v10, v152, v10
	v_mul_f32_e32 v152, 0x3fcc422a, v152
	v_mul_f32_e32 v152, 0xbfb8aa3b, v152
	v_mul_f32_e32 v153, 0xbfb8aa3b, v153
	v_exp_f32_e32 v152, v152
	v_exp_f32_e32 v153, v153
	v_add_f32_e32 v152, 1.0, v152
	v_add_f32_e32 v153, 1.0, v153
	v_rcp_f32_e32 v152, v152
	v_rcp_f32_e32 v153, v153
	v_mul_f32_e32 v152, v10, v152
	v_mul_f32_e32 v153, v11, v153
	v_cvt_pk_bf16_f32 v152, v152, v153
	v_mul_f32_e32 v153, 0x3d372713, v12
	v_mul_f32_e32 v153, v12, v153
	v_fma_f32 v153, v12, v153, v12
	v_mul_f32_e32 v153, 0x3fcc422a, v153
	v_mul_f32_e32 v153, 0xbfb8aa3b, v153
	v_exp_f32_e32 v153, v153
	s_nop 0
	v_add_f32_e32 v153, 1.0, v153
	v_rcp_f32_e32 v153, v153
	s_nop 0
	v_mul_f32_e32 v153, v12, v153
	v_cvt_pk_bf16_f32 v153, v153, v154
	global_store_dwordx4 v[142:143], v[150:153], off offset:256 nt
	v_mul_f32_e32 v142, 0x3d372713, v22
	v_mul_f32_e32 v142, v22, v142
	v_mul_f32_e32 v143, 0x3d372713, v23
	v_fma_f32 v142, v22, v142, v22
	v_mul_f32_e32 v143, v23, v143
	v_mul_f32_e32 v142, 0x3fcc422a, v142
	v_fma_f32 v143, v23, v143, v23
	v_mul_f32_e32 v142, 0xbfb8aa3b, v142
	v_mul_f32_e32 v143, 0x3fcc422a, v143
	v_exp_f32_e32 v142, v142
	v_mul_f32_e32 v143, 0xbfb8aa3b, v143
	v_exp_f32_e32 v143, v143
	v_mul_f32_e32 v154, 0x3d372713, v5
	v_add_f32_e32 v142, 1.0, v142
	v_rcp_f32_e32 v142, v142
	v_add_f32_e32 v143, 1.0, v143
	v_rcp_f32_e32 v143, v143
	v_mul_f32_e32 v154, v5, v154
	v_mul_f32_e32 v142, v22, v142
	v_fma_f32 v154, v5, v154, v5
	v_mul_f32_e32 v143, v23, v143
	v_cvt_pk_bf16_f32 v150, v142, v143
	v_mul_f32_e32 v142, 0x3d372713, v24
	v_mul_f32_e32 v142, v24, v142
	v_mul_f32_e32 v143, 0x3d372713, v25
	v_fma_f32 v142, v24, v142, v24
	v_mul_f32_e32 v143, v25, v143
	v_mul_f32_e32 v142, 0x3fcc422a, v142
	v_fma_f32 v143, v25, v143, v25
	v_mul_f32_e32 v142, 0xbfb8aa3b, v142
	v_mul_f32_e32 v143, 0x3fcc422a, v143
	v_exp_f32_e32 v142, v142
	v_mul_f32_e32 v143, 0xbfb8aa3b, v143
	v_exp_f32_e32 v143, v143
	v_mul_f32_e32 v154, 0x3fcc422a, v154
	v_add_f32_e32 v142, 1.0, v142
	v_rcp_f32_e32 v142, v142
	v_add_f32_e32 v143, 1.0, v143
	v_rcp_f32_e32 v143, v143
	v_mul_f32_e32 v154, 0xbfb8aa3b, v154
	v_mul_f32_e32 v142, v24, v142
	v_exp_f32_e32 v154, v154
	v_mul_f32_e32 v143, v25, v143
	v_cvt_pk_bf16_f32 v151, v142, v143
	v_mul_f32_e32 v142, 0x3d372713, v14
	v_mul_f32_e32 v142, v14, v142
	v_mul_f32_e32 v143, 0x3d372713, v15
	v_fma_f32 v142, v14, v142, v14
	v_mul_f32_e32 v143, v15, v143
	v_mul_f32_e32 v142, 0x3fcc422a, v142
	v_fma_f32 v143, v15, v143, v15
	v_mul_f32_e32 v142, 0xbfb8aa3b, v142
	v_mul_f32_e32 v143, 0x3fcc422a, v143
	v_exp_f32_e32 v142, v142
	v_mul_f32_e32 v143, 0xbfb8aa3b, v143
	v_exp_f32_e32 v143, v143
	v_add_f32_e32 v154, 1.0, v154
	v_add_f32_e32 v142, 1.0, v142
	v_rcp_f32_e32 v142, v142
	v_add_f32_e32 v143, 1.0, v143
	v_rcp_f32_e32 v143, v143
	v_rcp_f32_e32 v154, v154
	v_mul_f32_e32 v142, v14, v142
	v_mul_f32_e32 v143, v15, v143
	v_cvt_pk_bf16_f32 v152, v142, v143
	v_mul_f32_e32 v142, 0x3d372713, v16
	v_mul_f32_e32 v142, v16, v142
	v_mul_f32_e32 v143, 0x3d372713, v17
	v_fma_f32 v142, v16, v142, v16
	v_mul_f32_e32 v143, v17, v143
	v_mul_f32_e32 v142, 0x3fcc422a, v142
	v_fma_f32 v143, v17, v143, v17
	v_mul_f32_e32 v142, 0xbfb8aa3b, v142
	v_mul_f32_e32 v143, 0x3fcc422a, v143
	v_exp_f32_e32 v142, v142
	v_mul_f32_e32 v143, 0xbfb8aa3b, v143
	v_exp_f32_e32 v143, v143
	v_mul_f32_e32 v154, v5, v154
	v_add_f32_e32 v142, 1.0, v142
	v_rcp_f32_e32 v142, v142
	v_add_f32_e32 v143, 1.0, v143
	v_rcp_f32_e32 v143, v143
	v_mul_f32_e32 v142, v16, v142
	v_mul_f32_e32 v143, v17, v143
	v_cvt_pk_bf16_f32 v153, v142, v143
	v_add_co_u32_e32 v142, vcc, s6, v140
	s_nop 1
	v_addc_co_u32_e32 v143, vcc, 0, v141, vcc
	global_store_dwordx4 v[142:143], v[150:153], off nt
	s_nop 1
	v_mul_f32_e32 v150, 0x3d372713, v6
	v_mul_f32_e32 v151, 0x3d372713, v7
	v_mul_f32_e32 v150, v6, v150
	v_mul_f32_e32 v151, v7, v151
	v_fma_f32 v150, v6, v150, v6
	v_fma_f32 v151, v7, v151, v7
	v_mul_f32_e32 v150, 0x3fcc422a, v150
	v_mul_f32_e32 v151, 0x3fcc422a, v151
	v_mul_f32_e32 v150, 0xbfb8aa3b, v150
	v_mul_f32_e32 v151, 0xbfb8aa3b, v151
	v_exp_f32_e32 v150, v150
	v_exp_f32_e32 v151, v151
	v_mul_f32_e32 v152, 0x3d372713, v9
	v_mul_f32_e32 v152, v9, v152
	v_add_f32_e32 v150, 1.0, v150
	v_add_f32_e32 v151, 1.0, v151
	v_rcp_f32_e32 v150, v150
	v_rcp_f32_e32 v151, v151
	v_fma_f32 v152, v9, v152, v9
	v_mul_f32_e32 v152, 0x3fcc422a, v152
	v_mul_f32_e32 v150, v6, v150
	v_mul_f32_e32 v151, v7, v151
	v_cvt_pk_bf16_f32 v150, v150, v151
	v_mul_f32_e32 v151, 0x3d372713, v8
	v_mul_f32_e32 v151, v8, v151
	v_fma_f32 v151, v8, v151, v8
	v_mul_f32_e32 v151, 0x3fcc422a, v151
	v_mul_f32_e32 v151, 0xbfb8aa3b, v151
	v_mul_f32_e32 v152, 0xbfb8aa3b, v152
	v_exp_f32_e32 v151, v151
	v_exp_f32_e32 v152, v152
	v_mul_f32_e32 v153, 0x3d372713, v3
	v_mul_f32_e32 v153, v3, v153
	v_add_f32_e32 v151, 1.0, v151
	v_add_f32_e32 v152, 1.0, v152
	v_rcp_f32_e32 v151, v151
	v_rcp_f32_e32 v152, v152
	v_fma_f32 v153, v3, v153, v3
	v_mul_f32_e32 v153, 0x3fcc422a, v153
	v_mul_f32_e32 v151, v8, v151
	v_mul_f32_e32 v152, v9, v152
	v_cvt_pk_bf16_f32 v151, v151, v152
	v_mul_f32_e32 v152, 0x3d372713, v2
	v_mul_f32_e32 v152, v2, v152
	v_fma_f32 v152, v2, v152, v2
	v_mul_f32_e32 v152, 0x3fcc422a, v152
	v_mul_f32_e32 v152, 0xbfb8aa3b, v152
	v_mul_f32_e32 v153, 0xbfb8aa3b, v153
	v_exp_f32_e32 v152, v152
	v_exp_f32_e32 v153, v153
	v_add_f32_e32 v152, 1.0, v152
	v_add_f32_e32 v153, 1.0, v153
	v_rcp_f32_e32 v152, v152
	v_rcp_f32_e32 v153, v153
	v_mul_f32_e32 v152, v2, v152
	v_mul_f32_e32 v153, v3, v153
	v_cvt_pk_bf16_f32 v152, v152, v153
	v_mul_f32_e32 v153, 0x3d372713, v4
	v_mul_f32_e32 v153, v4, v153
	v_fma_f32 v153, v4, v153, v4
	v_mul_f32_e32 v153, 0x3fcc422a, v153
	v_mul_f32_e32 v153, 0xbfb8aa3b, v153
	v_exp_f32_e32 v153, v153
	s_nop 0
	v_add_f32_e32 v153, 1.0, v153
	v_rcp_f32_e32 v153, v153
	s_nop 0
	v_mul_f32_e32 v153, v4, v153
	v_cvt_pk_bf16_f32 v153, v153, v154
	global_store_dwordx4 v[142:143], v[150:153], off offset:256 nt

.LBB0_165:
	v_mul_f32_e32 v142, 0xbfb8aa3b, v126
	v_exp_f32_e32 v142, v142
	v_mul_f32_e32 v143, 0xbfb8aa3b, v127
	v_exp_f32_e32 v143, v143
	v_mul_f32_e32 v154, 0xbfb8aa3b, v93
	v_add_f32_e32 v142, 1.0, v142
	v_rcp_f32_e32 v142, v142
	v_add_f32_e32 v143, 1.0, v143
	v_rcp_f32_e32 v143, v143
	v_cvt_pk_bf16_f32 v150, v142, v143
	v_mul_f32_e32 v142, 0xbfb8aa3b, v128
	v_exp_f32_e32 v142, v142
	v_mul_f32_e32 v143, 0xbfb8aa3b, v129
	v_exp_f32_e32 v143, v143
	v_exp_f32_e32 v154, v154
	v_add_f32_e32 v142, 1.0, v142
	v_rcp_f32_e32 v142, v142
	v_add_f32_e32 v143, 1.0, v143
	v_rcp_f32_e32 v143, v143
	v_cvt_pk_bf16_f32 v151, v142, v143
	v_mul_f32_e32 v142, 0xbfb8aa3b, v122
	v_exp_f32_e32 v142, v142
	v_mul_f32_e32 v143, 0xbfb8aa3b, v123
	v_exp_f32_e32 v143, v143
	v_add_f32_e32 v154, 1.0, v154
	v_add_f32_e32 v142, 1.0, v142
	v_rcp_f32_e32 v142, v142
	v_add_f32_e32 v143, 1.0, v143
	v_rcp_f32_e32 v143, v143
	v_cvt_pk_bf16_f32 v152, v142, v143
	v_mul_f32_e32 v142, 0xbfb8aa3b, v124
	v_exp_f32_e32 v142, v142
	v_mul_f32_e32 v143, 0xbfb8aa3b, v125
	v_exp_f32_e32 v143, v143
	v_rcp_f32_e32 v154, v154
	v_add_f32_e32 v142, 1.0, v142
	v_rcp_f32_e32 v142, v142
	v_add_f32_e32 v143, 1.0, v143
	v_rcp_f32_e32 v143, v143
	v_cvt_pk_bf16_f32 v153, v142, v143
	v_mul_f32_e32 v142, 0xbfb8aa3b, v114
	v_exp_f32_e32 v142, v142
	v_mul_f32_e32 v143, 0xbfb8aa3b, v115
	v_exp_f32_e32 v143, v143
	global_store_dwordx4 v[140:141], v[150:153], off nt
	v_add_f32_e32 v142, 1.0, v142
	v_rcp_f32_e32 v142, v142
	v_add_f32_e32 v143, 1.0, v143
	v_rcp_f32_e32 v143, v143
	v_cvt_pk_bf16_f32 v150, v142, v143
	v_mul_f32_e32 v142, 0xbfb8aa3b, v116
	v_exp_f32_e32 v142, v142
	v_mul_f32_e32 v143, 0xbfb8aa3b, v117
	v_exp_f32_e32 v143, v143
	s_mov_b32 s6, 0x3a8000
	v_add_f32_e32 v142, 1.0, v142
	v_rcp_f32_e32 v142, v142
	v_add_f32_e32 v143, 1.0, v143
	v_rcp_f32_e32 v143, v143
	v_cvt_pk_bf16_f32 v151, v142, v143
	v_mul_f32_e32 v142, 0xbfb8aa3b, v106
	v_exp_f32_e32 v142, v142
	v_mul_f32_e32 v143, 0xbfb8aa3b, v107
	v_exp_f32_e32 v143, v143
	v_add_f32_e32 v142, 1.0, v142
	v_rcp_f32_e32 v142, v142
	v_add_f32_e32 v143, 1.0, v143
	v_rcp_f32_e32 v143, v143
	v_cvt_pk_bf16_f32 v152, v142, v143
	v_mul_f32_e32 v142, 0xbfb8aa3b, v108
	v_exp_f32_e32 v142, v142
	v_mul_f32_e32 v143, 0xbfb8aa3b, v109
	v_exp_f32_e32 v143, v143
	v_add_f32_e32 v142, 1.0, v142
	v_rcp_f32_e32 v142, v142
	v_add_f32_e32 v143, 1.0, v143
	v_rcp_f32_e32 v143, v143
	v_cvt_pk_bf16_f32 v153, v142, v143
	v_mul_f32_e32 v142, 0xbfb8aa3b, v118
	v_exp_f32_e32 v142, v142
	v_mul_f32_e32 v143, 0xbfb8aa3b, v119
	v_exp_f32_e32 v143, v143
	global_store_dwordx4 v[140:141], v[150:153], off offset:256 nt
	v_add_f32_e32 v142, 1.0, v142
	v_rcp_f32_e32 v142, v142
	v_add_f32_e32 v143, 1.0, v143
	v_rcp_f32_e32 v143, v143
	v_cvt_pk_bf16_f32 v150, v142, v143
	v_mul_f32_e32 v142, 0xbfb8aa3b, v120
	v_exp_f32_e32 v142, v142
	v_mul_f32_e32 v143, 0xbfb8aa3b, v121
	v_exp_f32_e32 v143, v143
	v_add_f32_e32 v142, 1.0, v142
	v_rcp_f32_e32 v142, v142
	v_add_f32_e32 v143, 1.0, v143
	v_rcp_f32_e32 v143, v143
	v_cvt_pk_bf16_f32 v151, v142, v143
	v_mul_f32_e32 v142, 0xbfb8aa3b, v110
	v_exp_f32_e32 v142, v142
	v_mul_f32_e32 v143, 0xbfb8aa3b, v111
	v_exp_f32_e32 v143, v143
	v_add_f32_e32 v142, 1.0, v142
	v_rcp_f32_e32 v142, v142
	v_add_f32_e32 v143, 1.0, v143
	v_rcp_f32_e32 v143, v143
	v_cvt_pk_bf16_f32 v152, v142, v143
	v_mul_f32_e32 v142, 0xbfb8aa3b, v112
	v_exp_f32_e32 v142, v142
	v_mul_f32_e32 v143, 0xbfb8aa3b, v113
	v_exp_f32_e32 v143, v143
	v_add_f32_e32 v142, 1.0, v142
	v_rcp_f32_e32 v142, v142
	v_add_f32_e32 v143, 1.0, v143
	v_rcp_f32_e32 v143, v143
	v_cvt_pk_bf16_f32 v153, v142, v143
	v_add_co_u32_e32 v142, vcc, s24, v140
	s_nop 1
	v_addc_co_u32_e32 v143, vcc, 0, v141, vcc
	global_store_dwordx4 v[142:143], v[150:153], off nt
	s_nop 1
	v_mul_f32_e32 v150, 0xbfb8aa3b, v98
	v_mul_f32_e32 v151, 0xbfb8aa3b, v99
	v_exp_f32_e32 v150, v150
	v_exp_f32_e32 v151, v151
	v_mul_f32_e32 v152, 0xbfb8aa3b, v101
	v_exp_f32_e32 v152, v152
	v_add_f32_e32 v150, 1.0, v150
	v_add_f32_e32 v151, 1.0, v151
	v_rcp_f32_e32 v150, v150
	v_rcp_f32_e32 v151, v151
	v_cvt_pk_bf16_f32 v150, v150, v151
	v_mul_f32_e32 v151, 0xbfb8aa3b, v100
	v_exp_f32_e32 v151, v151
	v_add_f32_e32 v152, 1.0, v152
	v_rcp_f32_e32 v152, v152
	v_mul_f32_e32 v153, 0xbfb8aa3b, v91
	v_add_f32_e32 v151, 1.0, v151
	v_rcp_f32_e32 v151, v151
	v_cvt_pk_bf16_f32 v151, v151, v152
	v_mul_f32_e32 v152, 0xbfb8aa3b, v90
	v_exp_f32_e32 v152, v152
	v_exp_f32_e32 v153, v153
	v_add_f32_e32 v152, 1.0, v152
	v_add_f32_e32 v153, 1.0, v153
	v_rcp_f32_e32 v152, v152
	v_rcp_f32_e32 v153, v153
	v_cvt_pk_bf16_f32 v152, v152, v153
	v_mul_f32_e32 v153, 0xbfb8aa3b, v92
	v_exp_f32_e32 v153, v153
	s_nop 0
	v_add_f32_e32 v153, 1.0, v153
	v_rcp_f32_e32 v153, v153
	v_cvt_pk_bf16_f32 v153, v153, v154
	global_store_dwordx4 v[142:143], v[150:153], off offset:256 nt
	v_mul_f32_e32 v142, 0xbfb8aa3b, v102
	v_exp_f32_e32 v142, v142
	v_mul_f32_e32 v143, 0xbfb8aa3b, v103
	v_exp_f32_e32 v143, v143
	v_mul_f32_e32 v154, 0xbfb8aa3b, v77
	v_add_f32_e32 v142, 1.0, v142
	v_rcp_f32_e32 v142, v142
	v_add_f32_e32 v143, 1.0, v143
	v_rcp_f32_e32 v143, v143
	v_cvt_pk_bf16_f32 v150, v142, v143
	v_mul_f32_e32 v142, 0xbfb8aa3b, v104
	v_exp_f32_e32 v142, v142
	v_mul_f32_e32 v143, 0xbfb8aa3b, v105
	v_exp_f32_e32 v143, v143
	v_exp_f32_e32 v154, v154
	v_add_f32_e32 v142, 1.0, v142
	v_rcp_f32_e32 v142, v142
	v_add_f32_e32 v143, 1.0, v143
	v_rcp_f32_e32 v143, v143
	v_cvt_pk_bf16_f32 v151, v142, v143
	v_mul_f32_e32 v142, 0xbfb8aa3b, v94
	v_exp_f32_e32 v142, v142
	v_mul_f32_e32 v143, 0xbfb8aa3b, v95
	v_exp_f32_e32 v143, v143
	v_add_f32_e32 v154, 1.0, v154
	v_add_f32_e32 v142, 1.0, v142
	v_rcp_f32_e32 v142, v142
	v_add_f32_e32 v143, 1.0, v143
	v_rcp_f32_e32 v143, v143
	v_cvt_pk_bf16_f32 v152, v142, v143
	v_mul_f32_e32 v142, 0xbfb8aa3b, v96
	v_exp_f32_e32 v142, v142
	v_mul_f32_e32 v143, 0xbfb8aa3b, v97
	v_exp_f32_e32 v143, v143
	v_rcp_f32_e32 v154, v154
	v_add_f32_e32 v142, 1.0, v142
	v_rcp_f32_e32 v142, v142
	v_add_f32_e32 v143, 1.0, v143
	v_rcp_f32_e32 v143, v143
	v_cvt_pk_bf16_f32 v153, v142, v143
	v_add_co_u32_e32 v142, vcc, s25, v140
	s_nop 1
	v_addc_co_u32_e32 v143, vcc, 0, v141, vcc
	global_store_dwordx4 v[142:143], v[150:153], off nt
	s_nop 1
	v_mul_f32_e32 v150, 0xbfb8aa3b, v82
	v_mul_f32_e32 v151, 0xbfb8aa3b, v83
	v_exp_f32_e32 v150, v150
	v_exp_f32_e32 v151, v151
	v_mul_f32_e32 v152, 0xbfb8aa3b, v85
	v_exp_f32_e32 v152, v152
	v_add_f32_e32 v150, 1.0, v150
	v_add_f32_e32 v151, 1.0, v151
	v_rcp_f32_e32 v150, v150
	v_rcp_f32_e32 v151, v151
	v_cvt_pk_bf16_f32 v150, v150, v151
	v_mul_f32_e32 v151, 0xbfb8aa3b, v84
	v_exp_f32_e32 v151, v151
	v_add_f32_e32 v152, 1.0, v152
	v_rcp_f32_e32 v152, v152
	v_mul_f32_e32 v153, 0xbfb8aa3b, v75
	v_add_f32_e32 v151, 1.0, v151
	v_rcp_f32_e32 v151, v151
	v_cvt_pk_bf16_f32 v151, v151, v152
	v_mul_f32_e32 v152, 0xbfb8aa3b, v74
	v_exp_f32_e32 v152, v152
	v_exp_f32_e32 v153, v153
	v_add_f32_e32 v152, 1.0, v152
	v_add_f32_e32 v153, 1.0, v153
	v_rcp_f32_e32 v152, v152
	v_rcp_f32_e32 v153, v153
	v_cvt_pk_bf16_f32 v152, v152, v153
	v_mul_f32_e32 v153, 0xbfb8aa3b, v76
	v_exp_f32_e32 v153, v153
	s_nop 0
	v_add_f32_e32 v153, 1.0, v153
	v_rcp_f32_e32 v153, v153
	v_cvt_pk_bf16_f32 v153, v153, v154
	global_store_dwordx4 v[142:143], v[150:153], off offset:256 nt
	v_mul_f32_e32 v142, 0xbfb8aa3b, v86
	v_exp_f32_e32 v142, v142
	v_mul_f32_e32 v143, 0xbfb8aa3b, v87
	v_exp_f32_e32 v143, v143
	v_mul_f32_e32 v154, 0xbfb8aa3b, v69
	v_add_f32_e32 v142, 1.0, v142
	v_rcp_f32_e32 v142, v142
	v_add_f32_e32 v143, 1.0, v143
	v_rcp_f32_e32 v143, v143
	v_cvt_pk_bf16_f32 v150, v142, v143
	v_mul_f32_e32 v142, 0xbfb8aa3b, v88
	v_exp_f32_e32 v142, v142
	v_mul_f32_e32 v143, 0xbfb8aa3b, v89
	v_exp_f32_e32 v143, v143
	v_exp_f32_e32 v154, v154
	v_add_f32_e32 v142, 1.0, v142
	v_rcp_f32_e32 v142, v142
	v_add_f32_e32 v143, 1.0, v143
	v_rcp_f32_e32 v143, v143
	v_cvt_pk_bf16_f32 v151, v142, v143
	v_mul_f32_e32 v142, 0xbfb8aa3b, v78
	v_exp_f32_e32 v142, v142
	v_mul_f32_e32 v143, 0xbfb8aa3b, v79
	v_exp_f32_e32 v143, v143
	v_add_f32_e32 v154, 1.0, v154
	v_add_f32_e32 v142, 1.0, v142
	v_rcp_f32_e32 v142, v142
	v_add_f32_e32 v143, 1.0, v143
	v_rcp_f32_e32 v143, v143
	v_cvt_pk_bf16_f32 v152, v142, v143
	v_mul_f32_e32 v142, 0xbfb8aa3b, v80
	v_exp_f32_e32 v142, v142
	v_mul_f32_e32 v143, 0xbfb8aa3b, v81
	v_exp_f32_e32 v143, v143
	v_rcp_f32_e32 v154, v154
	v_add_f32_e32 v142, 1.0, v142
	v_rcp_f32_e32 v142, v142
	v_add_f32_e32 v143, 1.0, v143
	v_rcp_f32_e32 v143, v143
	v_cvt_pk_bf16_f32 v153, v142, v143
	v_add_co_u32_e32 v142, vcc, s27, v140
	s_nop 1
	v_addc_co_u32_e32 v143, vcc, 0, v141, vcc
	global_store_dwordx4 v[142:143], v[150:153], off nt
	s_nop 1
	v_mul_f32_e32 v150, 0xbfb8aa3b, v70
	v_mul_f32_e32 v151, 0xbfb8aa3b, v71
	v_exp_f32_e32 v150, v150
	v_exp_f32_e32 v151, v151
	v_mul_f32_e32 v152, 0xbfb8aa3b, v73
	v_exp_f32_e32 v152, v152
	v_add_f32_e32 v150, 1.0, v150
	v_add_f32_e32 v151, 1.0, v151
	v_rcp_f32_e32 v150, v150
	v_rcp_f32_e32 v151, v151
	v_cvt_pk_bf16_f32 v150, v150, v151
	v_mul_f32_e32 v151, 0xbfb8aa3b, v72
	v_exp_f32_e32 v151, v151
	v_add_f32_e32 v152, 1.0, v152
	v_rcp_f32_e32 v152, v152
	v_mul_f32_e32 v153, 0xbfb8aa3b, v67
	v_add_f32_e32 v151, 1.0, v151
	v_rcp_f32_e32 v151, v151
	v_cvt_pk_bf16_f32 v151, v151, v152
	v_mul_f32_e32 v152, 0xbfb8aa3b, v66
	v_exp_f32_e32 v152, v152
	v_exp_f32_e32 v153, v153
	v_add_f32_e32 v152, 1.0, v152
	v_add_f32_e32 v153, 1.0, v153
	v_rcp_f32_e32 v152, v152
	v_rcp_f32_e32 v153, v153
	v_cvt_pk_bf16_f32 v152, v152, v153
	v_mul_f32_e32 v153, 0xbfb8aa3b, v68
	v_exp_f32_e32 v153, v153
	s_nop 0
	v_add_f32_e32 v153, 1.0, v153
	v_rcp_f32_e32 v153, v153
	v_cvt_pk_bf16_f32 v153, v153, v154
	global_store_dwordx4 v[142:143], v[150:153], off offset:256 nt
	v_mul_f32_e32 v142, 0xbfb8aa3b, v62
	v_exp_f32_e32 v142, v142
	v_mul_f32_e32 v143, 0xbfb8aa3b, v63
	v_exp_f32_e32 v143, v143
	v_mul_f32_e32 v154, 0xbfb8aa3b, v45
	v_add_f32_e32 v142, 1.0, v142
	v_rcp_f32_e32 v142, v142
	v_add_f32_e32 v143, 1.0, v143
	v_rcp_f32_e32 v143, v143
	v_cvt_pk_bf16_f32 v150, v142, v143
	v_mul_f32_e32 v142, 0xbfb8aa3b, v64
	v_exp_f32_e32 v142, v142
	v_mul_f32_e32 v143, 0xbfb8aa3b, v65
	v_exp_f32_e32 v143, v143
	v_exp_f32_e32 v154, v154
	v_add_f32_e32 v142, 1.0, v142
	v_rcp_f32_e32 v142, v142
	v_add_f32_e32 v143, 1.0, v143
	v_rcp_f32_e32 v143, v143
	v_cvt_pk_bf16_f32 v151, v142, v143
	v_mul_f32_e32 v142, 0xbfb8aa3b, v58
	v_exp_f32_e32 v142, v142
	v_mul_f32_e32 v143, 0xbfb8aa3b, v59
	v_exp_f32_e32 v143, v143
	v_add_f32_e32 v154, 1.0, v154
	v_add_f32_e32 v142, 1.0, v142
	v_rcp_f32_e32 v142, v142
	v_add_f32_e32 v143, 1.0, v143
	v_rcp_f32_e32 v143, v143
	v_cvt_pk_bf16_f32 v152, v142, v143
	v_mul_f32_e32 v142, 0xbfb8aa3b, v60
	v_exp_f32_e32 v142, v142
	v_mul_f32_e32 v143, 0xbfb8aa3b, v61
	v_exp_f32_e32 v143, v143
	v_rcp_f32_e32 v154, v154
	v_add_f32_e32 v142, 1.0, v142
	v_rcp_f32_e32 v142, v142
	v_add_f32_e32 v143, 1.0, v143
	v_rcp_f32_e32 v143, v143
	v_cvt_pk_bf16_f32 v153, v142, v143
	v_add_co_u32_e32 v142, vcc, s3, v140
	s_nop 1
	v_addc_co_u32_e32 v143, vcc, 0, v141, vcc
	global_store_dwordx4 v[142:143], v[150:153], off nt
	s_nop 1
	v_mul_f32_e32 v150, 0xbfb8aa3b, v50
	v_mul_f32_e32 v151, 0xbfb8aa3b, v51
	v_exp_f32_e32 v150, v150
	v_exp_f32_e32 v151, v151
	v_mul_f32_e32 v152, 0xbfb8aa3b, v53
	v_exp_f32_e32 v152, v152
	v_add_f32_e32 v150, 1.0, v150
	v_add_f32_e32 v151, 1.0, v151
	v_rcp_f32_e32 v150, v150
	v_rcp_f32_e32 v151, v151
	v_cvt_pk_bf16_f32 v150, v150, v151
	v_mul_f32_e32 v151, 0xbfb8aa3b, v52
	v_exp_f32_e32 v151, v151
	v_add_f32_e32 v152, 1.0, v152
	v_rcp_f32_e32 v152, v152
	v_mul_f32_e32 v153, 0xbfb8aa3b, v43
	v_add_f32_e32 v151, 1.0, v151
	v_rcp_f32_e32 v151, v151
	v_cvt_pk_bf16_f32 v151, v151, v152
	v_mul_f32_e32 v152, 0xbfb8aa3b, v42
	v_exp_f32_e32 v152, v152
	v_exp_f32_e32 v153, v153
	v_add_f32_e32 v152, 1.0, v152
	v_add_f32_e32 v153, 1.0, v153
	v_rcp_f32_e32 v152, v152
	v_rcp_f32_e32 v153, v153
	v_cvt_pk_bf16_f32 v152, v152, v153
	v_mul_f32_e32 v153, 0xbfb8aa3b, v44
	v_exp_f32_e32 v153, v153
	s_nop 0
	v_add_f32_e32 v153, 1.0, v153
	v_rcp_f32_e32 v153, v153
	v_cvt_pk_bf16_f32 v153, v153, v154
	global_store_dwordx4 v[142:143], v[150:153], off offset:256 nt
	v_mul_f32_e32 v142, 0xbfb8aa3b, v54
	v_exp_f32_e32 v142, v142
	v_mul_f32_e32 v143, 0xbfb8aa3b, v55
	v_exp_f32_e32 v143, v143
	v_mul_f32_e32 v154, 0xbfb8aa3b, v29
	v_add_f32_e32 v142, 1.0, v142
	v_rcp_f32_e32 v142, v142
	v_add_f32_e32 v143, 1.0, v143
	v_rcp_f32_e32 v143, v143
	v_cvt_pk_bf16_f32 v150, v142, v143
	v_mul_f32_e32 v142, 0xbfb8aa3b, v56
	v_exp_f32_e32 v142, v142
	v_mul_f32_e32 v143, 0xbfb8aa3b, v57
	v_exp_f32_e32 v143, v143
	v_exp_f32_e32 v154, v154
	v_add_f32_e32 v142, 1.0, v142
	v_rcp_f32_e32 v142, v142
	v_add_f32_e32 v143, 1.0, v143
	v_rcp_f32_e32 v143, v143
	v_cvt_pk_bf16_f32 v151, v142, v143
	v_mul_f32_e32 v142, 0xbfb8aa3b, v46
	v_exp_f32_e32 v142, v142
	v_mul_f32_e32 v143, 0xbfb8aa3b, v47
	v_exp_f32_e32 v143, v143
	v_add_f32_e32 v154, 1.0, v154
	v_add_f32_e32 v142, 1.0, v142
	v_rcp_f32_e32 v142, v142
	v_add_f32_e32 v143, 1.0, v143
	v_rcp_f32_e32 v143, v143
	v_cvt_pk_bf16_f32 v152, v142, v143
	v_mul_f32_e32 v142, 0xbfb8aa3b, v48
	v_exp_f32_e32 v142, v142
	v_mul_f32_e32 v143, 0xbfb8aa3b, v49
	v_exp_f32_e32 v143, v143
	v_rcp_f32_e32 v154, v154
	v_add_f32_e32 v142, 1.0, v142
	v_rcp_f32_e32 v142, v142
	v_add_f32_e32 v143, 1.0, v143
	v_rcp_f32_e32 v143, v143
	v_cvt_pk_bf16_f32 v153, v142, v143
	v_add_co_u32_e32 v142, vcc, s6, v140
	s_mov_b32 s6, 0x410000
	s_nop 0
	v_addc_co_u32_e32 v143, vcc, 0, v141, vcc
	global_store_dwordx4 v[142:143], v[150:153], off nt
	s_nop 1
	v_mul_f32_e32 v150, 0xbfb8aa3b, v34
	v_mul_f32_e32 v151, 0xbfb8aa3b, v35
	v_exp_f32_e32 v150, v150
	v_exp_f32_e32 v151, v151
	v_mul_f32_e32 v152, 0xbfb8aa3b, v37
	v_exp_f32_e32 v152, v152
	v_add_f32_e32 v150, 1.0, v150
	v_add_f32_e32 v151, 1.0, v151
	v_rcp_f32_e32 v150, v150
	v_rcp_f32_e32 v151, v151
	v_cvt_pk_bf16_f32 v150, v150, v151
	v_mul_f32_e32 v151, 0xbfb8aa3b, v36
	v_exp_f32_e32 v151, v151
	v_add_f32_e32 v152, 1.0, v152
	v_rcp_f32_e32 v152, v152
	v_mul_f32_e32 v153, 0xbfb8aa3b, v27
	v_add_f32_e32 v151, 1.0, v151
	v_rcp_f32_e32 v151, v151
	v_cvt_pk_bf16_f32 v151, v151, v152
	v_mul_f32_e32 v152, 0xbfb8aa3b, v26
	v_exp_f32_e32 v152, v152
	v_exp_f32_e32 v153, v153
	v_add_f32_e32 v152, 1.0, v152
	v_add_f32_e32 v153, 1.0, v153
	v_rcp_f32_e32 v152, v152
	v_rcp_f32_e32 v153, v153
	v_cvt_pk_bf16_f32 v152, v152, v153
	v_mul_f32_e32 v153, 0xbfb8aa3b, v28
	v_exp_f32_e32 v153, v153
	s_nop 0
	v_add_f32_e32 v153, 1.0, v153
	v_rcp_f32_e32 v153, v153
	v_cvt_pk_bf16_f32 v153, v153, v154
	global_store_dwordx4 v[142:143], v[150:153], off offset:256 nt
	v_mul_f32_e32 v142, 0xbfb8aa3b, v38
	v_exp_f32_e32 v142, v142
	v_mul_f32_e32 v143, 0xbfb8aa3b, v39
	v_exp_f32_e32 v143, v143
	v_mul_f32_e32 v154, 0xbfb8aa3b, v13
	v_add_f32_e32 v142, 1.0, v142
	v_rcp_f32_e32 v142, v142
	v_add_f32_e32 v143, 1.0, v143
	v_rcp_f32_e32 v143, v143
	v_cvt_pk_bf16_f32 v150, v142, v143
	v_mul_f32_e32 v142, 0xbfb8aa3b, v40
	v_exp_f32_e32 v142, v142
	v_mul_f32_e32 v143, 0xbfb8aa3b, v41
	v_exp_f32_e32 v143, v143
	v_exp_f32_e32 v154, v154
	v_add_f32_e32 v142, 1.0, v142
	v_rcp_f32_e32 v142, v142
	v_add_f32_e32 v143, 1.0, v143
	v_rcp_f32_e32 v143, v143
	v_cvt_pk_bf16_f32 v151, v142, v143
	v_mul_f32_e32 v142, 0xbfb8aa3b, v30
	v_exp_f32_e32 v142, v142
	v_mul_f32_e32 v143, 0xbfb8aa3b, v31
	v_exp_f32_e32 v143, v143
	v_add_f32_e32 v154, 1.0, v154
	v_add_f32_e32 v142, 1.0, v142
	v_rcp_f32_e32 v142, v142
	v_add_f32_e32 v143, 1.0, v143
	v_rcp_f32_e32 v143, v143
	v_cvt_pk_bf16_f32 v152, v142, v143
	v_mul_f32_e32 v142, 0xbfb8aa3b, v32
	v_exp_f32_e32 v142, v142
	v_mul_f32_e32 v143, 0xbfb8aa3b, v33
	v_exp_f32_e32 v143, v143
	v_rcp_f32_e32 v154, v154
	v_add_f32_e32 v142, 1.0, v142
	v_rcp_f32_e32 v142, v142
	v_add_f32_e32 v143, 1.0, v143
	v_rcp_f32_e32 v143, v143
	v_cvt_pk_bf16_f32 v153, v142, v143
	v_add_co_u32_e32 v142, vcc, s6, v140
	s_mov_b32 s6, 0x478000
	s_nop 0
	v_addc_co_u32_e32 v143, vcc, 0, v141, vcc
	global_store_dwordx4 v[142:143], v[150:153], off nt
	s_nop 1
	v_mul_f32_e32 v150, 0xbfb8aa3b, v18
	v_mul_f32_e32 v151, 0xbfb8aa3b, v19
	v_exp_f32_e32 v150, v150
	v_exp_f32_e32 v151, v151
	v_mul_f32_e32 v152, 0xbfb8aa3b, v21
	v_exp_f32_e32 v152, v152
	v_add_f32_e32 v150, 1.0, v150
	v_add_f32_e32 v151, 1.0, v151
	v_rcp_f32_e32 v150, v150
	v_rcp_f32_e32 v151, v151
	v_cvt_pk_bf16_f32 v150, v150, v151
	v_mul_f32_e32 v151, 0xbfb8aa3b, v20
	v_exp_f32_e32 v151, v151
	v_add_f32_e32 v152, 1.0, v152
	v_rcp_f32_e32 v152, v152
	v_mul_f32_e32 v153, 0xbfb8aa3b, v11
	v_add_f32_e32 v151, 1.0, v151
	v_rcp_f32_e32 v151, v151
	v_cvt_pk_bf16_f32 v151, v151, v152
	v_mul_f32_e32 v152, 0xbfb8aa3b, v10
	v_exp_f32_e32 v152, v152
	v_exp_f32_e32 v153, v153
	v_add_f32_e32 v152, 1.0, v152
	v_add_f32_e32 v153, 1.0, v153
	v_rcp_f32_e32 v152, v152
	v_rcp_f32_e32 v153, v153
	v_cvt_pk_bf16_f32 v152, v152, v153
	v_mul_f32_e32 v153, 0xbfb8aa3b, v12
	v_exp_f32_e32 v153, v153
	s_nop 0
	v_add_f32_e32 v153, 1.0, v153
	v_rcp_f32_e32 v153, v153
	v_cvt_pk_bf16_f32 v153, v153, v154
	global_store_dwordx4 v[142:143], v[150:153], off offset:256 nt
	v_mul_f32_e32 v142, 0xbfb8aa3b, v22
	v_exp_f32_e32 v142, v142
	v_mul_f32_e32 v143, 0xbfb8aa3b, v23
	v_exp_f32_e32 v143, v143
	v_mul_f32_e32 v154, 0xbfb8aa3b, v5
	v_add_f32_e32 v142, 1.0, v142
	v_rcp_f32_e32 v142, v142
	v_add_f32_e32 v143, 1.0, v143
	v_rcp_f32_e32 v143, v143
	v_cvt_pk_bf16_f32 v150, v142, v143
	v_mul_f32_e32 v142, 0xbfb8aa3b, v24
	v_exp_f32_e32 v142, v142
	v_mul_f32_e32 v143, 0xbfb8aa3b, v25
	v_exp_f32_e32 v143, v143
	v_exp_f32_e32 v154, v154
	v_add_f32_e32 v142, 1.0, v142
	v_rcp_f32_e32 v142, v142
	v_add_f32_e32 v143, 1.0, v143
	v_rcp_f32_e32 v143, v143
	v_cvt_pk_bf16_f32 v151, v142, v143
	v_mul_f32_e32 v142, 0xbfb8aa3b, v14
	v_exp_f32_e32 v142, v142
	v_mul_f32_e32 v143, 0xbfb8aa3b, v15
	v_exp_f32_e32 v143, v143
	v_add_f32_e32 v154, 1.0, v154
	v_add_f32_e32 v142, 1.0, v142
	v_rcp_f32_e32 v142, v142
	v_add_f32_e32 v143, 1.0, v143
	v_rcp_f32_e32 v143, v143
	v_cvt_pk_bf16_f32 v152, v142, v143
	v_mul_f32_e32 v142, 0xbfb8aa3b, v16
	v_exp_f32_e32 v142, v142
	v_mul_f32_e32 v143, 0xbfb8aa3b, v17
	v_exp_f32_e32 v143, v143
	v_rcp_f32_e32 v154, v154
	v_add_f32_e32 v142, 1.0, v142
	v_rcp_f32_e32 v142, v142
	v_add_f32_e32 v143, 1.0, v143
	v_rcp_f32_e32 v143, v143
	v_cvt_pk_bf16_f32 v153, v142, v143
	v_add_co_u32_e32 v142, vcc, s6, v140
	s_nop 1
	v_addc_co_u32_e32 v143, vcc, 0, v141, vcc
	global_store_dwordx4 v[142:143], v[150:153], off nt
	s_nop 1
	v_mul_f32_e32 v150, 0xbfb8aa3b, v6
	v_mul_f32_e32 v151, 0xbfb8aa3b, v7
	v_exp_f32_e32 v150, v150
	v_exp_f32_e32 v151, v151
	v_mul_f32_e32 v152, 0xbfb8aa3b, v9
	v_exp_f32_e32 v152, v152
	v_add_f32_e32 v150, 1.0, v150
	v_add_f32_e32 v151, 1.0, v151
	v_rcp_f32_e32 v150, v150
	v_rcp_f32_e32 v151, v151
	v_cvt_pk_bf16_f32 v150, v150, v151
	v_mul_f32_e32 v151, 0xbfb8aa3b, v8
	v_exp_f32_e32 v151, v151
	v_add_f32_e32 v152, 1.0, v152
	v_rcp_f32_e32 v152, v152
	v_mul_f32_e32 v153, 0xbfb8aa3b, v3
	v_add_f32_e32 v151, 1.0, v151
	v_rcp_f32_e32 v151, v151
	v_cvt_pk_bf16_f32 v151, v151, v152
	v_mul_f32_e32 v152, 0xbfb8aa3b, v2
	v_exp_f32_e32 v152, v152
	v_exp_f32_e32 v153, v153
	v_add_f32_e32 v152, 1.0, v152
	v_add_f32_e32 v153, 1.0, v153
	v_rcp_f32_e32 v152, v152
	v_rcp_f32_e32 v153, v153
	v_cvt_pk_bf16_f32 v152, v152, v153
	v_mul_f32_e32 v153, 0xbfb8aa3b, v4
	v_exp_f32_e32 v153, v153
	s_nop 0
	v_add_f32_e32 v153, 1.0, v153
	v_rcp_f32_e32 v153, v153
	v_cvt_pk_bf16_f32 v153, v153, v154
	global_store_dwordx4 v[142:143], v[150:153], off offset:256 nt
	s_cbranch_execnz .LBB0_128
.LBB0_166:
	v_cvt_pk_bf16_f32 v126, v126, v127
	v_cvt_pk_bf16_f32 v127, v128, v129
	v_cvt_pk_bf16_f32 v128, v122, v123
	v_cvt_pk_bf16_f32 v129, v124, v125
	global_store_dwordx4 v[140:141], v[126:129], off nt
	v_cvt_pk_bf16_f32 v114, v114, v115
	v_cvt_pk_bf16_f32 v115, v116, v117
	v_cvt_pk_bf16_f32 v116, v106, v107
	v_cvt_pk_bf16_f32 v117, v108, v109
	global_store_dwordx4 v[140:141], v[114:117], off offset:256 nt
	v_cvt_pk_bf16_f32 v106, v118, v119
	v_cvt_pk_bf16_f32 v107, v120, v121
	v_cvt_pk_bf16_f32 v108, v110, v111
	v_add_co_u32_e32 v110, vcc, s24, v140
	v_cvt_pk_bf16_f32 v109, v112, v113
	s_mov_b32 s6, 0x3a8000
	s_nop 0
	v_addc_co_u32_e32 v111, vcc, 0, v141, vcc
	global_store_dwordx4 v[110:111], v[106:109], off nt
	v_cvt_pk_bf16_f32 v98, v98, v99
	v_cvt_pk_bf16_f32 v99, v100, v101
	v_cvt_pk_bf16_f32 v100, v90, v91
	v_cvt_pk_bf16_f32 v101, v92, v93
	global_store_dwordx4 v[110:111], v[98:101], off offset:256 nt
	v_cvt_pk_bf16_f32 v90, v102, v103
	v_cvt_pk_bf16_f32 v91, v104, v105
	v_cvt_pk_bf16_f32 v92, v94, v95
	v_add_co_u32_e32 v94, vcc, s25, v140
	v_cvt_pk_bf16_f32 v93, v96, v97
	s_nop 1
	v_addc_co_u32_e32 v95, vcc, 0, v141, vcc
	global_store_dwordx4 v[94:95], v[90:93], off nt
	v_cvt_pk_bf16_f32 v82, v82, v83
	v_cvt_pk_bf16_f32 v83, v84, v85
	v_cvt_pk_bf16_f32 v84, v74, v75
	v_cvt_pk_bf16_f32 v85, v76, v77
	global_store_dwordx4 v[94:95], v[82:85], off offset:256 nt
	v_cvt_pk_bf16_f32 v74, v86, v87
	v_cvt_pk_bf16_f32 v75, v88, v89
	v_cvt_pk_bf16_f32 v76, v78, v79
	v_add_co_u32_e32 v78, vcc, s27, v140
	v_cvt_pk_bf16_f32 v77, v80, v81
	s_nop 1
	v_addc_co_u32_e32 v79, vcc, 0, v141, vcc
	global_store_dwordx4 v[78:79], v[74:77], off nt
	v_cvt_pk_bf16_f32 v70, v70, v71
	v_cvt_pk_bf16_f32 v71, v72, v73
	v_cvt_pk_bf16_f32 v72, v66, v67
	v_cvt_pk_bf16_f32 v73, v68, v69
	global_store_dwordx4 v[78:79], v[70:73], off offset:256 nt
	v_cvt_pk_bf16_f32 v62, v62, v63
	v_cvt_pk_bf16_f32 v63, v64, v65
	v_cvt_pk_bf16_f32 v64, v58, v59
	v_add_co_u32_e32 v58, vcc, s3, v140
	v_cvt_pk_bf16_f32 v65, v60, v61
	s_nop 1
	v_addc_co_u32_e32 v59, vcc, 0, v141, vcc
	global_store_dwordx4 v[58:59], v[62:65], off nt
	v_cvt_pk_bf16_f32 v50, v50, v51
	v_cvt_pk_bf16_f32 v51, v52, v53
	v_cvt_pk_bf16_f32 v52, v42, v43
	v_cvt_pk_bf16_f32 v53, v44, v45
	global_store_dwordx4 v[58:59], v[50:53], off offset:256 nt
	v_cvt_pk_bf16_f32 v42, v54, v55
	v_cvt_pk_bf16_f32 v43, v56, v57
	v_cvt_pk_bf16_f32 v44, v46, v47
	v_add_co_u32_e32 v46, vcc, s6, v140
	s_mov_b32 s6, 0x410000
	s_nop 0
	v_addc_co_u32_e32 v47, vcc, 0, v141, vcc
	v_cvt_pk_bf16_f32 v45, v48, v49
	global_store_dwordx4 v[46:47], v[42:45], off nt
	v_cvt_pk_bf16_f32 v34, v34, v35
	v_cvt_pk_bf16_f32 v35, v36, v37
	v_cvt_pk_bf16_f32 v36, v26, v27
	v_cvt_pk_bf16_f32 v37, v28, v29
	global_store_dwordx4 v[46:47], v[34:37], off offset:256 nt
	v_cvt_pk_bf16_f32 v26, v38, v39
	v_cvt_pk_bf16_f32 v27, v40, v41
	v_cvt_pk_bf16_f32 v28, v30, v31
	v_add_co_u32_e32 v30, vcc, s6, v140
	s_mov_b32 s6, 0x478000
	s_nop 0
	v_addc_co_u32_e32 v31, vcc, 0, v141, vcc
	v_cvt_pk_bf16_f32 v29, v32, v33
	global_store_dwordx4 v[30:31], v[26:29], off nt
	v_cvt_pk_bf16_f32 v18, v18, v19
	v_cvt_pk_bf16_f32 v19, v20, v21
	v_cvt_pk_bf16_f32 v20, v10, v11
	v_cvt_pk_bf16_f32 v21, v12, v13
	global_store_dwordx4 v[30:31], v[18:21], off offset:256 nt
	v_cvt_pk_bf16_f32 v10, v22, v23
	v_cvt_pk_bf16_f32 v11, v24, v25
	v_cvt_pk_bf16_f32 v12, v14, v15
	v_add_co_u32_e32 v14, vcc, s6, v140
	v_cvt_pk_bf16_f32 v13, v16, v17
	s_nop 1
	v_addc_co_u32_e32 v15, vcc, 0, v141, vcc
	global_store_dwordx4 v[14:15], v[10:13], off nt
	v_cvt_pk_bf16_f32 v6, v6, v7
	v_cvt_pk_bf16_f32 v7, v8, v9
	v_cvt_pk_bf16_f32 v8, v2, v3
	v_cvt_pk_bf16_f32 v9, v4, v5
	global_store_dwordx4 v[14:15], v[6:9], off offset:256 nt
	s_branch .LBB0_128
